# cand22 + sample-group attention: full-wave sums/max via DPP + permlane swaps in place of serial ds_bpermute round trips
# speedup vs baseline: 1.0081x; 1.0022x over previous
.LBB0_1424:
	s_ashr_i32 s2, s33, 6
	s_and_b32 s0, s33, 63
	s_ashr_i32 s3, s2, 31
	s_mul_i32 s51, s2, 0x5000
	s_mul_hi_i32 s50, s2, 0x5000
	s_add_u32 vcc_lo, s42, s51
	s_addc_u32 vcc_hi, s43, s50
	s_lshl_b32 s50, s0, 8
	s_add_u32 s50, vcc_lo, s50
	s_addc_u32 s51, vcc_hi, 0
	global_load_dword v8, v2, s[50:51]
	v_writelane_b32 v250, s0, 49
	s_lshl_b32 s43, s33, 5
	v_writelane_b32 v250, s2, 50
	s_lshl_b64 s[0:1], s[2:3], 18
	s_and_b32 s43, s43, 0x700
	s_or_b32 s0, s0, s43
	v_writelane_b32 v250, s3, 51
	s_add_u32 vcc_lo, vcc_lo, s43
	v_writelane_b32 v250, s0, 52
	s_addc_u32 vcc_hi, vcc_hi, 0
	v_lshl_add_u64 v[10:11], vcc, 0, v[2:3]
	v_writelane_b32 v250, s1, 53
	v_readlane_b32 s54, v252, 45
	v_readlane_b32 s55, v252, 46
	v_readlane_b32 s56, v252, 47
	v_readlane_b32 s57, v252, 48
	v_readlane_b32 s58, v252, 49
	v_readlane_b32 s59, v252, 50
	v_readlane_b32 s60, v252, 51
	v_readlane_b32 s61, v252, 52
	v_readlane_b32 s62, v252, 53
	v_readlane_b32 s63, v252, 54
	v_readlane_b32 s52, v252, 55
	v_readlane_b32 s53, v252, 56
	v_readlane_b32 s66, v252, 57
	v_readlane_b32 s67, v252, 58
	v_readlane_b32 s68, v252, 59
	v_readlane_b32 s69, v252, 60
	v_readlane_b32 s70, v252, 61
	v_readlane_b32 s71, v252, 62
	v_readlane_b32 s72, v252, 63
	v_readlane_b32 s73, v251, 0
	v_readlane_b32 s74, v251, 1
	v_readlane_b32 s75, v251, 2
	v_readlane_b32 s44, v251, 3
	v_readlane_b32 s45, v251, 4
	v_readlane_b32 s46, v251, 5
	v_readlane_b32 s47, v251, 6
	v_readlane_b32 s96, v251, 7
	v_readlane_b32 s97, v251, 8
	v_readlane_b32 s94, v251, 9
	v_readlane_b32 s95, v251, 10
	v_readlane_b32 s92, v251, 11
	v_readlane_b32 s93, v251, 12
	v_readlane_b32 s90, v251, 13
	v_readlane_b32 s91, v251, 14
	v_readlane_b32 s88, v251, 15
	v_readlane_b32 s89, v251, 16
	v_readlane_b32 s84, v251, 17
	v_readlane_b32 s85, v251, 18
	v_readlane_b32 s82, v251, 19
	v_readlane_b32 s83, v251, 20
	v_readlane_b32 s80, v251, 21
	v_readlane_b32 s81, v251, 22
	v_readlane_b32 s76, v251, 23
	v_readlane_b32 s77, v251, 24
	v_readlane_b32 s2, v251, 27
	v_readlane_b32 s3, v251, 28
	v_readlane_b32 s4, v251, 29
	v_readlane_b32 s5, v251, 30
	v_readlane_b32 s6, v251, 31
	v_readlane_b32 s7, v251, 32
	v_readlane_b32 s8, v251, 33
	v_readlane_b32 s9, v251, 34
	v_readlane_b32 s10, v251, 35
	v_readlane_b32 s11, v251, 36
	v_readlane_b32 s12, v251, 37
	v_readlane_b32 s13, v251, 38
	v_readlane_b32 s14, v251, 39
	v_readlane_b32 s15, v251, 40
	v_readlane_b32 s16, v251, 41
	v_readlane_b32 s17, v251, 42
	v_readlane_b32 s18, v251, 43
	v_readlane_b32 s19, v251, 44
	v_readlane_b32 s20, v251, 45
	v_readlane_b32 s21, v251, 46
	v_readlane_b32 s22, v251, 47
	v_readlane_b32 s23, v251, 48
	v_readlane_b32 s24, v251, 49
	s_waitcnt vmcnt(0)
	v_mul_f32_e32 v13, 0x3e000000, v8
	v_lshl_add_u64 v[8:9], v[4:5], 0, s[0:1]
	s_movk_i32 s0, 0x4000
	v_add_co_u32_e32 v10, vcc, s0, v10
	s_movk_i32 s1, 0x1000
	s_nop 0
	v_addc_co_u32_e32 v11, vcc, 0, v11, vcc
	global_load_dword v14, v[10:11], off
	global_load_dword v12, v[10:11], off offset:2048
	global_load_dword v64, v[8:9], off
	global_load_dword v65, v[8:9], off offset:2048
	v_add_co_u32_e32 v10, vcc, s1, v8
	s_movk_i32 s1, 0x2000
	s_nop 0
	v_addc_co_u32_e32 v11, vcc, 0, v9, vcc
	v_add_co_u32_e32 v16, vcc, s1, v8
	s_movk_i32 s1, 0x3000
	s_nop 0
	v_addc_co_u32_e32 v17, vcc, 0, v9, vcc
	global_load_dword v66, v[16:17], off offset:-4096
	global_load_dword v67, v[10:11], off offset:2048
	global_load_dword v68, v[16:17], off
	global_load_dword v69, v[16:17], off offset:2048
	v_add_co_u32_e32 v10, vcc, s1, v8
	v_readlane_b32 s25, v251, 50
	s_nop 0
	v_addc_co_u32_e32 v11, vcc, 0, v9, vcc
	v_add_co_u32_e32 v16, vcc, s0, v8
	s_movk_i32 s0, 0x5000
	s_nop 0
	v_addc_co_u32_e32 v17, vcc, 0, v9, vcc
	global_load_dword v70, v[16:17], off offset:-4096
	global_load_dword v71, v[10:11], off offset:2048
	global_load_dword v72, v[16:17], off
	global_load_dword v73, v[16:17], off offset:2048
	v_add_co_u32_e32 v10, vcc, s0, v8
	s_movk_i32 s0, 0x6000
	s_nop 0
	v_addc_co_u32_e32 v11, vcc, 0, v9, vcc
	v_add_co_u32_e32 v16, vcc, s0, v8
	s_movk_i32 s0, 0x7000
	s_nop 0
	v_addc_co_u32_e32 v17, vcc, 0, v9, vcc
	global_load_dword v74, v[16:17], off offset:-4096
	global_load_dword v75, v[10:11], off offset:2048
	global_load_dword v76, v[16:17], off
	global_load_dword v77, v[16:17], off offset:2048
	v_add_co_u32_e32 v10, vcc, s0, v8
	s_mov_b32 s0, 0x8000
	s_nop 0
	v_addc_co_u32_e32 v11, vcc, 0, v9, vcc
	v_add_co_u32_e32 v16, vcc, s0, v8
	s_mov_b32 s0, 0x9000
	s_nop 0
	v_addc_co_u32_e32 v17, vcc, 0, v9, vcc
	global_load_dword v78, v[16:17], off offset:-4096
	global_load_dword v79, v[10:11], off offset:2048
	global_load_dword v80, v[16:17], off
	global_load_dword v81, v[16:17], off offset:2048
	v_add_co_u32_e32 v10, vcc, s0, v8
	s_mov_b32 s0, 0xa000
	s_nop 0
	v_addc_co_u32_e32 v11, vcc, 0, v9, vcc
	v_add_co_u32_e32 v16, vcc, s0, v8
	s_mov_b32 s0, 0xb000
	s_nop 0
	v_addc_co_u32_e32 v17, vcc, 0, v9, vcc
	global_load_dword v82, v[16:17], off offset:-4096
	global_load_dword v83, v[10:11], off offset:2048
	global_load_dword v84, v[16:17], off
	global_load_dword v85, v[16:17], off offset:2048
	v_add_co_u32_e32 v10, vcc, s0, v8
	s_mov_b32 s0, 0xc000
	s_nop 0
	v_addc_co_u32_e32 v11, vcc, 0, v9, vcc
	v_add_co_u32_e32 v16, vcc, s0, v8
	s_mov_b32 s0, 0xd000
	s_nop 0
	v_addc_co_u32_e32 v17, vcc, 0, v9, vcc
	global_load_dword v86, v[16:17], off offset:-4096
	global_load_dword v87, v[10:11], off offset:2048
	global_load_dword v61, v[16:17], off
	global_load_dword v60, v[16:17], off offset:2048
	v_add_co_u32_e32 v10, vcc, s0, v8
	s_mov_b32 s0, 0xe000
	s_nop 0
	v_addc_co_u32_e32 v11, vcc, 0, v9, vcc
	v_add_co_u32_e32 v16, vcc, s0, v8
	s_mov_b32 s0, 0xf000
	s_nop 0
	v_addc_co_u32_e32 v17, vcc, 0, v9, vcc
	global_load_dword v59, v[16:17], off offset:-4096
	global_load_dword v58, v[10:11], off offset:2048
	global_load_dword v57, v[16:17], off
	global_load_dword v56, v[16:17], off offset:2048
	v_add_co_u32_e32 v10, vcc, s0, v8
	s_mov_b32 s0, 0x10000
	s_nop 0
	v_addc_co_u32_e32 v11, vcc, 0, v9, vcc
	v_add_co_u32_e32 v16, vcc, s0, v8
	s_mov_b32 s0, 0x11000
	s_nop 0
	v_addc_co_u32_e32 v17, vcc, 0, v9, vcc
	global_load_dword v55, v[16:17], off offset:-4096
	global_load_dword v54, v[10:11], off offset:2048
	global_load_dword v53, v[16:17], off
	global_load_dword v52, v[16:17], off offset:2048
	v_add_co_u32_e32 v10, vcc, s0, v8
	s_mov_b32 s0, 0x12000
	s_nop 0
	v_addc_co_u32_e32 v11, vcc, 0, v9, vcc
	v_add_co_u32_e32 v16, vcc, s0, v8
	s_mov_b32 s0, 0x13000
	s_nop 0
	v_addc_co_u32_e32 v17, vcc, 0, v9, vcc
	global_load_dword v51, v[16:17], off offset:-4096
	global_load_dword v50, v[10:11], off offset:2048
	global_load_dword v49, v[16:17], off
	global_load_dword v48, v[16:17], off offset:2048
	v_add_co_u32_e32 v10, vcc, s0, v8
	s_mov_b32 s0, 0x14000
	s_nop 0
	v_addc_co_u32_e32 v11, vcc, 0, v9, vcc
	v_add_co_u32_e32 v16, vcc, s0, v8
	s_mov_b32 s0, 0x15000
	s_nop 0
	v_addc_co_u32_e32 v17, vcc, 0, v9, vcc
	global_load_dword v47, v[16:17], off offset:-4096
	global_load_dword v46, v[10:11], off offset:2048
	global_load_dword v45, v[16:17], off
	global_load_dword v44, v[16:17], off offset:2048
	v_add_co_u32_e32 v10, vcc, s0, v8
	s_mov_b32 s0, 0x16000
	s_nop 0
	v_addc_co_u32_e32 v11, vcc, 0, v9, vcc
	v_add_co_u32_e32 v16, vcc, s0, v8
	s_mov_b32 s0, 0x17000
	s_nop 0
	v_addc_co_u32_e32 v17, vcc, 0, v9, vcc
	global_load_dword v43, v[16:17], off offset:-4096
	global_load_dword v42, v[10:11], off offset:2048
	global_load_dword v41, v[16:17], off
	global_load_dword v40, v[16:17], off offset:2048
	v_add_co_u32_e32 v10, vcc, s0, v8
	s_mov_b32 s0, 0x18000
	s_nop 0
	v_addc_co_u32_e32 v11, vcc, 0, v9, vcc
	v_add_co_u32_e32 v16, vcc, s0, v8
	s_mov_b32 s0, 0x19000
	s_nop 0
	v_addc_co_u32_e32 v17, vcc, 0, v9, vcc
	global_load_dword v39, v[16:17], off offset:-4096
	global_load_dword v38, v[10:11], off offset:2048
	global_load_dword v37, v[16:17], off
	global_load_dword v36, v[16:17], off offset:2048
	v_add_co_u32_e32 v10, vcc, s0, v8
	s_mov_b32 s0, 0x1a000
	s_nop 0
	v_addc_co_u32_e32 v11, vcc, 0, v9, vcc
	v_add_co_u32_e32 v16, vcc, s0, v8
	s_mov_b32 s0, 0x1b000
	s_nop 0
	v_addc_co_u32_e32 v17, vcc, 0, v9, vcc
	global_load_dword v35, v[16:17], off offset:-4096
	global_load_dword v27, v[10:11], off offset:2048
	global_load_dword v26, v[16:17], off
	global_load_dword v25, v[16:17], off offset:2048
	v_add_co_u32_e32 v10, vcc, s0, v8
	s_mov_b32 s0, 0x1c000
	s_nop 0
	v_addc_co_u32_e32 v11, vcc, 0, v9, vcc
	v_add_co_u32_e32 v16, vcc, s0, v8
	s_mov_b32 s0, 0x1d000
	s_nop 0
	v_addc_co_u32_e32 v17, vcc, 0, v9, vcc
	global_load_dword v24, v[16:17], off offset:-4096
	global_load_dword v23, v[10:11], off offset:2048
	global_load_dword v22, v[16:17], off
	global_load_dword v21, v[16:17], off offset:2048
	v_add_co_u32_e32 v10, vcc, s0, v8
	s_mov_b32 s0, 0x1e000
	s_nop 0
	v_addc_co_u32_e32 v11, vcc, 0, v9, vcc
	v_add_co_u32_e32 v16, vcc, s0, v8
	s_mov_b32 s0, 0x1f000
	s_nop 0
	v_addc_co_u32_e32 v17, vcc, 0, v9, vcc
	v_add_co_u32_e32 v62, vcc, s0, v8
	s_mov_b32 s0, 0x20000
	s_nop 0
	v_addc_co_u32_e32 v63, vcc, 0, v9, vcc
	global_load_dword v20, v[16:17], off offset:-4096
	global_load_dword v19, v[10:11], off offset:2048
	global_load_dword v18, v[16:17], off
	s_nop 0
	global_load_dword v17, v[16:17], off offset:2048
	v_add_co_u32_e32 v10, vcc, s0, v8
	v_readlane_b32 s0, v251, 25
	s_nop 0
	v_addc_co_u32_e32 v11, vcc, 0, v9, vcc
	global_load_dword v16, v[10:11], off offset:-4096
	global_load_dword v15, v[62:63], off offset:2048
	s_waitcnt vmcnt(62)
	v_mul_f32_e32 v62, v13, v64
	v_readlane_b32 s1, v251, 26
	v_readlane_b32 s26, v251, 51
	v_readlane_b32 s27, v251, 52
	v_readlane_b32 s28, v251, 53
	s_nop 1
	v_add_f32_dpp v62, v62, v62 quad_perm:[1,0,3,2] row_mask:0xf bank_mask:0xf
	v_readlane_b32 s29, v251, 54
	v_readlane_b32 s30, v251, 55
	v_readlane_b32 s31, v251, 56
	v_readlane_b32 s34, v251, 57
	s_nop 1
	v_add_f32_dpp v62, v62, v62 quad_perm:[2,3,0,1] row_mask:0xf bank_mask:0xf
	v_readlane_b32 s35, v251, 58
	v_readlane_b32 s36, v251, 59
	v_readlane_b32 s37, v251, 60
	v_readlane_b32 s38, v251, 61
	s_nop 1
	v_add_f32_dpp v62, v62, v62 row_half_mirror row_mask:0xf bank_mask:0xf
	v_readlane_b32 s39, v251, 62
	v_readlane_b32 s40, v251, 63
	v_readlane_b32 s41, v250, 0
	v_readlane_b32 s42, v250, 1
	s_nop 1
	v_add_f32_dpp v62, v62, v62 row_mirror row_mask:0xf bank_mask:0xf
	v_readlane_b32 s43, v250, 2
	v_readlane_b32 s48, v250, 3
	v_readlane_b32 s49, v250, 4
	v_readlane_b32 s50, v250, 5
	v_mov_b32_e32 v63, v62
	s_nop 1
	v_permlane16_swap_b32_e32 v63, v62
	v_add_f32_e32 v62, v62, v63
	v_readlane_b32 s51, v250, 6
	v_readlane_b32 s64, v250, 7
	v_readlane_b32 s65, v250, 8
	v_readlane_b32 s78, v250, 9
	v_mov_b32_e32 v63, v62
	s_nop 1
	v_permlane32_swap_b32_e32 v63, v62
	v_add_f32_e32 v62, v62, v63
	v_mul_f32_e32 v63, v13, v65
	v_cndmask_b32_e64 v62, 0, v62, s[54:55]
	v_readlane_b32 s79, v250, 10
	v_readlane_b32 s86, v250, 11
	v_readlane_b32 s87, v250, 12
	s_nop 1
	v_add_f32_dpp v63, v63, v63 quad_perm:[1,0,3,2] row_mask:0xf bank_mask:0xf
	v_readlane_b32 vcc_lo, v250, 13
	v_readlane_b32 vcc_hi, v250, 14
	s_nop 1
	v_add_f32_dpp v63, v63, v63 quad_perm:[2,3,0,1] row_mask:0xf bank_mask:0xf
	s_nop 1
	v_add_f32_dpp v63, v63, v63 row_half_mirror row_mask:0xf bank_mask:0xf
	s_nop 1
	v_add_f32_dpp v63, v63, v63 row_mirror row_mask:0xf bank_mask:0xf
	v_mov_b32_e32 v64, v63
	s_nop 1
	v_permlane16_swap_b32_e32 v64, v63
	v_add_f32_e32 v63, v63, v64
	v_mov_b32_e32 v64, v63
	s_nop 1
	v_permlane32_swap_b32_e32 v64, v63
	v_add_f32_e32 v63, v63, v64
	v_cndmask_b32_e64 v62, v62, v63, s[56:57]
	s_waitcnt vmcnt(61)
	v_mul_f32_e32 v63, v13, v66
	s_nop 1
	v_add_f32_dpp v63, v63, v63 quad_perm:[1,0,3,2] row_mask:0xf bank_mask:0xf
	s_nop 1
	v_add_f32_dpp v63, v63, v63 quad_perm:[2,3,0,1] row_mask:0xf bank_mask:0xf
	s_nop 1
	v_add_f32_dpp v63, v63, v63 row_half_mirror row_mask:0xf bank_mask:0xf
	s_nop 1
	v_add_f32_dpp v63, v63, v63 row_mirror row_mask:0xf bank_mask:0xf
	v_mov_b32_e32 v64, v63
	s_nop 1
	v_permlane16_swap_b32_e32 v64, v63
	v_add_f32_e32 v63, v63, v64
	v_mov_b32_e32 v64, v63
	s_nop 1
	v_permlane32_swap_b32_e32 v64, v63
	v_add_f32_e32 v63, v63, v64
	v_cndmask_b32_e64 v62, v62, v63, s[58:59]
	s_waitcnt vmcnt(60)
	v_mul_f32_e32 v63, v13, v67
	s_nop 1
	v_add_f32_dpp v63, v63, v63 quad_perm:[1,0,3,2] row_mask:0xf bank_mask:0xf
	s_nop 1
	v_add_f32_dpp v63, v63, v63 quad_perm:[2,3,0,1] row_mask:0xf bank_mask:0xf
	s_nop 1
	v_add_f32_dpp v63, v63, v63 row_half_mirror row_mask:0xf bank_mask:0xf
	s_nop 1
	v_add_f32_dpp v63, v63, v63 row_mirror row_mask:0xf bank_mask:0xf
	v_mov_b32_e32 v64, v63
	s_nop 1
	v_permlane16_swap_b32_e32 v64, v63
	v_add_f32_e32 v63, v63, v64
	v_mov_b32_e32 v64, v63
	s_nop 1
	v_permlane32_swap_b32_e32 v64, v63
	v_add_f32_e32 v63, v63, v64
	v_cndmask_b32_e64 v62, v62, v63, s[60:61]
	s_waitcnt vmcnt(59)
	v_mul_f32_e32 v63, v13, v68
	s_nop 1
	v_add_f32_dpp v63, v63, v63 quad_perm:[1,0,3,2] row_mask:0xf bank_mask:0xf
	s_nop 1
	v_add_f32_dpp v63, v63, v63 quad_perm:[2,3,0,1] row_mask:0xf bank_mask:0xf
	s_nop 1
	v_add_f32_dpp v63, v63, v63 row_half_mirror row_mask:0xf bank_mask:0xf
	s_nop 1
	v_add_f32_dpp v63, v63, v63 row_mirror row_mask:0xf bank_mask:0xf
	v_mov_b32_e32 v64, v63
	s_nop 1
	v_permlane16_swap_b32_e32 v64, v63
	v_add_f32_e32 v63, v63, v64
	v_mov_b32_e32 v64, v63
	s_nop 1
	v_permlane32_swap_b32_e32 v64, v63
	v_add_f32_e32 v63, v63, v64
	v_cndmask_b32_e64 v62, v62, v63, s[62:63]
	s_waitcnt vmcnt(58)
	v_mul_f32_e32 v63, v13, v69
	s_nop 1
	v_add_f32_dpp v63, v63, v63 quad_perm:[1,0,3,2] row_mask:0xf bank_mask:0xf
	s_nop 1
	v_add_f32_dpp v63, v63, v63 quad_perm:[2,3,0,1] row_mask:0xf bank_mask:0xf
	s_nop 1
	v_add_f32_dpp v63, v63, v63 row_half_mirror row_mask:0xf bank_mask:0xf
	s_nop 1
	v_add_f32_dpp v63, v63, v63 row_mirror row_mask:0xf bank_mask:0xf
	v_mov_b32_e32 v64, v63
	s_nop 1
	v_permlane16_swap_b32_e32 v64, v63
	v_add_f32_e32 v63, v63, v64
	v_mov_b32_e32 v64, v63
	s_nop 1
	v_permlane32_swap_b32_e32 v64, v63
	v_add_f32_e32 v63, v63, v64
	v_cndmask_b32_e64 v62, v62, v63, s[52:53]
	s_waitcnt vmcnt(57)
	v_mul_f32_e32 v63, v13, v70
	s_nop 1
	v_add_f32_dpp v63, v63, v63 quad_perm:[1,0,3,2] row_mask:0xf bank_mask:0xf
	s_nop 1
	v_add_f32_dpp v63, v63, v63 quad_perm:[2,3,0,1] row_mask:0xf bank_mask:0xf
	s_nop 1
	v_add_f32_dpp v63, v63, v63 row_half_mirror row_mask:0xf bank_mask:0xf
	s_nop 1
	v_add_f32_dpp v63, v63, v63 row_mirror row_mask:0xf bank_mask:0xf
	v_mov_b32_e32 v64, v63
	s_nop 1
	v_permlane16_swap_b32_e32 v64, v63
	v_add_f32_e32 v63, v63, v64
	v_mov_b32_e32 v64, v63
	s_nop 1
	v_permlane32_swap_b32_e32 v64, v63
	v_add_f32_e32 v63, v63, v64
	v_cndmask_b32_e64 v62, v62, v63, s[66:67]
	s_waitcnt vmcnt(56)
	v_mul_f32_e32 v63, v13, v71
	s_nop 1
	v_add_f32_dpp v63, v63, v63 quad_perm:[1,0,3,2] row_mask:0xf bank_mask:0xf
	s_nop 1
	v_add_f32_dpp v63, v63, v63 quad_perm:[2,3,0,1] row_mask:0xf bank_mask:0xf
	s_nop 1
	v_add_f32_dpp v63, v63, v63 row_half_mirror row_mask:0xf bank_mask:0xf
	s_nop 1
	v_add_f32_dpp v63, v63, v63 row_mirror row_mask:0xf bank_mask:0xf
	v_mov_b32_e32 v64, v63
	s_nop 1
	v_permlane16_swap_b32_e32 v64, v63
	v_add_f32_e32 v63, v63, v64
	v_mov_b32_e32 v64, v63
	s_nop 1
	v_permlane32_swap_b32_e32 v64, v63
	v_add_f32_e32 v63, v63, v64
	v_cndmask_b32_e64 v62, v62, v63, s[68:69]
	s_waitcnt vmcnt(55)
	v_mul_f32_e32 v63, v13, v72
	s_nop 1
	v_add_f32_dpp v63, v63, v63 quad_perm:[1,0,3,2] row_mask:0xf bank_mask:0xf
	s_nop 1
	v_add_f32_dpp v63, v63, v63 quad_perm:[2,3,0,1] row_mask:0xf bank_mask:0xf
	s_nop 1
	v_add_f32_dpp v63, v63, v63 row_half_mirror row_mask:0xf bank_mask:0xf
	s_nop 1
	v_add_f32_dpp v63, v63, v63 row_mirror row_mask:0xf bank_mask:0xf
	v_mov_b32_e32 v64, v63
	s_nop 1
	v_permlane16_swap_b32_e32 v64, v63
	v_add_f32_e32 v63, v63, v64
	v_mov_b32_e32 v64, v63
	s_nop 1
	v_permlane32_swap_b32_e32 v64, v63
	v_add_f32_e32 v63, v63, v64
	v_cndmask_b32_e64 v62, v62, v63, s[70:71]
	s_waitcnt vmcnt(54)
	v_mul_f32_e32 v63, v13, v73
	s_nop 1
	v_add_f32_dpp v63, v63, v63 quad_perm:[1,0,3,2] row_mask:0xf bank_mask:0xf
	s_nop 1
	v_add_f32_dpp v63, v63, v63 quad_perm:[2,3,0,1] row_mask:0xf bank_mask:0xf
	s_nop 1
	v_add_f32_dpp v63, v63, v63 row_half_mirror row_mask:0xf bank_mask:0xf
	s_nop 1
	v_add_f32_dpp v63, v63, v63 row_mirror row_mask:0xf bank_mask:0xf
	v_mov_b32_e32 v64, v63
	s_nop 1
	v_permlane16_swap_b32_e32 v64, v63
	v_add_f32_e32 v63, v63, v64
	v_mov_b32_e32 v64, v63
	s_nop 1
	v_permlane32_swap_b32_e32 v64, v63
	v_add_f32_e32 v63, v63, v64
	v_cndmask_b32_e64 v62, v62, v63, s[72:73]
	s_waitcnt vmcnt(53)
	v_mul_f32_e32 v63, v13, v74
	s_nop 1
	v_add_f32_dpp v63, v63, v63 quad_perm:[1,0,3,2] row_mask:0xf bank_mask:0xf
	s_nop 1
	v_add_f32_dpp v63, v63, v63 quad_perm:[2,3,0,1] row_mask:0xf bank_mask:0xf
	s_nop 1
	v_add_f32_dpp v63, v63, v63 row_half_mirror row_mask:0xf bank_mask:0xf
	s_nop 1
	v_add_f32_dpp v63, v63, v63 row_mirror row_mask:0xf bank_mask:0xf
	v_mov_b32_e32 v64, v63
	s_nop 1
	v_permlane16_swap_b32_e32 v64, v63
	v_add_f32_e32 v63, v63, v64
	v_mov_b32_e32 v64, v63
	s_nop 1
	v_permlane32_swap_b32_e32 v64, v63
	v_add_f32_e32 v63, v63, v64
	v_cndmask_b32_e64 v62, v62, v63, s[74:75]
	s_waitcnt vmcnt(52)
	v_mul_f32_e32 v63, v13, v75
	s_nop 1
	v_add_f32_dpp v63, v63, v63 quad_perm:[1,0,3,2] row_mask:0xf bank_mask:0xf
	s_nop 1
	v_add_f32_dpp v63, v63, v63 quad_perm:[2,3,0,1] row_mask:0xf bank_mask:0xf
	s_nop 1
	v_add_f32_dpp v63, v63, v63 row_half_mirror row_mask:0xf bank_mask:0xf
	s_nop 1
	v_add_f32_dpp v63, v63, v63 row_mirror row_mask:0xf bank_mask:0xf
	v_mov_b32_e32 v64, v63
	s_nop 1
	v_permlane16_swap_b32_e32 v64, v63
	v_add_f32_e32 v63, v63, v64
	v_mov_b32_e32 v64, v63
	s_nop 1
	v_permlane32_swap_b32_e32 v64, v63
	v_add_f32_e32 v63, v63, v64
	v_cndmask_b32_e64 v62, v62, v63, s[44:45]
	s_waitcnt vmcnt(51)
	v_mul_f32_e32 v63, v13, v76
	s_nop 1
	v_add_f32_dpp v63, v63, v63 quad_perm:[1,0,3,2] row_mask:0xf bank_mask:0xf
	s_nop 1
	v_add_f32_dpp v63, v63, v63 quad_perm:[2,3,0,1] row_mask:0xf bank_mask:0xf
	s_nop 1
	v_add_f32_dpp v63, v63, v63 row_half_mirror row_mask:0xf bank_mask:0xf
	s_nop 1
	v_add_f32_dpp v63, v63, v63 row_mirror row_mask:0xf bank_mask:0xf
	v_mov_b32_e32 v64, v63
	s_nop 1
	v_permlane16_swap_b32_e32 v64, v63
	v_add_f32_e32 v63, v63, v64
	v_mov_b32_e32 v64, v63
	s_nop 1
	v_permlane32_swap_b32_e32 v64, v63
	v_add_f32_e32 v63, v63, v64
	v_cndmask_b32_e64 v62, v62, v63, s[46:47]
	s_waitcnt vmcnt(50)
	v_mul_f32_e32 v63, v13, v77
	s_nop 1
	v_add_f32_dpp v63, v63, v63 quad_perm:[1,0,3,2] row_mask:0xf bank_mask:0xf
	s_nop 1
	v_add_f32_dpp v63, v63, v63 quad_perm:[2,3,0,1] row_mask:0xf bank_mask:0xf
	s_nop 1
	v_add_f32_dpp v63, v63, v63 row_half_mirror row_mask:0xf bank_mask:0xf
	s_nop 1
	v_add_f32_dpp v63, v63, v63 row_mirror row_mask:0xf bank_mask:0xf
	v_mov_b32_e32 v64, v63
	s_nop 1
	v_permlane16_swap_b32_e32 v64, v63
	v_add_f32_e32 v63, v63, v64
	v_mov_b32_e32 v64, v63
	s_nop 1
	v_permlane32_swap_b32_e32 v64, v63
	v_add_f32_e32 v63, v63, v64
	v_cndmask_b32_e64 v62, v62, v63, s[96:97]
	s_waitcnt vmcnt(49)
	v_mul_f32_e32 v63, v13, v78
	s_nop 1
	v_add_f32_dpp v63, v63, v63 quad_perm:[1,0,3,2] row_mask:0xf bank_mask:0xf
	s_nop 1
	v_add_f32_dpp v63, v63, v63 quad_perm:[2,3,0,1] row_mask:0xf bank_mask:0xf
	s_nop 1
	v_add_f32_dpp v63, v63, v63 row_half_mirror row_mask:0xf bank_mask:0xf
	s_nop 1
	v_add_f32_dpp v63, v63, v63 row_mirror row_mask:0xf bank_mask:0xf
	v_mov_b32_e32 v64, v63
	s_nop 1
	v_permlane16_swap_b32_e32 v64, v63
	v_add_f32_e32 v63, v63, v64
	v_mov_b32_e32 v64, v63
	s_nop 1
	v_permlane32_swap_b32_e32 v64, v63
	v_add_f32_e32 v63, v63, v64
	v_cndmask_b32_e64 v62, v62, v63, s[94:95]
	s_waitcnt vmcnt(48)
	v_mul_f32_e32 v63, v13, v79
	s_nop 1
	v_add_f32_dpp v63, v63, v63 quad_perm:[1,0,3,2] row_mask:0xf bank_mask:0xf
	s_nop 1
	v_add_f32_dpp v63, v63, v63 quad_perm:[2,3,0,1] row_mask:0xf bank_mask:0xf
	s_nop 1
	v_add_f32_dpp v63, v63, v63 row_half_mirror row_mask:0xf bank_mask:0xf
	s_nop 1
	v_add_f32_dpp v63, v63, v63 row_mirror row_mask:0xf bank_mask:0xf
	v_mov_b32_e32 v64, v63
	s_nop 1
	v_permlane16_swap_b32_e32 v64, v63
	v_add_f32_e32 v63, v63, v64
	v_mov_b32_e32 v64, v63
	s_nop 1
	v_permlane32_swap_b32_e32 v64, v63
	v_add_f32_e32 v63, v63, v64
	v_cndmask_b32_e64 v62, v62, v63, s[92:93]
	s_waitcnt vmcnt(47)
	v_mul_f32_e32 v63, v13, v80
	s_nop 1
	v_add_f32_dpp v63, v63, v63 quad_perm:[1,0,3,2] row_mask:0xf bank_mask:0xf
	s_nop 1
	v_add_f32_dpp v63, v63, v63 quad_perm:[2,3,0,1] row_mask:0xf bank_mask:0xf
	s_nop 1
	v_add_f32_dpp v63, v63, v63 row_half_mirror row_mask:0xf bank_mask:0xf
	s_nop 1
	v_add_f32_dpp v63, v63, v63 row_mirror row_mask:0xf bank_mask:0xf
	v_mov_b32_e32 v64, v63
	s_nop 1
	v_permlane16_swap_b32_e32 v64, v63
	v_add_f32_e32 v63, v63, v64
	v_mov_b32_e32 v64, v63
	s_nop 1
	v_permlane32_swap_b32_e32 v64, v63
	v_add_f32_e32 v63, v63, v64
	v_cndmask_b32_e64 v62, v62, v63, s[90:91]
	s_waitcnt vmcnt(46)
	v_mul_f32_e32 v63, v13, v81
	s_nop 1
	v_add_f32_dpp v63, v63, v63 quad_perm:[1,0,3,2] row_mask:0xf bank_mask:0xf
	s_nop 1
	v_add_f32_dpp v63, v63, v63 quad_perm:[2,3,0,1] row_mask:0xf bank_mask:0xf
	s_nop 1
	v_add_f32_dpp v63, v63, v63 row_half_mirror row_mask:0xf bank_mask:0xf
	s_nop 1
	v_add_f32_dpp v63, v63, v63 row_mirror row_mask:0xf bank_mask:0xf
	v_mov_b32_e32 v64, v63
	s_nop 1
	v_permlane16_swap_b32_e32 v64, v63
	v_add_f32_e32 v63, v63, v64
	v_mov_b32_e32 v64, v63
	s_nop 1
	v_permlane32_swap_b32_e32 v64, v63
	v_add_f32_e32 v63, v63, v64
	v_cndmask_b32_e64 v62, v62, v63, s[88:89]
	s_waitcnt vmcnt(45)
	v_mul_f32_e32 v63, v13, v82
	s_nop 1
	v_add_f32_dpp v63, v63, v63 quad_perm:[1,0,3,2] row_mask:0xf bank_mask:0xf
	s_nop 1
	v_add_f32_dpp v63, v63, v63 quad_perm:[2,3,0,1] row_mask:0xf bank_mask:0xf
	s_nop 1
	v_add_f32_dpp v63, v63, v63 row_half_mirror row_mask:0xf bank_mask:0xf
	s_nop 1
	v_add_f32_dpp v63, v63, v63 row_mirror row_mask:0xf bank_mask:0xf
	v_mov_b32_e32 v64, v63
	s_nop 1
	v_permlane16_swap_b32_e32 v64, v63
	v_add_f32_e32 v63, v63, v64
	v_mov_b32_e32 v64, v63
	s_nop 1
	v_permlane32_swap_b32_e32 v64, v63
	v_add_f32_e32 v63, v63, v64
	v_cndmask_b32_e64 v62, v62, v63, s[84:85]
	s_waitcnt vmcnt(44)
	v_mul_f32_e32 v63, v13, v83
	s_nop 1
	v_add_f32_dpp v63, v63, v63 quad_perm:[1,0,3,2] row_mask:0xf bank_mask:0xf
	s_nop 1
	v_add_f32_dpp v63, v63, v63 quad_perm:[2,3,0,1] row_mask:0xf bank_mask:0xf
	s_nop 1
	v_add_f32_dpp v63, v63, v63 row_half_mirror row_mask:0xf bank_mask:0xf
	s_nop 1
	v_add_f32_dpp v63, v63, v63 row_mirror row_mask:0xf bank_mask:0xf
	v_mov_b32_e32 v64, v63
	s_nop 1
	v_permlane16_swap_b32_e32 v64, v63
	v_add_f32_e32 v63, v63, v64
	v_mov_b32_e32 v64, v63
	s_nop 1
	v_permlane32_swap_b32_e32 v64, v63
	v_add_f32_e32 v63, v63, v64
	v_cndmask_b32_e64 v62, v62, v63, s[82:83]
	s_waitcnt vmcnt(43)
	v_mul_f32_e32 v63, v13, v84
	s_nop 1
	v_add_f32_dpp v63, v63, v63 quad_perm:[1,0,3,2] row_mask:0xf bank_mask:0xf
	s_nop 1
	v_add_f32_dpp v63, v63, v63 quad_perm:[2,3,0,1] row_mask:0xf bank_mask:0xf
	s_nop 1
	v_add_f32_dpp v63, v63, v63 row_half_mirror row_mask:0xf bank_mask:0xf
	s_nop 1
	v_add_f32_dpp v63, v63, v63 row_mirror row_mask:0xf bank_mask:0xf
	v_mov_b32_e32 v64, v63
	s_nop 1
	v_permlane16_swap_b32_e32 v64, v63
	v_add_f32_e32 v63, v63, v64
	v_mov_b32_e32 v64, v63
	s_nop 1
	v_permlane32_swap_b32_e32 v64, v63
	v_add_f32_e32 v63, v63, v64
	v_cndmask_b32_e64 v62, v62, v63, s[80:81]
	s_waitcnt vmcnt(42)
	v_mul_f32_e32 v63, v13, v85
	s_nop 1
	v_add_f32_dpp v63, v63, v63 quad_perm:[1,0,3,2] row_mask:0xf bank_mask:0xf
	s_nop 1
	v_add_f32_dpp v63, v63, v63 quad_perm:[2,3,0,1] row_mask:0xf bank_mask:0xf
	s_nop 1
	v_add_f32_dpp v63, v63, v63 row_half_mirror row_mask:0xf bank_mask:0xf
	s_nop 1
	v_add_f32_dpp v63, v63, v63 row_mirror row_mask:0xf bank_mask:0xf
	v_mov_b32_e32 v64, v63
	s_nop 1
	v_permlane16_swap_b32_e32 v64, v63
	v_add_f32_e32 v63, v63, v64
	v_mov_b32_e32 v64, v63
	s_nop 1
	v_permlane32_swap_b32_e32 v64, v63
	v_add_f32_e32 v63, v63, v64
	v_cndmask_b32_e64 v62, v62, v63, s[76:77]
	s_waitcnt vmcnt(41)
	v_mul_f32_e32 v63, v13, v86
	s_nop 1
	v_add_f32_dpp v63, v63, v63 quad_perm:[1,0,3,2] row_mask:0xf bank_mask:0xf
	s_nop 1
	v_add_f32_dpp v63, v63, v63 quad_perm:[2,3,0,1] row_mask:0xf bank_mask:0xf
	s_nop 1
	v_add_f32_dpp v63, v63, v63 row_half_mirror row_mask:0xf bank_mask:0xf
	s_nop 1
	v_add_f32_dpp v63, v63, v63 row_mirror row_mask:0xf bank_mask:0xf
	v_mov_b32_e32 v64, v63
	s_nop 1
	v_permlane16_swap_b32_e32 v64, v63
	v_add_f32_e32 v63, v63, v64
	v_mov_b32_e32 v64, v63
	s_nop 1
	v_permlane32_swap_b32_e32 v64, v63
	v_add_f32_e32 v63, v63, v64
	v_cndmask_b32_e64 v62, v62, v63, s[0:1]
	s_waitcnt vmcnt(40)
	v_mul_f32_e32 v63, v13, v87
	s_nop 1
	v_add_f32_dpp v63, v63, v63 quad_perm:[1,0,3,2] row_mask:0xf bank_mask:0xf
	s_nop 1
	v_add_f32_dpp v63, v63, v63 quad_perm:[2,3,0,1] row_mask:0xf bank_mask:0xf
	s_nop 1
	v_add_f32_dpp v63, v63, v63 row_half_mirror row_mask:0xf bank_mask:0xf
	s_nop 1
	v_add_f32_dpp v63, v63, v63 row_mirror row_mask:0xf bank_mask:0xf
	v_mov_b32_e32 v64, v63
	s_nop 1
	v_permlane16_swap_b32_e32 v64, v63
	v_add_f32_e32 v63, v63, v64
	v_mov_b32_e32 v64, v63
	s_nop 1
	v_permlane32_swap_b32_e32 v64, v63
	v_add_f32_e32 v63, v63, v64
	v_cndmask_b32_e64 v62, v62, v63, s[2:3]
	s_waitcnt vmcnt(39)
	v_mul_f32_e32 v63, v13, v61
	s_nop 1
	v_add_f32_dpp v63, v63, v63 quad_perm:[1,0,3,2] row_mask:0xf bank_mask:0xf
	s_nop 1
	v_add_f32_dpp v61, v63, v63 quad_perm:[2,3,0,1] row_mask:0xf bank_mask:0xf
	s_nop 1
	v_add_f32_dpp v61, v61, v61 row_half_mirror row_mask:0xf bank_mask:0xf
	s_nop 1
	v_add_f32_dpp v61, v61, v61 row_mirror row_mask:0xf bank_mask:0xf
	v_mov_b32_e32 v63, v61
	s_nop 1
	v_permlane16_swap_b32_e32 v63, v61
	v_add_f32_e32 v61, v61, v63
	v_mov_b32_e32 v63, v61
	s_nop 1
	v_permlane32_swap_b32_e32 v63, v61
	v_add_f32_e32 v61, v61, v63
	v_cndmask_b32_e64 v61, v62, v61, s[4:5]
	s_waitcnt vmcnt(38)
	v_mul_f32_e32 v62, v13, v60
	s_nop 1
	v_add_f32_dpp v62, v62, v62 quad_perm:[1,0,3,2] row_mask:0xf bank_mask:0xf
	s_nop 1
	v_add_f32_dpp v60, v62, v62 quad_perm:[2,3,0,1] row_mask:0xf bank_mask:0xf
	s_nop 1
	v_add_f32_dpp v60, v60, v60 row_half_mirror row_mask:0xf bank_mask:0xf
	s_nop 1
	v_add_f32_dpp v60, v60, v60 row_mirror row_mask:0xf bank_mask:0xf
	v_mov_b32_e32 v62, v60
	s_nop 1
	v_permlane16_swap_b32_e32 v62, v60
	v_add_f32_e32 v60, v60, v62
	v_mov_b32_e32 v62, v60
	s_nop 1
	v_permlane32_swap_b32_e32 v62, v60
	v_add_f32_e32 v60, v60, v62
	v_cndmask_b32_e64 v60, v61, v60, s[6:7]
	s_waitcnt vmcnt(37)
	v_mul_f32_e32 v61, v13, v59
	s_nop 1
	v_add_f32_dpp v61, v61, v61 quad_perm:[1,0,3,2] row_mask:0xf bank_mask:0xf
	s_nop 1
	v_add_f32_dpp v59, v61, v61 quad_perm:[2,3,0,1] row_mask:0xf bank_mask:0xf
	s_nop 1
	v_add_f32_dpp v59, v59, v59 row_half_mirror row_mask:0xf bank_mask:0xf
	s_nop 1
	v_add_f32_dpp v59, v59, v59 row_mirror row_mask:0xf bank_mask:0xf
	v_mov_b32_e32 v61, v59
	s_nop 1
	v_permlane16_swap_b32_e32 v61, v59
	v_add_f32_e32 v59, v59, v61
	v_mov_b32_e32 v61, v59
	s_nop 1
	v_permlane32_swap_b32_e32 v61, v59
	v_add_f32_e32 v59, v59, v61
	v_cndmask_b32_e64 v59, v60, v59, s[8:9]
	s_waitcnt vmcnt(36)
	v_mul_f32_e32 v60, v13, v58
	s_nop 1
	v_add_f32_dpp v60, v60, v60 quad_perm:[1,0,3,2] row_mask:0xf bank_mask:0xf
	s_nop 1
	v_add_f32_dpp v58, v60, v60 quad_perm:[2,3,0,1] row_mask:0xf bank_mask:0xf
	s_nop 1
	v_add_f32_dpp v58, v58, v58 row_half_mirror row_mask:0xf bank_mask:0xf
	s_nop 1
	v_add_f32_dpp v58, v58, v58 row_mirror row_mask:0xf bank_mask:0xf
	v_mov_b32_e32 v60, v58
	s_nop 1
	v_permlane16_swap_b32_e32 v60, v58
	v_add_f32_e32 v58, v58, v60
	v_mov_b32_e32 v60, v58
	s_nop 1
	v_permlane32_swap_b32_e32 v60, v58
	v_add_f32_e32 v58, v58, v60
	v_cndmask_b32_e64 v58, v59, v58, s[10:11]
	s_waitcnt vmcnt(35)
	v_mul_f32_e32 v59, v13, v57
	s_nop 1
	v_add_f32_dpp v59, v59, v59 quad_perm:[1,0,3,2] row_mask:0xf bank_mask:0xf
	s_nop 1
	v_add_f32_dpp v57, v59, v59 quad_perm:[2,3,0,1] row_mask:0xf bank_mask:0xf
	s_nop 1
	v_add_f32_dpp v57, v57, v57 row_half_mirror row_mask:0xf bank_mask:0xf
	s_nop 1
	v_add_f32_dpp v57, v57, v57 row_mirror row_mask:0xf bank_mask:0xf
	v_mov_b32_e32 v59, v57
	s_nop 1
	v_permlane16_swap_b32_e32 v59, v57
	v_add_f32_e32 v57, v57, v59
	v_mov_b32_e32 v59, v57
	s_nop 1
	v_permlane32_swap_b32_e32 v59, v57
	v_add_f32_e32 v57, v57, v59
	v_cndmask_b32_e64 v57, v58, v57, s[12:13]
	s_waitcnt vmcnt(34)
	v_mul_f32_e32 v58, v13, v56
	s_nop 1
	v_add_f32_dpp v58, v58, v58 quad_perm:[1,0,3,2] row_mask:0xf bank_mask:0xf
	s_nop 1
	v_add_f32_dpp v56, v58, v58 quad_perm:[2,3,0,1] row_mask:0xf bank_mask:0xf
	s_nop 1
	v_add_f32_dpp v56, v56, v56 row_half_mirror row_mask:0xf bank_mask:0xf
	s_nop 1
	v_add_f32_dpp v56, v56, v56 row_mirror row_mask:0xf bank_mask:0xf
	v_mov_b32_e32 v58, v56
	s_nop 1
	v_permlane16_swap_b32_e32 v58, v56
	v_add_f32_e32 v56, v56, v58
	v_mov_b32_e32 v58, v56
	s_nop 1
	v_permlane32_swap_b32_e32 v58, v56
	v_add_f32_e32 v56, v56, v58
	v_cndmask_b32_e64 v56, v57, v56, s[14:15]
	s_waitcnt vmcnt(33)
	v_mul_f32_e32 v57, v13, v55
	global_load_dword v58, v[10:11], off
	global_load_dword v59, v[10:11], off offset:2048
	s_nop 1
	v_add_f32_dpp v57, v57, v57 quad_perm:[1,0,3,2] row_mask:0xf bank_mask:0xf
	s_nop 1
	v_add_f32_dpp v55, v57, v57 quad_perm:[2,3,0,1] row_mask:0xf bank_mask:0xf
	s_nop 1
	v_add_f32_dpp v55, v55, v55 row_half_mirror row_mask:0xf bank_mask:0xf
	s_nop 1
	v_add_f32_dpp v55, v55, v55 row_mirror row_mask:0xf bank_mask:0xf
	v_mov_b32_e32 v57, v55
	s_nop 1
	v_permlane16_swap_b32_e32 v57, v55
	v_add_f32_e32 v55, v55, v57
	v_mov_b32_e32 v57, v55
	s_nop 1
	v_permlane32_swap_b32_e32 v57, v55
	v_add_f32_e32 v55, v55, v57
	v_cndmask_b32_e64 v55, v56, v55, s[16:17]
	s_waitcnt vmcnt(34)
	v_mul_f32_e32 v56, v13, v54
	s_nop 1
	v_add_f32_dpp v56, v56, v56 quad_perm:[1,0,3,2] row_mask:0xf bank_mask:0xf
	s_nop 1
	v_add_f32_dpp v54, v56, v56 quad_perm:[2,3,0,1] row_mask:0xf bank_mask:0xf
	s_nop 1
	v_add_f32_dpp v54, v54, v54 row_half_mirror row_mask:0xf bank_mask:0xf
	s_nop 1
	v_add_f32_dpp v54, v54, v54 row_mirror row_mask:0xf bank_mask:0xf
	v_mov_b32_e32 v56, v54
	s_nop 1
	v_permlane16_swap_b32_e32 v56, v54
	v_add_f32_e32 v54, v54, v56
	v_mov_b32_e32 v56, v54
	s_nop 1
	v_permlane32_swap_b32_e32 v56, v54
	v_add_f32_e32 v54, v54, v56
	v_cndmask_b32_e64 v54, v55, v54, s[18:19]
	s_waitcnt vmcnt(33)
	v_mul_f32_e32 v55, v13, v53
	s_nop 1
	v_add_f32_dpp v55, v55, v55 quad_perm:[1,0,3,2] row_mask:0xf bank_mask:0xf
	s_nop 1
	v_add_f32_dpp v53, v55, v55 quad_perm:[2,3,0,1] row_mask:0xf bank_mask:0xf
	s_nop 1
	v_add_f32_dpp v53, v53, v53 row_half_mirror row_mask:0xf bank_mask:0xf
	s_nop 1
	v_add_f32_dpp v53, v53, v53 row_mirror row_mask:0xf bank_mask:0xf
	v_mov_b32_e32 v55, v53
	s_nop 1
	v_permlane16_swap_b32_e32 v55, v53
	v_add_f32_e32 v53, v53, v55
	v_mov_b32_e32 v55, v53
	s_nop 1
	v_permlane32_swap_b32_e32 v55, v53
	v_add_f32_e32 v53, v53, v55
	v_cndmask_b32_e64 v53, v54, v53, s[20:21]
	s_waitcnt vmcnt(32)
	v_mul_f32_e32 v54, v13, v52
	s_nop 1
	v_add_f32_dpp v54, v54, v54 quad_perm:[1,0,3,2] row_mask:0xf bank_mask:0xf
	s_nop 1
	v_add_f32_dpp v52, v54, v54 quad_perm:[2,3,0,1] row_mask:0xf bank_mask:0xf
	s_nop 1
	v_add_f32_dpp v52, v52, v52 row_half_mirror row_mask:0xf bank_mask:0xf
	s_nop 1
	v_add_f32_dpp v52, v52, v52 row_mirror row_mask:0xf bank_mask:0xf
	v_mov_b32_e32 v54, v52
	s_nop 1
	v_permlane16_swap_b32_e32 v54, v52
	v_add_f32_e32 v52, v52, v54
	v_mov_b32_e32 v54, v52
	s_nop 1
	v_permlane32_swap_b32_e32 v54, v52
	v_add_f32_e32 v52, v52, v54
	v_cndmask_b32_e64 v52, v53, v52, s[22:23]
	s_waitcnt vmcnt(31)
	v_mul_f32_e32 v53, v13, v51
	s_nop 1
	v_add_f32_dpp v53, v53, v53 quad_perm:[1,0,3,2] row_mask:0xf bank_mask:0xf
	s_nop 1
	v_add_f32_dpp v51, v53, v53 quad_perm:[2,3,0,1] row_mask:0xf bank_mask:0xf
	s_nop 1
	v_add_f32_dpp v51, v51, v51 row_half_mirror row_mask:0xf bank_mask:0xf
	s_nop 1
	v_add_f32_dpp v51, v51, v51 row_mirror row_mask:0xf bank_mask:0xf
	v_mov_b32_e32 v53, v51
	s_nop 1
	v_permlane16_swap_b32_e32 v53, v51
	v_add_f32_e32 v51, v51, v53
	v_mov_b32_e32 v53, v51
	s_nop 1
	v_permlane32_swap_b32_e32 v53, v51
	v_add_f32_e32 v51, v51, v53
	v_cndmask_b32_e64 v51, v52, v51, s[24:25]
	s_waitcnt vmcnt(30)
	v_mul_f32_e32 v52, v13, v50
	s_nop 1
	v_add_f32_dpp v52, v52, v52 quad_perm:[1,0,3,2] row_mask:0xf bank_mask:0xf
	s_nop 1
	v_add_f32_dpp v50, v52, v52 quad_perm:[2,3,0,1] row_mask:0xf bank_mask:0xf
	s_nop 1
	v_add_f32_dpp v50, v50, v50 row_half_mirror row_mask:0xf bank_mask:0xf
	s_nop 1
	v_add_f32_dpp v50, v50, v50 row_mirror row_mask:0xf bank_mask:0xf
	v_mov_b32_e32 v52, v50
	s_nop 1
	v_permlane16_swap_b32_e32 v52, v50
	v_add_f32_e32 v50, v50, v52
	v_mov_b32_e32 v52, v50
	s_nop 1
	v_permlane32_swap_b32_e32 v52, v50
	v_add_f32_e32 v50, v50, v52
	v_cndmask_b32_e64 v50, v51, v50, s[26:27]
	s_waitcnt vmcnt(29)
	v_mul_f32_e32 v51, v13, v49
	s_nop 1
	v_add_f32_dpp v51, v51, v51 quad_perm:[1,0,3,2] row_mask:0xf bank_mask:0xf
	s_nop 1
	v_add_f32_dpp v49, v51, v51 quad_perm:[2,3,0,1] row_mask:0xf bank_mask:0xf
	s_nop 1
	v_add_f32_dpp v49, v49, v49 row_half_mirror row_mask:0xf bank_mask:0xf
	s_nop 1
	v_add_f32_dpp v49, v49, v49 row_mirror row_mask:0xf bank_mask:0xf
	v_mov_b32_e32 v51, v49
	s_nop 1
	v_permlane16_swap_b32_e32 v51, v49
	v_add_f32_e32 v49, v49, v51
	v_mov_b32_e32 v51, v49
	s_nop 1
	v_permlane32_swap_b32_e32 v51, v49
	v_add_f32_e32 v49, v49, v51
	v_cndmask_b32_e64 v49, v50, v49, s[28:29]
	s_waitcnt vmcnt(28)
	v_mul_f32_e32 v50, v13, v48
	s_nop 1
	v_add_f32_dpp v50, v50, v50 quad_perm:[1,0,3,2] row_mask:0xf bank_mask:0xf
	s_nop 1
	v_add_f32_dpp v48, v50, v50 quad_perm:[2,3,0,1] row_mask:0xf bank_mask:0xf
	s_nop 1
	v_add_f32_dpp v48, v48, v48 row_half_mirror row_mask:0xf bank_mask:0xf
	s_nop 1
	v_add_f32_dpp v48, v48, v48 row_mirror row_mask:0xf bank_mask:0xf
	v_mov_b32_e32 v50, v48
	s_nop 1
	v_permlane16_swap_b32_e32 v50, v48
	v_add_f32_e32 v48, v48, v50
	v_mov_b32_e32 v50, v48
	s_nop 1
	v_permlane32_swap_b32_e32 v50, v48
	v_add_f32_e32 v48, v48, v50
	v_cndmask_b32_e64 v48, v49, v48, s[30:31]
	s_waitcnt vmcnt(27)
	v_mul_f32_e32 v49, v13, v47
	s_nop 1
	v_add_f32_dpp v49, v49, v49 quad_perm:[1,0,3,2] row_mask:0xf bank_mask:0xf
	s_nop 1
	v_add_f32_dpp v47, v49, v49 quad_perm:[2,3,0,1] row_mask:0xf bank_mask:0xf
	s_nop 1
	v_add_f32_dpp v47, v47, v47 row_half_mirror row_mask:0xf bank_mask:0xf
	s_nop 1
	v_add_f32_dpp v47, v47, v47 row_mirror row_mask:0xf bank_mask:0xf
	v_mov_b32_e32 v49, v47
	s_nop 1
	v_permlane16_swap_b32_e32 v49, v47
	v_add_f32_e32 v47, v47, v49
	v_mov_b32_e32 v49, v47
	s_nop 1
	v_permlane32_swap_b32_e32 v49, v47
	v_add_f32_e32 v47, v47, v49
	v_cndmask_b32_e64 v47, v48, v47, s[34:35]
	s_waitcnt vmcnt(26)
	v_mul_f32_e32 v48, v13, v46
	s_nop 1
	v_add_f32_dpp v48, v48, v48 quad_perm:[1,0,3,2] row_mask:0xf bank_mask:0xf
	s_nop 1
	v_add_f32_dpp v46, v48, v48 quad_perm:[2,3,0,1] row_mask:0xf bank_mask:0xf
	s_nop 1
	v_add_f32_dpp v46, v46, v46 row_half_mirror row_mask:0xf bank_mask:0xf
	s_nop 1
	v_add_f32_dpp v46, v46, v46 row_mirror row_mask:0xf bank_mask:0xf
	v_mov_b32_e32 v48, v46
	s_nop 1
	v_permlane16_swap_b32_e32 v48, v46
	v_add_f32_e32 v46, v46, v48
	v_mov_b32_e32 v48, v46
	s_nop 1
	v_permlane32_swap_b32_e32 v48, v46
	v_add_f32_e32 v46, v46, v48
	v_cndmask_b32_e64 v46, v47, v46, s[36:37]
	s_waitcnt vmcnt(25)
	v_mul_f32_e32 v47, v13, v45
	s_nop 1
	v_add_f32_dpp v47, v47, v47 quad_perm:[1,0,3,2] row_mask:0xf bank_mask:0xf
	s_nop 1
	v_add_f32_dpp v45, v47, v47 quad_perm:[2,3,0,1] row_mask:0xf bank_mask:0xf
	s_nop 1
	v_add_f32_dpp v45, v45, v45 row_half_mirror row_mask:0xf bank_mask:0xf
	s_nop 1
	v_add_f32_dpp v45, v45, v45 row_mirror row_mask:0xf bank_mask:0xf
	v_mov_b32_e32 v47, v45
	s_nop 1
	v_permlane16_swap_b32_e32 v47, v45
	v_add_f32_e32 v45, v45, v47
	v_mov_b32_e32 v47, v45
	s_nop 1
	v_permlane32_swap_b32_e32 v47, v45
	v_add_f32_e32 v45, v45, v47
	v_cndmask_b32_e64 v45, v46, v45, s[38:39]
	s_waitcnt vmcnt(24)
	v_mul_f32_e32 v46, v13, v44
	s_nop 1
	v_add_f32_dpp v46, v46, v46 quad_perm:[1,0,3,2] row_mask:0xf bank_mask:0xf
	s_nop 1
	v_add_f32_dpp v44, v46, v46 quad_perm:[2,3,0,1] row_mask:0xf bank_mask:0xf
	s_nop 1
	v_add_f32_dpp v44, v44, v44 row_half_mirror row_mask:0xf bank_mask:0xf
	s_nop 1
	v_add_f32_dpp v44, v44, v44 row_mirror row_mask:0xf bank_mask:0xf
	v_mov_b32_e32 v46, v44
	s_nop 1
	v_permlane16_swap_b32_e32 v46, v44
	v_add_f32_e32 v44, v44, v46
	v_mov_b32_e32 v46, v44
	s_nop 1
	v_permlane32_swap_b32_e32 v46, v44
	v_add_f32_e32 v44, v44, v46
	v_cndmask_b32_e64 v44, v45, v44, s[40:41]
	s_waitcnt vmcnt(23)
	v_mul_f32_e32 v45, v13, v43
	s_nop 1
	v_add_f32_dpp v45, v45, v45 quad_perm:[1,0,3,2] row_mask:0xf bank_mask:0xf
	s_nop 1
	v_add_f32_dpp v43, v45, v45 quad_perm:[2,3,0,1] row_mask:0xf bank_mask:0xf
	s_nop 1
	v_add_f32_dpp v43, v43, v43 row_half_mirror row_mask:0xf bank_mask:0xf
	s_nop 1
	v_add_f32_dpp v43, v43, v43 row_mirror row_mask:0xf bank_mask:0xf
	v_mov_b32_e32 v45, v43
	s_nop 1
	v_permlane16_swap_b32_e32 v45, v43
	v_add_f32_e32 v43, v43, v45
	v_mov_b32_e32 v45, v43
	s_nop 1
	v_permlane32_swap_b32_e32 v45, v43
	v_add_f32_e32 v43, v43, v45
	v_cndmask_b32_e64 v43, v44, v43, s[42:43]
	s_waitcnt vmcnt(22)
	v_mul_f32_e32 v44, v13, v42
	s_nop 1
	v_add_f32_dpp v44, v44, v44 quad_perm:[1,0,3,2] row_mask:0xf bank_mask:0xf
	s_nop 1
	v_add_f32_dpp v42, v44, v44 quad_perm:[2,3,0,1] row_mask:0xf bank_mask:0xf
	s_nop 1
	v_add_f32_dpp v42, v42, v42 row_half_mirror row_mask:0xf bank_mask:0xf
	s_nop 1
	v_add_f32_dpp v42, v42, v42 row_mirror row_mask:0xf bank_mask:0xf
	v_mov_b32_e32 v44, v42
	s_nop 1
	v_permlane16_swap_b32_e32 v44, v42
	v_add_f32_e32 v42, v42, v44
	v_mov_b32_e32 v44, v42
	s_nop 1
	v_permlane32_swap_b32_e32 v44, v42
	v_add_f32_e32 v42, v42, v44
	v_cndmask_b32_e64 v42, v43, v42, s[48:49]
	s_waitcnt vmcnt(21)
	v_mul_f32_e32 v43, v13, v41
	s_nop 1
	v_add_f32_dpp v43, v43, v43 quad_perm:[1,0,3,2] row_mask:0xf bank_mask:0xf
	s_nop 1
	v_add_f32_dpp v41, v43, v43 quad_perm:[2,3,0,1] row_mask:0xf bank_mask:0xf
	s_nop 1
	v_add_f32_dpp v41, v41, v41 row_half_mirror row_mask:0xf bank_mask:0xf
	s_nop 1
	v_add_f32_dpp v41, v41, v41 row_mirror row_mask:0xf bank_mask:0xf
	v_mov_b32_e32 v43, v41
	s_nop 1
	v_permlane16_swap_b32_e32 v43, v41
	v_add_f32_e32 v41, v41, v43
	v_mov_b32_e32 v43, v41
	s_nop 1
	v_permlane32_swap_b32_e32 v43, v41
	v_add_f32_e32 v41, v41, v43
	v_cndmask_b32_e64 v41, v42, v41, s[50:51]
	s_waitcnt vmcnt(20)
	v_mul_f32_e32 v42, v13, v40
	s_nop 1
	v_add_f32_dpp v42, v42, v42 quad_perm:[1,0,3,2] row_mask:0xf bank_mask:0xf
	s_nop 1
	v_add_f32_dpp v40, v42, v42 quad_perm:[2,3,0,1] row_mask:0xf bank_mask:0xf
	s_nop 1
	v_add_f32_dpp v40, v40, v40 row_half_mirror row_mask:0xf bank_mask:0xf
	s_nop 1
	v_add_f32_dpp v40, v40, v40 row_mirror row_mask:0xf bank_mask:0xf
	v_mov_b32_e32 v42, v40
	s_nop 1
	v_permlane16_swap_b32_e32 v42, v40
	v_add_f32_e32 v40, v40, v42
	v_mov_b32_e32 v42, v40
	s_nop 1
	v_permlane32_swap_b32_e32 v42, v40
	v_add_f32_e32 v40, v40, v42
	v_cndmask_b32_e64 v40, v41, v40, s[64:65]
	s_waitcnt vmcnt(19)
	v_mul_f32_e32 v41, v13, v39
	s_nop 1
	v_add_f32_dpp v41, v41, v41 quad_perm:[1,0,3,2] row_mask:0xf bank_mask:0xf
	s_nop 1
	v_add_f32_dpp v39, v41, v41 quad_perm:[2,3,0,1] row_mask:0xf bank_mask:0xf
	s_nop 1
	v_add_f32_dpp v39, v39, v39 row_half_mirror row_mask:0xf bank_mask:0xf
	s_nop 1
	v_add_f32_dpp v39, v39, v39 row_mirror row_mask:0xf bank_mask:0xf
	v_mov_b32_e32 v41, v39
	s_nop 1
	v_permlane16_swap_b32_e32 v41, v39
	v_add_f32_e32 v39, v39, v41
	v_mov_b32_e32 v41, v39
	s_nop 1
	v_permlane32_swap_b32_e32 v41, v39
	v_add_f32_e32 v39, v39, v41
	v_cndmask_b32_e64 v39, v40, v39, s[78:79]
	s_waitcnt vmcnt(18)
	v_mul_f32_e32 v40, v13, v38
	s_nop 1
	v_add_f32_dpp v40, v40, v40 quad_perm:[1,0,3,2] row_mask:0xf bank_mask:0xf
	s_nop 1
	v_add_f32_dpp v38, v40, v40 quad_perm:[2,3,0,1] row_mask:0xf bank_mask:0xf
	s_nop 1
	v_add_f32_dpp v38, v38, v38 row_half_mirror row_mask:0xf bank_mask:0xf
	s_nop 1
	v_add_f32_dpp v38, v38, v38 row_mirror row_mask:0xf bank_mask:0xf
	v_mov_b32_e32 v40, v38
	s_nop 1
	v_permlane16_swap_b32_e32 v40, v38
	v_add_f32_e32 v38, v38, v40
	v_mov_b32_e32 v40, v38
	s_nop 1
	v_permlane32_swap_b32_e32 v40, v38
	v_add_f32_e32 v38, v38, v40
	v_cndmask_b32_e64 v38, v39, v38, s[86:87]
	s_waitcnt vmcnt(17)
	v_mul_f32_e32 v39, v13, v37
	s_nop 1
	v_add_f32_dpp v39, v39, v39 quad_perm:[1,0,3,2] row_mask:0xf bank_mask:0xf
	s_nop 1
	v_add_f32_dpp v37, v39, v39 quad_perm:[2,3,0,1] row_mask:0xf bank_mask:0xf
	s_nop 1
	v_add_f32_dpp v37, v37, v37 row_half_mirror row_mask:0xf bank_mask:0xf
	s_nop 1
	v_add_f32_dpp v37, v37, v37 row_mirror row_mask:0xf bank_mask:0xf
	v_mov_b32_e32 v39, v37
	s_nop 1
	v_permlane16_swap_b32_e32 v39, v37
	v_add_f32_e32 v37, v37, v39
	v_mov_b32_e32 v39, v37
	s_nop 1
	v_permlane32_swap_b32_e32 v39, v37
	v_add_f32_e32 v37, v37, v39
	v_cndmask_b32_e32 v37, v38, v37, vcc
	s_waitcnt vmcnt(16)
	v_mul_f32_e32 v38, v13, v36
	v_readlane_b32 vcc_lo, v250, 15
	v_readlane_b32 vcc_hi, v250, 16
	s_nop 1
	v_add_f32_dpp v38, v38, v38 quad_perm:[1,0,3,2] row_mask:0xf bank_mask:0xf
	s_nop 1
	v_add_f32_dpp v36, v38, v38 quad_perm:[2,3,0,1] row_mask:0xf bank_mask:0xf
	s_nop 1
	v_add_f32_dpp v36, v36, v36 row_half_mirror row_mask:0xf bank_mask:0xf
	s_nop 1
	v_add_f32_dpp v36, v36, v36 row_mirror row_mask:0xf bank_mask:0xf
	v_mov_b32_e32 v38, v36
	s_nop 1
	v_permlane16_swap_b32_e32 v38, v36
	v_add_f32_e32 v36, v36, v38
	v_mov_b32_e32 v38, v36
	s_nop 1
	v_permlane32_swap_b32_e32 v38, v36
	v_add_f32_e32 v36, v36, v38
	v_cndmask_b32_e32 v36, v37, v36, vcc
	s_waitcnt vmcnt(15)
	v_mul_f32_e32 v37, v13, v35
	v_readlane_b32 vcc_lo, v250, 17
	v_readlane_b32 vcc_hi, v250, 18
	s_nop 1
	v_add_f32_dpp v37, v37, v37 quad_perm:[1,0,3,2] row_mask:0xf bank_mask:0xf
	s_nop 1
	v_add_f32_dpp v35, v37, v37 quad_perm:[2,3,0,1] row_mask:0xf bank_mask:0xf
	s_nop 1
	v_add_f32_dpp v35, v35, v35 row_half_mirror row_mask:0xf bank_mask:0xf
	s_nop 1
	v_add_f32_dpp v35, v35, v35 row_mirror row_mask:0xf bank_mask:0xf
	v_mov_b32_e32 v37, v35
	s_nop 1
	v_permlane16_swap_b32_e32 v37, v35
	v_add_f32_e32 v35, v35, v37
	v_mov_b32_e32 v37, v35
	s_nop 1
	v_permlane32_swap_b32_e32 v37, v35
	v_add_f32_e32 v35, v35, v37
	v_cndmask_b32_e32 v35, v36, v35, vcc
	s_waitcnt vmcnt(14)
	v_mul_f32_e32 v36, v13, v27
	v_readlane_b32 vcc_lo, v250, 19
	v_readlane_b32 vcc_hi, v250, 20
	s_nop 1
	v_add_f32_dpp v36, v36, v36 quad_perm:[1,0,3,2] row_mask:0xf bank_mask:0xf
	s_nop 1
	v_add_f32_dpp v27, v36, v36 quad_perm:[2,3,0,1] row_mask:0xf bank_mask:0xf
	s_nop 1
	v_add_f32_dpp v27, v27, v27 row_half_mirror row_mask:0xf bank_mask:0xf
	s_nop 1
	v_add_f32_dpp v27, v27, v27 row_mirror row_mask:0xf bank_mask:0xf
	v_mov_b32_e32 v36, v27
	s_nop 1
	v_permlane16_swap_b32_e32 v36, v27
	v_add_f32_e32 v27, v27, v36
	v_mov_b32_e32 v36, v27
	s_nop 1
	v_permlane32_swap_b32_e32 v36, v27
	v_add_f32_e32 v27, v27, v36
	v_cndmask_b32_e32 v27, v35, v27, vcc
	s_waitcnt vmcnt(13)
	v_mul_f32_e32 v35, v13, v26
	v_readlane_b32 vcc_lo, v250, 21
	v_readlane_b32 vcc_hi, v250, 22
	s_nop 1
	v_add_f32_dpp v35, v35, v35 quad_perm:[1,0,3,2] row_mask:0xf bank_mask:0xf
	s_nop 1
	v_add_f32_dpp v26, v35, v35 quad_perm:[2,3,0,1] row_mask:0xf bank_mask:0xf
	s_nop 1
	v_add_f32_dpp v26, v26, v26 row_half_mirror row_mask:0xf bank_mask:0xf
	s_nop 1
	v_add_f32_dpp v26, v26, v26 row_mirror row_mask:0xf bank_mask:0xf
	v_mov_b32_e32 v35, v26
	s_nop 1
	v_permlane16_swap_b32_e32 v35, v26
	v_add_f32_e32 v26, v26, v35
	v_mov_b32_e32 v35, v26
	s_nop 1
	v_permlane32_swap_b32_e32 v35, v26
	v_add_f32_e32 v26, v26, v35
	v_cndmask_b32_e32 v26, v27, v26, vcc
	s_waitcnt vmcnt(12)
	v_mul_f32_e32 v27, v13, v25
	v_readlane_b32 vcc_lo, v250, 23
	v_readlane_b32 vcc_hi, v250, 24
	s_nop 1
	v_add_f32_dpp v27, v27, v27 quad_perm:[1,0,3,2] row_mask:0xf bank_mask:0xf
	s_nop 1
	v_add_f32_dpp v25, v27, v27 quad_perm:[2,3,0,1] row_mask:0xf bank_mask:0xf
	s_nop 1
	v_add_f32_dpp v25, v25, v25 row_half_mirror row_mask:0xf bank_mask:0xf
	s_nop 1
	v_add_f32_dpp v25, v25, v25 row_mirror row_mask:0xf bank_mask:0xf
	v_mov_b32_e32 v27, v25
	s_nop 1
	v_permlane16_swap_b32_e32 v27, v25
	v_add_f32_e32 v25, v25, v27
	v_mov_b32_e32 v27, v25
	s_nop 1
	v_permlane32_swap_b32_e32 v27, v25
	v_add_f32_e32 v25, v25, v27
	v_cndmask_b32_e32 v25, v26, v25, vcc
	s_waitcnt vmcnt(11)
	v_mul_f32_e32 v26, v13, v24
	v_readlane_b32 vcc_lo, v250, 25
	v_readlane_b32 vcc_hi, v250, 26
	s_nop 1
	v_add_f32_dpp v26, v26, v26 quad_perm:[1,0,3,2] row_mask:0xf bank_mask:0xf
	s_nop 1
	v_add_f32_dpp v24, v26, v26 quad_perm:[2,3,0,1] row_mask:0xf bank_mask:0xf
	s_nop 1
	v_add_f32_dpp v24, v24, v24 row_half_mirror row_mask:0xf bank_mask:0xf
	s_nop 1
	v_add_f32_dpp v24, v24, v24 row_mirror row_mask:0xf bank_mask:0xf
	v_mov_b32_e32 v26, v24
	s_nop 1
	v_permlane16_swap_b32_e32 v26, v24
	v_add_f32_e32 v24, v24, v26
	v_mov_b32_e32 v26, v24
	s_nop 1
	v_permlane32_swap_b32_e32 v26, v24
	v_add_f32_e32 v24, v24, v26
	v_cndmask_b32_e32 v24, v25, v24, vcc
	s_waitcnt vmcnt(10)
	v_mul_f32_e32 v25, v13, v23
	v_readlane_b32 vcc_lo, v250, 27
	v_readlane_b32 vcc_hi, v250, 28
	s_nop 1
	v_add_f32_dpp v25, v25, v25 quad_perm:[1,0,3,2] row_mask:0xf bank_mask:0xf
	s_nop 1
	v_add_f32_dpp v23, v25, v25 quad_perm:[2,3,0,1] row_mask:0xf bank_mask:0xf
	s_nop 1
	v_add_f32_dpp v23, v23, v23 row_half_mirror row_mask:0xf bank_mask:0xf
	s_nop 1
	v_add_f32_dpp v23, v23, v23 row_mirror row_mask:0xf bank_mask:0xf
	v_mov_b32_e32 v25, v23
	s_nop 1
	v_permlane16_swap_b32_e32 v25, v23
	v_add_f32_e32 v23, v23, v25
	v_mov_b32_e32 v25, v23
	s_nop 1
	v_permlane32_swap_b32_e32 v25, v23
	v_add_f32_e32 v23, v23, v25
	v_cndmask_b32_e32 v23, v24, v23, vcc
	s_waitcnt vmcnt(9)
	v_mul_f32_e32 v24, v13, v22
	v_readlane_b32 vcc_lo, v250, 29
	v_readlane_b32 vcc_hi, v250, 30
	s_nop 1
	v_add_f32_dpp v24, v24, v24 quad_perm:[1,0,3,2] row_mask:0xf bank_mask:0xf
	s_nop 1
	v_add_f32_dpp v22, v24, v24 quad_perm:[2,3,0,1] row_mask:0xf bank_mask:0xf
	s_nop 1
	v_add_f32_dpp v22, v22, v22 row_half_mirror row_mask:0xf bank_mask:0xf
	s_nop 1
	v_add_f32_dpp v22, v22, v22 row_mirror row_mask:0xf bank_mask:0xf
	v_mov_b32_e32 v24, v22
	s_nop 1
	v_permlane16_swap_b32_e32 v24, v22
	v_add_f32_e32 v22, v22, v24
	v_mov_b32_e32 v24, v22
	s_nop 1
	v_permlane32_swap_b32_e32 v24, v22
	v_add_f32_e32 v22, v22, v24
	v_cndmask_b32_e32 v22, v23, v22, vcc
	s_waitcnt vmcnt(8)
	v_mul_f32_e32 v23, v13, v21
	v_readlane_b32 vcc_lo, v250, 31
	v_readlane_b32 vcc_hi, v250, 32
	s_nop 1
	v_add_f32_dpp v23, v23, v23 quad_perm:[1,0,3,2] row_mask:0xf bank_mask:0xf
	s_nop 1
	v_add_f32_dpp v21, v23, v23 quad_perm:[2,3,0,1] row_mask:0xf bank_mask:0xf
	s_nop 1
	v_add_f32_dpp v21, v21, v21 row_half_mirror row_mask:0xf bank_mask:0xf
	s_nop 1
	v_add_f32_dpp v21, v21, v21 row_mirror row_mask:0xf bank_mask:0xf
	v_mov_b32_e32 v23, v21
	s_nop 1
	v_permlane16_swap_b32_e32 v23, v21
	v_add_f32_e32 v21, v21, v23
	v_mov_b32_e32 v23, v21
	s_nop 1
	v_permlane32_swap_b32_e32 v23, v21
	v_add_f32_e32 v21, v21, v23
	v_cndmask_b32_e32 v21, v22, v21, vcc
	s_waitcnt vmcnt(7)
	v_mul_f32_e32 v22, v13, v20
	v_readlane_b32 vcc_lo, v250, 33
	v_readlane_b32 vcc_hi, v250, 34
	s_nop 1
	v_add_f32_dpp v22, v22, v22 quad_perm:[1,0,3,2] row_mask:0xf bank_mask:0xf
	s_nop 1
	v_add_f32_dpp v20, v22, v22 quad_perm:[2,3,0,1] row_mask:0xf bank_mask:0xf
	s_nop 1
	v_add_f32_dpp v20, v20, v20 row_half_mirror row_mask:0xf bank_mask:0xf
	s_nop 1
	v_add_f32_dpp v20, v20, v20 row_mirror row_mask:0xf bank_mask:0xf
	v_mov_b32_e32 v22, v20
	s_nop 1
	v_permlane16_swap_b32_e32 v22, v20
	v_add_f32_e32 v20, v20, v22
	v_mov_b32_e32 v22, v20
	s_nop 1
	v_permlane32_swap_b32_e32 v22, v20
	v_add_f32_e32 v20, v20, v22
	v_cndmask_b32_e32 v20, v21, v20, vcc
	s_waitcnt vmcnt(6)
	v_mul_f32_e32 v21, v13, v19
	v_readlane_b32 vcc_lo, v250, 35
	v_readlane_b32 vcc_hi, v250, 36
	s_nop 1
	v_add_f32_dpp v21, v21, v21 quad_perm:[1,0,3,2] row_mask:0xf bank_mask:0xf
	s_nop 1
	v_add_f32_dpp v19, v21, v21 quad_perm:[2,3,0,1] row_mask:0xf bank_mask:0xf
	s_nop 1
	v_add_f32_dpp v19, v19, v19 row_half_mirror row_mask:0xf bank_mask:0xf
	s_nop 1
	v_add_f32_dpp v19, v19, v19 row_mirror row_mask:0xf bank_mask:0xf
	v_mov_b32_e32 v21, v19
	s_nop 1
	v_permlane16_swap_b32_e32 v21, v19
	v_add_f32_e32 v19, v19, v21
	v_mov_b32_e32 v21, v19
	s_nop 1
	v_permlane32_swap_b32_e32 v21, v19
	v_add_f32_e32 v19, v19, v21
	v_cndmask_b32_e32 v19, v20, v19, vcc
	s_waitcnt vmcnt(5)
	v_mul_f32_e32 v20, v13, v18
	v_readlane_b32 vcc_lo, v250, 37
	v_readlane_b32 vcc_hi, v250, 38
	s_nop 1
	v_add_f32_dpp v20, v20, v20 quad_perm:[1,0,3,2] row_mask:0xf bank_mask:0xf
	s_nop 1
	v_add_f32_dpp v18, v20, v20 quad_perm:[2,3,0,1] row_mask:0xf bank_mask:0xf
	s_nop 1
	v_add_f32_dpp v18, v18, v18 row_half_mirror row_mask:0xf bank_mask:0xf
	s_nop 1
	v_add_f32_dpp v18, v18, v18 row_mirror row_mask:0xf bank_mask:0xf
	v_mov_b32_e32 v20, v18
	s_nop 1
	v_permlane16_swap_b32_e32 v20, v18
	v_add_f32_e32 v18, v18, v20
	v_mov_b32_e32 v20, v18
	s_nop 1
	v_permlane32_swap_b32_e32 v20, v18
	v_add_f32_e32 v18, v18, v20
	v_cndmask_b32_e32 v18, v19, v18, vcc
	s_waitcnt vmcnt(4)
	v_mul_f32_e32 v19, v13, v17
	v_readlane_b32 vcc_lo, v250, 39
	v_readlane_b32 vcc_hi, v250, 40
	s_nop 1
	v_add_f32_dpp v19, v19, v19 quad_perm:[1,0,3,2] row_mask:0xf bank_mask:0xf
	s_nop 1
	v_add_f32_dpp v17, v19, v19 quad_perm:[2,3,0,1] row_mask:0xf bank_mask:0xf
	s_nop 1
	v_add_f32_dpp v17, v17, v17 row_half_mirror row_mask:0xf bank_mask:0xf
	s_nop 1
	v_add_f32_dpp v17, v17, v17 row_mirror row_mask:0xf bank_mask:0xf
	v_mov_b32_e32 v19, v17
	s_nop 1
	v_permlane16_swap_b32_e32 v19, v17
	v_add_f32_e32 v17, v17, v19
	v_mov_b32_e32 v19, v17
	s_nop 1
	v_permlane32_swap_b32_e32 v19, v17
	v_add_f32_e32 v17, v17, v19
	v_cndmask_b32_e32 v17, v18, v17, vcc
	s_waitcnt vmcnt(3)
	v_mul_f32_e32 v18, v13, v16
	v_readlane_b32 vcc_lo, v250, 41
	v_readlane_b32 vcc_hi, v250, 42
	s_nop 1
	v_add_f32_dpp v18, v18, v18 quad_perm:[1,0,3,2] row_mask:0xf bank_mask:0xf
	s_nop 1
	v_add_f32_dpp v16, v18, v18 quad_perm:[2,3,0,1] row_mask:0xf bank_mask:0xf
	s_nop 1
	v_add_f32_dpp v16, v16, v16 row_half_mirror row_mask:0xf bank_mask:0xf
	s_nop 1
	v_add_f32_dpp v16, v16, v16 row_mirror row_mask:0xf bank_mask:0xf
	v_mov_b32_e32 v18, v16
	s_nop 1
	v_permlane16_swap_b32_e32 v18, v16
	v_add_f32_e32 v16, v16, v18
	v_mov_b32_e32 v18, v16
	s_nop 1
	v_permlane32_swap_b32_e32 v18, v16
	v_add_f32_e32 v16, v16, v18
	v_cndmask_b32_e32 v16, v17, v16, vcc
	s_waitcnt vmcnt(2)
	v_mul_f32_e32 v17, v13, v15
	v_readlane_b32 vcc_lo, v250, 43
	v_readlane_b32 vcc_hi, v250, 44
	s_nop 1
	v_add_f32_dpp v17, v17, v17 quad_perm:[1,0,3,2] row_mask:0xf bank_mask:0xf
	s_nop 1
	v_add_f32_dpp v15, v17, v17 quad_perm:[2,3,0,1] row_mask:0xf bank_mask:0xf
	s_nop 1
	v_add_f32_dpp v15, v15, v15 row_half_mirror row_mask:0xf bank_mask:0xf
	s_nop 1
	v_add_f32_dpp v15, v15, v15 row_mirror row_mask:0xf bank_mask:0xf
	v_mov_b32_e32 v17, v15
	s_nop 1
	v_permlane16_swap_b32_e32 v17, v15
	v_add_f32_e32 v15, v15, v17
	v_mov_b32_e32 v17, v15
	s_nop 1
	v_permlane32_swap_b32_e32 v17, v15
	v_add_f32_e32 v15, v15, v17
	v_cndmask_b32_e32 v15, v16, v15, vcc
	s_mov_b32 vcc_lo, 0x21000
	v_add_co_u32_e32 v10, vcc, vcc_lo, v8
	s_nop 1
	v_addc_co_u32_e32 v11, vcc, 0, v9, vcc
	s_mov_b32 vcc_lo, 0x22000
	s_nop 0
	v_add_co_u32_e32 v16, vcc, vcc_lo, v8
	s_nop 1
	v_addc_co_u32_e32 v17, vcc, 0, v9, vcc
	s_mov_b32 vcc_lo, 0x23000
	global_load_dword v60, v[16:17], off offset:-4096
	global_load_dword v61, v[10:11], off offset:2048
	global_load_dword v62, v[16:17], off
	global_load_dword v63, v[16:17], off offset:2048
	v_add_co_u32_e32 v10, vcc, vcc_lo, v8
	s_nop 1
	v_addc_co_u32_e32 v11, vcc, 0, v9, vcc
	s_mov_b32 vcc_lo, 0x24000
	s_nop 0
	v_add_co_u32_e32 v16, vcc, vcc_lo, v8
	s_nop 1
	v_addc_co_u32_e32 v17, vcc, 0, v9, vcc
	s_mov_b32 vcc_lo, 0x25000
	global_load_dword v64, v[16:17], off offset:-4096
	global_load_dword v65, v[10:11], off offset:2048
	global_load_dword v66, v[16:17], off
	global_load_dword v67, v[16:17], off offset:2048
	v_add_co_u32_e32 v10, vcc, vcc_lo, v8
	s_nop 1
	v_addc_co_u32_e32 v11, vcc, 0, v9, vcc
	s_mov_b32 vcc_lo, 0x26000
	s_nop 0
	v_add_co_u32_e32 v16, vcc, vcc_lo, v8
	s_nop 1
	v_addc_co_u32_e32 v17, vcc, 0, v9, vcc
	s_mov_b32 vcc_lo, 0x27000
	global_load_dword v68, v[16:17], off offset:-4096
	global_load_dword v69, v[10:11], off offset:2048
	global_load_dword v70, v[16:17], off
	global_load_dword v71, v[16:17], off offset:2048
	v_add_co_u32_e32 v10, vcc, vcc_lo, v8
	s_nop 1
	v_addc_co_u32_e32 v11, vcc, 0, v9, vcc
	s_mov_b32 vcc_lo, 0x28000
	s_nop 0
	v_add_co_u32_e32 v16, vcc, vcc_lo, v8
	s_nop 1
	v_addc_co_u32_e32 v17, vcc, 0, v9, vcc
	s_mov_b32 vcc_lo, 0x29000
	global_load_dword v72, v[16:17], off offset:-4096
	global_load_dword v73, v[10:11], off offset:2048
	global_load_dword v74, v[16:17], off
	global_load_dword v75, v[16:17], off offset:2048
	v_add_co_u32_e32 v10, vcc, vcc_lo, v8
	s_nop 1
	v_addc_co_u32_e32 v11, vcc, 0, v9, vcc
	s_mov_b32 vcc_lo, 0x2a000
	s_nop 0
	v_add_co_u32_e32 v16, vcc, vcc_lo, v8
	s_nop 1
	v_addc_co_u32_e32 v17, vcc, 0, v9, vcc
	s_mov_b32 vcc_lo, 0x2b000
	global_load_dword v76, v[16:17], off offset:-4096
	global_load_dword v77, v[10:11], off offset:2048
	global_load_dword v78, v[16:17], off
	global_load_dword v79, v[16:17], off offset:2048
	v_add_co_u32_e32 v10, vcc, vcc_lo, v8
	s_nop 1
	v_addc_co_u32_e32 v11, vcc, 0, v9, vcc
	s_mov_b32 vcc_lo, 0x2c000
	s_nop 0
	v_add_co_u32_e32 v16, vcc, vcc_lo, v8
	s_nop 1
	v_addc_co_u32_e32 v17, vcc, 0, v9, vcc
	s_mov_b32 vcc_lo, 0x2d000
	global_load_dword v80, v[16:17], off offset:-4096
	global_load_dword v81, v[10:11], off offset:2048
	global_load_dword v82, v[16:17], off
	global_load_dword v83, v[16:17], off offset:2048
	v_add_co_u32_e32 v10, vcc, vcc_lo, v8
	s_nop 1
	v_addc_co_u32_e32 v11, vcc, 0, v9, vcc
	s_mov_b32 vcc_lo, 0x2e000
	s_nop 0
	v_add_co_u32_e32 v16, vcc, vcc_lo, v8
	s_nop 1
	v_addc_co_u32_e32 v17, vcc, 0, v9, vcc
	s_mov_b32 vcc_lo, 0x2f000
	global_load_dword v84, v[16:17], off offset:-4096
	global_load_dword v55, v[10:11], off offset:2048
	global_load_dword v54, v[16:17], off
	global_load_dword v53, v[16:17], off offset:2048
	v_add_co_u32_e32 v10, vcc, vcc_lo, v8
	s_nop 1
	v_addc_co_u32_e32 v11, vcc, 0, v9, vcc
	s_mov_b32 vcc_lo, 0x30000
	s_nop 0
	v_add_co_u32_e32 v16, vcc, vcc_lo, v8
	s_nop 1
	v_addc_co_u32_e32 v17, vcc, 0, v9, vcc
	s_mov_b32 vcc_lo, 0x31000
	global_load_dword v52, v[16:17], off offset:-4096
	global_load_dword v51, v[10:11], off offset:2048
	global_load_dword v50, v[16:17], off
	global_load_dword v49, v[16:17], off offset:2048
	v_add_co_u32_e32 v10, vcc, vcc_lo, v8
	s_nop 1
	v_addc_co_u32_e32 v11, vcc, 0, v9, vcc
	s_mov_b32 vcc_lo, 0x32000
	s_nop 0
	v_add_co_u32_e32 v16, vcc, vcc_lo, v8
	s_nop 1
	v_addc_co_u32_e32 v17, vcc, 0, v9, vcc
	s_mov_b32 vcc_lo, 0x33000
	global_load_dword v48, v[16:17], off offset:-4096
	global_load_dword v47, v[10:11], off offset:2048
	global_load_dword v46, v[16:17], off
	global_load_dword v45, v[16:17], off offset:2048
	v_add_co_u32_e32 v10, vcc, vcc_lo, v8
	s_nop 1
	v_addc_co_u32_e32 v11, vcc, 0, v9, vcc
	s_mov_b32 vcc_lo, 0x34000
	s_nop 0
	v_add_co_u32_e32 v16, vcc, vcc_lo, v8
	s_nop 1
	v_addc_co_u32_e32 v17, vcc, 0, v9, vcc
	s_mov_b32 vcc_lo, 0x35000
	global_load_dword v44, v[16:17], off offset:-4096
	global_load_dword v43, v[10:11], off offset:2048
	global_load_dword v42, v[16:17], off
	global_load_dword v41, v[16:17], off offset:2048
	v_add_co_u32_e32 v10, vcc, vcc_lo, v8
	s_nop 1
	v_addc_co_u32_e32 v11, vcc, 0, v9, vcc
	s_mov_b32 vcc_lo, 0x36000
	s_nop 0
	v_add_co_u32_e32 v16, vcc, vcc_lo, v8
	s_nop 1
	v_addc_co_u32_e32 v17, vcc, 0, v9, vcc
	s_mov_b32 vcc_lo, 0x37000
	global_load_dword v40, v[16:17], off offset:-4096
	global_load_dword v39, v[10:11], off offset:2048
	global_load_dword v38, v[16:17], off
	global_load_dword v37, v[16:17], off offset:2048
	v_add_co_u32_e32 v10, vcc, vcc_lo, v8
	s_nop 1
	v_addc_co_u32_e32 v11, vcc, 0, v9, vcc
	s_mov_b32 vcc_lo, 0x38000
	s_nop 0
	v_add_co_u32_e32 v16, vcc, vcc_lo, v8
	s_nop 1
	v_addc_co_u32_e32 v17, vcc, 0, v9, vcc
	s_mov_b32 vcc_lo, 0x39000
	global_load_dword v36, v[16:17], off offset:-4096
	global_load_dword v35, v[10:11], off offset:2048
	global_load_dword v27, v[16:17], off
	global_load_dword v26, v[16:17], off offset:2048
	v_add_co_u32_e32 v10, vcc, vcc_lo, v8
	s_nop 1
	v_addc_co_u32_e32 v11, vcc, 0, v9, vcc
	s_mov_b32 vcc_lo, 0x3a000
	s_nop 0
	v_add_co_u32_e32 v16, vcc, vcc_lo, v8
	s_nop 1
	v_addc_co_u32_e32 v17, vcc, 0, v9, vcc
	s_mov_b32 vcc_lo, 0x3b000
	global_load_dword v25, v[16:17], off offset:-4096
	global_load_dword v24, v[10:11], off offset:2048
	global_load_dword v23, v[16:17], off
	global_load_dword v22, v[16:17], off offset:2048
	v_add_co_u32_e32 v10, vcc, vcc_lo, v8
	s_nop 1
	v_addc_co_u32_e32 v11, vcc, 0, v9, vcc
	s_mov_b32 vcc_lo, 0x3c000
	s_nop 0
	v_add_co_u32_e32 v16, vcc, vcc_lo, v8
	s_nop 1
	v_addc_co_u32_e32 v17, vcc, 0, v9, vcc
	s_mov_b32 vcc_lo, 0x3d000
	global_load_dword v21, v[16:17], off offset:-4096
	global_load_dword v20, v[10:11], off offset:2048
	global_load_dword v19, v[16:17], off
	global_load_dword v18, v[16:17], off offset:2048
	v_add_co_u32_e32 v10, vcc, vcc_lo, v8
	s_nop 1
	v_addc_co_u32_e32 v11, vcc, 0, v9, vcc
	s_mov_b32 vcc_lo, 0x3e000
	s_nop 0
	v_add_co_u32_e32 v56, vcc, vcc_lo, v8
	s_nop 1
	v_addc_co_u32_e32 v57, vcc, 0, v9, vcc
	s_mov_b32 vcc_lo, 0x3f000
	global_load_dword v17, v[56:57], off offset:-4096
	global_load_dword v16, v[10:11], off offset:2048
	s_nop 0
	global_load_dword v11, v[56:57], off
	global_load_dword v10, v[56:57], off offset:2048
	v_add_co_u32_e32 v56, vcc, vcc_lo, v8
	s_nop 1
	v_addc_co_u32_e32 v57, vcc, 0, v9, vcc
	global_load_dword v9, v[56:57], off
	global_load_dword v8, v[56:57], off offset:2048
	s_waitcnt vmcnt(62)
	v_mul_f32_e32 v56, v13, v58
	s_nop 1
	v_add_f32_dpp v56, v56, v56 quad_perm:[1,0,3,2] row_mask:0xf bank_mask:0xf
	s_nop 1
	v_add_f32_dpp v56, v56, v56 quad_perm:[2,3,0,1] row_mask:0xf bank_mask:0xf
	s_nop 1
	v_add_f32_dpp v56, v56, v56 row_half_mirror row_mask:0xf bank_mask:0xf
	s_nop 1
	v_add_f32_dpp v56, v56, v56 row_mirror row_mask:0xf bank_mask:0xf
	v_mov_b32_e32 v57, v56
	s_nop 1
	v_permlane16_swap_b32_e32 v57, v56
	v_add_f32_e32 v56, v56, v57
	v_mov_b32_e32 v57, v56
	s_nop 1
	v_permlane32_swap_b32_e32 v57, v56
	v_add_f32_e32 v56, v56, v57
	v_mul_f32_e32 v57, v13, v59
	v_cndmask_b32_e64 v56, 0, v56, s[54:55]
	s_nop 1
	v_add_f32_dpp v57, v57, v57 quad_perm:[1,0,3,2] row_mask:0xf bank_mask:0xf
	s_nop 1
	v_add_f32_dpp v57, v57, v57 quad_perm:[2,3,0,1] row_mask:0xf bank_mask:0xf
	s_nop 1
	v_add_f32_dpp v57, v57, v57 row_half_mirror row_mask:0xf bank_mask:0xf
	s_nop 1
	v_add_f32_dpp v57, v57, v57 row_mirror row_mask:0xf bank_mask:0xf
	v_mov_b32_e32 v58, v57
	s_nop 1
	v_permlane16_swap_b32_e32 v58, v57
	v_add_f32_e32 v57, v57, v58
	v_mov_b32_e32 v58, v57
	s_nop 1
	v_permlane32_swap_b32_e32 v58, v57
	v_add_f32_e32 v57, v57, v58
	v_cndmask_b32_e64 v56, v56, v57, s[56:57]
	s_waitcnt vmcnt(61)
	v_mul_f32_e32 v57, v13, v60
	s_nop 1
	v_add_f32_dpp v57, v57, v57 quad_perm:[1,0,3,2] row_mask:0xf bank_mask:0xf
	s_nop 1
	v_add_f32_dpp v57, v57, v57 quad_perm:[2,3,0,1] row_mask:0xf bank_mask:0xf
	s_nop 1
	v_add_f32_dpp v57, v57, v57 row_half_mirror row_mask:0xf bank_mask:0xf
	s_nop 1
	v_add_f32_dpp v57, v57, v57 row_mirror row_mask:0xf bank_mask:0xf
	v_mov_b32_e32 v58, v57
	s_nop 1
	v_permlane16_swap_b32_e32 v58, v57
	v_add_f32_e32 v57, v57, v58
	v_mov_b32_e32 v58, v57
	s_nop 1
	v_permlane32_swap_b32_e32 v58, v57
	v_add_f32_e32 v57, v57, v58
	v_cndmask_b32_e64 v56, v56, v57, s[58:59]
	s_waitcnt vmcnt(60)
	v_mul_f32_e32 v57, v13, v61
	s_nop 1
	v_add_f32_dpp v57, v57, v57 quad_perm:[1,0,3,2] row_mask:0xf bank_mask:0xf
	s_nop 1
	v_add_f32_dpp v57, v57, v57 quad_perm:[2,3,0,1] row_mask:0xf bank_mask:0xf
	s_nop 1
	v_add_f32_dpp v57, v57, v57 row_half_mirror row_mask:0xf bank_mask:0xf
	s_nop 1
	v_add_f32_dpp v57, v57, v57 row_mirror row_mask:0xf bank_mask:0xf
	v_mov_b32_e32 v58, v57
	s_nop 1
	v_permlane16_swap_b32_e32 v58, v57
	v_add_f32_e32 v57, v57, v58
	v_mov_b32_e32 v58, v57
	s_nop 1
	v_permlane32_swap_b32_e32 v58, v57
	v_add_f32_e32 v57, v57, v58
	v_cndmask_b32_e64 v56, v56, v57, s[60:61]
	s_waitcnt vmcnt(59)
	v_mul_f32_e32 v57, v13, v62
	s_nop 1
	v_add_f32_dpp v57, v57, v57 quad_perm:[1,0,3,2] row_mask:0xf bank_mask:0xf
	s_nop 1
	v_add_f32_dpp v57, v57, v57 quad_perm:[2,3,0,1] row_mask:0xf bank_mask:0xf
	s_nop 1
	v_add_f32_dpp v57, v57, v57 row_half_mirror row_mask:0xf bank_mask:0xf
	s_nop 1
	v_add_f32_dpp v57, v57, v57 row_mirror row_mask:0xf bank_mask:0xf
	v_mov_b32_e32 v58, v57
	s_nop 1
	v_permlane16_swap_b32_e32 v58, v57
	v_add_f32_e32 v57, v57, v58
	v_mov_b32_e32 v58, v57
	s_nop 1
	v_permlane32_swap_b32_e32 v58, v57
	v_add_f32_e32 v57, v57, v58
	v_cndmask_b32_e64 v56, v56, v57, s[62:63]
	s_waitcnt vmcnt(58)
	v_mul_f32_e32 v57, v13, v63
	s_nop 1
	v_add_f32_dpp v57, v57, v57 quad_perm:[1,0,3,2] row_mask:0xf bank_mask:0xf
	s_nop 1
	v_add_f32_dpp v57, v57, v57 quad_perm:[2,3,0,1] row_mask:0xf bank_mask:0xf
	s_nop 1
	v_add_f32_dpp v57, v57, v57 row_half_mirror row_mask:0xf bank_mask:0xf
	s_nop 1
	v_add_f32_dpp v57, v57, v57 row_mirror row_mask:0xf bank_mask:0xf
	v_mov_b32_e32 v58, v57
	s_nop 1
	v_permlane16_swap_b32_e32 v58, v57
	v_add_f32_e32 v57, v57, v58
	v_mov_b32_e32 v58, v57
	s_nop 1
	v_permlane32_swap_b32_e32 v58, v57
	v_add_f32_e32 v57, v57, v58
	v_cndmask_b32_e64 v56, v56, v57, s[52:53]
	s_waitcnt vmcnt(57)
	v_mul_f32_e32 v57, v13, v64
	s_nop 1
	v_add_f32_dpp v57, v57, v57 quad_perm:[1,0,3,2] row_mask:0xf bank_mask:0xf
	s_nop 1
	v_add_f32_dpp v57, v57, v57 quad_perm:[2,3,0,1] row_mask:0xf bank_mask:0xf
	s_nop 1
	v_add_f32_dpp v57, v57, v57 row_half_mirror row_mask:0xf bank_mask:0xf
	s_nop 1
	v_add_f32_dpp v57, v57, v57 row_mirror row_mask:0xf bank_mask:0xf
	v_mov_b32_e32 v58, v57
	s_nop 1
	v_permlane16_swap_b32_e32 v58, v57
	v_add_f32_e32 v57, v57, v58
	v_mov_b32_e32 v58, v57
	s_nop 1
	v_permlane32_swap_b32_e32 v58, v57
	v_add_f32_e32 v57, v57, v58
	v_cndmask_b32_e64 v56, v56, v57, s[66:67]
	s_waitcnt vmcnt(56)
	v_mul_f32_e32 v57, v13, v65
	s_nop 1
	v_add_f32_dpp v57, v57, v57 quad_perm:[1,0,3,2] row_mask:0xf bank_mask:0xf
	s_nop 1
	v_add_f32_dpp v57, v57, v57 quad_perm:[2,3,0,1] row_mask:0xf bank_mask:0xf
	s_nop 1
	v_add_f32_dpp v57, v57, v57 row_half_mirror row_mask:0xf bank_mask:0xf
	s_nop 1
	v_add_f32_dpp v57, v57, v57 row_mirror row_mask:0xf bank_mask:0xf
	v_mov_b32_e32 v58, v57
	s_nop 1
	v_permlane16_swap_b32_e32 v58, v57
	v_add_f32_e32 v57, v57, v58
	v_mov_b32_e32 v58, v57
	s_nop 1
	v_permlane32_swap_b32_e32 v58, v57
	v_add_f32_e32 v57, v57, v58
	v_cndmask_b32_e64 v56, v56, v57, s[68:69]
	s_waitcnt vmcnt(55)
	v_mul_f32_e32 v57, v13, v66
	s_nop 1
	v_add_f32_dpp v57, v57, v57 quad_perm:[1,0,3,2] row_mask:0xf bank_mask:0xf
	s_nop 1
	v_add_f32_dpp v57, v57, v57 quad_perm:[2,3,0,1] row_mask:0xf bank_mask:0xf
	s_nop 1
	v_add_f32_dpp v57, v57, v57 row_half_mirror row_mask:0xf bank_mask:0xf
	s_nop 1
	v_add_f32_dpp v57, v57, v57 row_mirror row_mask:0xf bank_mask:0xf
	v_mov_b32_e32 v58, v57
	s_nop 1
	v_permlane16_swap_b32_e32 v58, v57
	v_add_f32_e32 v57, v57, v58
	v_mov_b32_e32 v58, v57
	s_nop 1
	v_permlane32_swap_b32_e32 v58, v57
	v_add_f32_e32 v57, v57, v58
	v_cndmask_b32_e64 v56, v56, v57, s[70:71]
	s_waitcnt vmcnt(54)
	v_mul_f32_e32 v57, v13, v67
	s_nop 1
	v_add_f32_dpp v57, v57, v57 quad_perm:[1,0,3,2] row_mask:0xf bank_mask:0xf
	s_nop 1
	v_add_f32_dpp v57, v57, v57 quad_perm:[2,3,0,1] row_mask:0xf bank_mask:0xf
	s_nop 1
	v_add_f32_dpp v57, v57, v57 row_half_mirror row_mask:0xf bank_mask:0xf
	s_nop 1
	v_add_f32_dpp v57, v57, v57 row_mirror row_mask:0xf bank_mask:0xf
	v_mov_b32_e32 v58, v57
	s_nop 1
	v_permlane16_swap_b32_e32 v58, v57
	v_add_f32_e32 v57, v57, v58
	v_mov_b32_e32 v58, v57
	s_nop 1
	v_permlane32_swap_b32_e32 v58, v57
	v_add_f32_e32 v57, v57, v58
	v_cndmask_b32_e64 v56, v56, v57, s[72:73]
	s_waitcnt vmcnt(53)
	v_mul_f32_e32 v57, v13, v68
	s_nop 1
	v_add_f32_dpp v57, v57, v57 quad_perm:[1,0,3,2] row_mask:0xf bank_mask:0xf
	s_nop 1
	v_add_f32_dpp v57, v57, v57 quad_perm:[2,3,0,1] row_mask:0xf bank_mask:0xf
	s_nop 1
	v_add_f32_dpp v57, v57, v57 row_half_mirror row_mask:0xf bank_mask:0xf
	s_nop 1
	v_add_f32_dpp v57, v57, v57 row_mirror row_mask:0xf bank_mask:0xf
	v_mov_b32_e32 v58, v57
	s_nop 1
	v_permlane16_swap_b32_e32 v58, v57
	v_add_f32_e32 v57, v57, v58
	v_mov_b32_e32 v58, v57
	s_nop 1
	v_permlane32_swap_b32_e32 v58, v57
	v_add_f32_e32 v57, v57, v58
	v_cndmask_b32_e64 v56, v56, v57, s[74:75]
	s_waitcnt vmcnt(52)
	v_mul_f32_e32 v57, v13, v69
	s_nop 1
	v_add_f32_dpp v57, v57, v57 quad_perm:[1,0,3,2] row_mask:0xf bank_mask:0xf
	s_nop 1
	v_add_f32_dpp v57, v57, v57 quad_perm:[2,3,0,1] row_mask:0xf bank_mask:0xf
	s_nop 1
	v_add_f32_dpp v57, v57, v57 row_half_mirror row_mask:0xf bank_mask:0xf
	s_nop 1
	v_add_f32_dpp v57, v57, v57 row_mirror row_mask:0xf bank_mask:0xf
	v_mov_b32_e32 v58, v57
	s_nop 1
	v_permlane16_swap_b32_e32 v58, v57
	v_add_f32_e32 v57, v57, v58
	v_mov_b32_e32 v58, v57
	s_nop 1
	v_permlane32_swap_b32_e32 v58, v57
	v_add_f32_e32 v57, v57, v58
	v_cndmask_b32_e64 v56, v56, v57, s[44:45]
	s_waitcnt vmcnt(51)
	v_mul_f32_e32 v57, v13, v70
	v_readlane_b32 s44, v250, 47
	v_readlane_b32 s45, v250, 48
	s_nop 1
	v_add_f32_dpp v57, v57, v57 quad_perm:[1,0,3,2] row_mask:0xf bank_mask:0xf
	s_nop 1
	v_add_f32_dpp v57, v57, v57 quad_perm:[2,3,0,1] row_mask:0xf bank_mask:0xf
	s_nop 1
	v_add_f32_dpp v57, v57, v57 row_half_mirror row_mask:0xf bank_mask:0xf
	s_nop 1
	v_add_f32_dpp v57, v57, v57 row_mirror row_mask:0xf bank_mask:0xf
	v_mov_b32_e32 v58, v57
	s_nop 1
	v_permlane16_swap_b32_e32 v58, v57
	v_add_f32_e32 v57, v57, v58
	v_mov_b32_e32 v58, v57
	s_nop 1
	v_permlane32_swap_b32_e32 v58, v57
	v_add_f32_e32 v57, v57, v58
	v_cndmask_b32_e64 v56, v56, v57, s[46:47]
	s_waitcnt vmcnt(50)
	v_mul_f32_e32 v57, v13, v71
	s_nop 1
	v_add_f32_dpp v57, v57, v57 quad_perm:[1,0,3,2] row_mask:0xf bank_mask:0xf
	s_nop 1
	v_add_f32_dpp v57, v57, v57 quad_perm:[2,3,0,1] row_mask:0xf bank_mask:0xf
	s_nop 1
	v_add_f32_dpp v57, v57, v57 row_half_mirror row_mask:0xf bank_mask:0xf
	s_nop 1
	v_add_f32_dpp v57, v57, v57 row_mirror row_mask:0xf bank_mask:0xf
	v_mov_b32_e32 v58, v57
	s_nop 1
	v_permlane16_swap_b32_e32 v58, v57
	v_add_f32_e32 v57, v57, v58
	v_mov_b32_e32 v58, v57
	s_nop 1
	v_permlane32_swap_b32_e32 v58, v57
	v_add_f32_e32 v57, v57, v58
	v_cndmask_b32_e64 v56, v56, v57, s[96:97]
	s_waitcnt vmcnt(49)
	v_mul_f32_e32 v57, v13, v72
	s_nop 1
	v_add_f32_dpp v57, v57, v57 quad_perm:[1,0,3,2] row_mask:0xf bank_mask:0xf
	s_nop 1
	v_add_f32_dpp v57, v57, v57 quad_perm:[2,3,0,1] row_mask:0xf bank_mask:0xf
	s_nop 1
	v_add_f32_dpp v57, v57, v57 row_half_mirror row_mask:0xf bank_mask:0xf
	s_nop 1
	v_add_f32_dpp v57, v57, v57 row_mirror row_mask:0xf bank_mask:0xf
	v_mov_b32_e32 v58, v57
	s_nop 1
	v_permlane16_swap_b32_e32 v58, v57
	v_add_f32_e32 v57, v57, v58
	v_mov_b32_e32 v58, v57
	s_nop 1
	v_permlane32_swap_b32_e32 v58, v57
	v_add_f32_e32 v57, v57, v58
	v_cndmask_b32_e64 v56, v56, v57, s[94:95]
	s_waitcnt vmcnt(48)
	v_mul_f32_e32 v57, v13, v73
	s_nop 1
	v_add_f32_dpp v57, v57, v57 quad_perm:[1,0,3,2] row_mask:0xf bank_mask:0xf
	s_nop 1
	v_add_f32_dpp v57, v57, v57 quad_perm:[2,3,0,1] row_mask:0xf bank_mask:0xf
	s_nop 1
	v_add_f32_dpp v57, v57, v57 row_half_mirror row_mask:0xf bank_mask:0xf
	s_nop 1
	v_add_f32_dpp v57, v57, v57 row_mirror row_mask:0xf bank_mask:0xf
	v_mov_b32_e32 v58, v57
	s_nop 1
	v_permlane16_swap_b32_e32 v58, v57
	v_add_f32_e32 v57, v57, v58
	v_mov_b32_e32 v58, v57
	s_nop 1
	v_permlane32_swap_b32_e32 v58, v57
	v_add_f32_e32 v57, v57, v58
	v_cndmask_b32_e64 v56, v56, v57, s[92:93]
	s_waitcnt vmcnt(47)
	v_mul_f32_e32 v57, v13, v74
	s_nop 1
	v_add_f32_dpp v57, v57, v57 quad_perm:[1,0,3,2] row_mask:0xf bank_mask:0xf
	s_nop 1
	v_add_f32_dpp v57, v57, v57 quad_perm:[2,3,0,1] row_mask:0xf bank_mask:0xf
	s_nop 1
	v_add_f32_dpp v57, v57, v57 row_half_mirror row_mask:0xf bank_mask:0xf
	s_nop 1
	v_add_f32_dpp v57, v57, v57 row_mirror row_mask:0xf bank_mask:0xf
	v_mov_b32_e32 v58, v57
	s_nop 1
	v_permlane16_swap_b32_e32 v58, v57
	v_add_f32_e32 v57, v57, v58
	v_mov_b32_e32 v58, v57
	s_nop 1
	v_permlane32_swap_b32_e32 v58, v57
	v_add_f32_e32 v57, v57, v58
	v_cndmask_b32_e64 v56, v56, v57, s[90:91]
	s_waitcnt vmcnt(46)
	v_mul_f32_e32 v57, v13, v75
	s_nop 1
	v_add_f32_dpp v57, v57, v57 quad_perm:[1,0,3,2] row_mask:0xf bank_mask:0xf
	s_nop 1
	v_add_f32_dpp v57, v57, v57 quad_perm:[2,3,0,1] row_mask:0xf bank_mask:0xf
	s_nop 1
	v_add_f32_dpp v57, v57, v57 row_half_mirror row_mask:0xf bank_mask:0xf
	s_nop 1
	v_add_f32_dpp v57, v57, v57 row_mirror row_mask:0xf bank_mask:0xf
	v_mov_b32_e32 v58, v57
	s_nop 1
	v_permlane16_swap_b32_e32 v58, v57
	v_add_f32_e32 v57, v57, v58
	v_mov_b32_e32 v58, v57
	s_nop 1
	v_permlane32_swap_b32_e32 v58, v57
	v_add_f32_e32 v57, v57, v58
	v_cndmask_b32_e64 v56, v56, v57, s[88:89]
	s_waitcnt vmcnt(45)
	v_mul_f32_e32 v57, v13, v76
	s_nop 1
	v_add_f32_dpp v57, v57, v57 quad_perm:[1,0,3,2] row_mask:0xf bank_mask:0xf
	s_nop 1
	v_add_f32_dpp v57, v57, v57 quad_perm:[2,3,0,1] row_mask:0xf bank_mask:0xf
	s_nop 1
	v_add_f32_dpp v57, v57, v57 row_half_mirror row_mask:0xf bank_mask:0xf
	s_nop 1
	v_add_f32_dpp v57, v57, v57 row_mirror row_mask:0xf bank_mask:0xf
	v_mov_b32_e32 v58, v57
	s_nop 1
	v_permlane16_swap_b32_e32 v58, v57
	v_add_f32_e32 v57, v57, v58
	v_mov_b32_e32 v58, v57
	s_nop 1
	v_permlane32_swap_b32_e32 v58, v57
	v_add_f32_e32 v57, v57, v58
	v_cndmask_b32_e64 v56, v56, v57, s[84:85]
	s_waitcnt vmcnt(44)
	v_mul_f32_e32 v57, v13, v77
	s_nop 1
	v_add_f32_dpp v57, v57, v57 quad_perm:[1,0,3,2] row_mask:0xf bank_mask:0xf
	s_nop 1
	v_add_f32_dpp v57, v57, v57 quad_perm:[2,3,0,1] row_mask:0xf bank_mask:0xf
	s_nop 1
	v_add_f32_dpp v57, v57, v57 row_half_mirror row_mask:0xf bank_mask:0xf
	s_nop 1
	v_add_f32_dpp v57, v57, v57 row_mirror row_mask:0xf bank_mask:0xf
	v_mov_b32_e32 v58, v57
	s_nop 1
	v_permlane16_swap_b32_e32 v58, v57
	v_add_f32_e32 v57, v57, v58
	v_mov_b32_e32 v58, v57
	s_nop 1
	v_permlane32_swap_b32_e32 v58, v57
	v_add_f32_e32 v57, v57, v58
	v_cndmask_b32_e64 v56, v56, v57, s[82:83]
	s_waitcnt vmcnt(43)
	v_mul_f32_e32 v57, v13, v78
	s_nop 1
	v_add_f32_dpp v57, v57, v57 quad_perm:[1,0,3,2] row_mask:0xf bank_mask:0xf
	s_nop 1
	v_add_f32_dpp v57, v57, v57 quad_perm:[2,3,0,1] row_mask:0xf bank_mask:0xf
	s_nop 1
	v_add_f32_dpp v57, v57, v57 row_half_mirror row_mask:0xf bank_mask:0xf
	s_nop 1
	v_add_f32_dpp v57, v57, v57 row_mirror row_mask:0xf bank_mask:0xf
	v_mov_b32_e32 v58, v57
	s_nop 1
	v_permlane16_swap_b32_e32 v58, v57
	v_add_f32_e32 v57, v57, v58
	v_mov_b32_e32 v58, v57
	s_nop 1
	v_permlane32_swap_b32_e32 v58, v57
	v_add_f32_e32 v57, v57, v58
	v_cndmask_b32_e64 v56, v56, v57, s[80:81]
	s_waitcnt vmcnt(42)
	v_mul_f32_e32 v57, v13, v79
	s_nop 1
	v_add_f32_dpp v57, v57, v57 quad_perm:[1,0,3,2] row_mask:0xf bank_mask:0xf
	s_nop 1
	v_add_f32_dpp v57, v57, v57 quad_perm:[2,3,0,1] row_mask:0xf bank_mask:0xf
	s_nop 1
	v_add_f32_dpp v57, v57, v57 row_half_mirror row_mask:0xf bank_mask:0xf
	s_nop 1
	v_add_f32_dpp v57, v57, v57 row_mirror row_mask:0xf bank_mask:0xf
	v_mov_b32_e32 v58, v57
	s_nop 1
	v_permlane16_swap_b32_e32 v58, v57
	v_add_f32_e32 v57, v57, v58
	v_mov_b32_e32 v58, v57
	s_nop 1
	v_permlane32_swap_b32_e32 v58, v57
	v_add_f32_e32 v57, v57, v58
	v_cndmask_b32_e64 v56, v56, v57, s[76:77]
	s_waitcnt vmcnt(41)
	v_mul_f32_e32 v57, v13, v80
	s_nop 1
	v_add_f32_dpp v57, v57, v57 quad_perm:[1,0,3,2] row_mask:0xf bank_mask:0xf
	s_nop 1
	v_add_f32_dpp v57, v57, v57 quad_perm:[2,3,0,1] row_mask:0xf bank_mask:0xf
	s_nop 1
	v_add_f32_dpp v57, v57, v57 row_half_mirror row_mask:0xf bank_mask:0xf
	s_nop 1
	v_add_f32_dpp v57, v57, v57 row_mirror row_mask:0xf bank_mask:0xf
	v_mov_b32_e32 v58, v57
	s_nop 1
	v_permlane16_swap_b32_e32 v58, v57
	v_add_f32_e32 v57, v57, v58
	v_mov_b32_e32 v58, v57
	s_nop 1
	v_permlane32_swap_b32_e32 v58, v57
	v_add_f32_e32 v57, v57, v58
	v_cndmask_b32_e64 v56, v56, v57, s[0:1]
	s_waitcnt vmcnt(40)
	v_mul_f32_e32 v57, v13, v81
	v_readlane_b32 s0, v250, 13
	v_readlane_b32 s1, v250, 14
	s_nop 1
	v_add_f32_dpp v57, v57, v57 quad_perm:[1,0,3,2] row_mask:0xf bank_mask:0xf
	s_nop 1
	v_add_f32_dpp v57, v57, v57 quad_perm:[2,3,0,1] row_mask:0xf bank_mask:0xf
	s_nop 1
	v_add_f32_dpp v57, v57, v57 row_half_mirror row_mask:0xf bank_mask:0xf
	s_nop 1
	v_add_f32_dpp v57, v57, v57 row_mirror row_mask:0xf bank_mask:0xf
	v_mov_b32_e32 v58, v57
	s_nop 1
	v_permlane16_swap_b32_e32 v58, v57
	v_add_f32_e32 v57, v57, v58
	v_mov_b32_e32 v58, v57
	s_nop 1
	v_permlane32_swap_b32_e32 v58, v57
	v_add_f32_e32 v57, v57, v58
	v_cndmask_b32_e64 v56, v56, v57, s[2:3]
	s_waitcnt vmcnt(39)
	v_mul_f32_e32 v57, v13, v82
	v_readlane_b32 s2, v250, 50
	v_readlane_b32 s3, v250, 51
	s_nop 1
	v_add_f32_dpp v57, v57, v57 quad_perm:[1,0,3,2] row_mask:0xf bank_mask:0xf
	s_nop 1
	v_add_f32_dpp v57, v57, v57 quad_perm:[2,3,0,1] row_mask:0xf bank_mask:0xf
	s_nop 1
	v_add_f32_dpp v57, v57, v57 row_half_mirror row_mask:0xf bank_mask:0xf
	s_nop 1
	v_add_f32_dpp v57, v57, v57 row_mirror row_mask:0xf bank_mask:0xf
	v_mov_b32_e32 v58, v57
	s_nop 1
	v_permlane16_swap_b32_e32 v58, v57
	v_add_f32_e32 v57, v57, v58
	v_mov_b32_e32 v58, v57
	s_nop 1
	v_permlane32_swap_b32_e32 v58, v57
	v_add_f32_e32 v57, v57, v58
	v_cndmask_b32_e64 v56, v56, v57, s[4:5]
	s_waitcnt vmcnt(38)
	v_mul_f32_e32 v57, v13, v83
	v_readlane_b32 s4, v252, 8
	v_readlane_b32 s5, v252, 9
	s_nop 1
	v_add_f32_dpp v57, v57, v57 quad_perm:[1,0,3,2] row_mask:0xf bank_mask:0xf
	s_nop 1
	v_add_f32_dpp v57, v57, v57 quad_perm:[2,3,0,1] row_mask:0xf bank_mask:0xf
	s_nop 1
	v_add_f32_dpp v57, v57, v57 row_half_mirror row_mask:0xf bank_mask:0xf
	s_nop 1
	v_add_f32_dpp v57, v57, v57 row_mirror row_mask:0xf bank_mask:0xf
	v_mov_b32_e32 v58, v57
	s_nop 1
	v_permlane16_swap_b32_e32 v58, v57
	v_add_f32_e32 v57, v57, v58
	v_mov_b32_e32 v58, v57
	s_nop 1
	v_permlane32_swap_b32_e32 v58, v57
	v_add_f32_e32 v57, v57, v58
	v_cndmask_b32_e64 v56, v56, v57, s[6:7]
	s_waitcnt vmcnt(37)
	v_mul_f32_e32 v57, v13, v84
	s_nop 1
	v_add_f32_dpp v57, v57, v57 quad_perm:[1,0,3,2] row_mask:0xf bank_mask:0xf
	s_nop 1
	v_add_f32_dpp v57, v57, v57 quad_perm:[2,3,0,1] row_mask:0xf bank_mask:0xf
	s_nop 1
	v_add_f32_dpp v57, v57, v57 row_half_mirror row_mask:0xf bank_mask:0xf
	s_nop 1
	v_add_f32_dpp v57, v57, v57 row_mirror row_mask:0xf bank_mask:0xf
	v_mov_b32_e32 v58, v57
	s_nop 1
	v_permlane16_swap_b32_e32 v58, v57
	v_add_f32_e32 v57, v57, v58
	v_mov_b32_e32 v58, v57
	s_nop 1
	v_permlane32_swap_b32_e32 v58, v57
	v_add_f32_e32 v57, v57, v58
	v_cndmask_b32_e64 v56, v56, v57, s[8:9]
	s_waitcnt vmcnt(36)
	v_mul_f32_e32 v57, v13, v55
	s_nop 1
	v_add_f32_dpp v57, v57, v57 quad_perm:[1,0,3,2] row_mask:0xf bank_mask:0xf
	s_nop 1
	v_add_f32_dpp v55, v57, v57 quad_perm:[2,3,0,1] row_mask:0xf bank_mask:0xf
	s_nop 1
	v_add_f32_dpp v55, v55, v55 row_half_mirror row_mask:0xf bank_mask:0xf
	s_nop 1
	v_add_f32_dpp v55, v55, v55 row_mirror row_mask:0xf bank_mask:0xf
	v_mov_b32_e32 v57, v55
	s_nop 1
	v_permlane16_swap_b32_e32 v57, v55
	v_add_f32_e32 v55, v55, v57
	v_mov_b32_e32 v57, v55
	s_nop 1
	v_permlane32_swap_b32_e32 v57, v55
	v_add_f32_e32 v55, v55, v57
	v_cndmask_b32_e64 v55, v56, v55, s[10:11]
	s_waitcnt vmcnt(35)
	v_mul_f32_e32 v56, v13, v54
	s_nop 1
	v_add_f32_dpp v56, v56, v56 quad_perm:[1,0,3,2] row_mask:0xf bank_mask:0xf
	s_nop 1
	v_add_f32_dpp v54, v56, v56 quad_perm:[2,3,0,1] row_mask:0xf bank_mask:0xf
	s_nop 1
	v_add_f32_dpp v54, v54, v54 row_half_mirror row_mask:0xf bank_mask:0xf
	s_nop 1
	v_add_f32_dpp v54, v54, v54 row_mirror row_mask:0xf bank_mask:0xf
	v_mov_b32_e32 v56, v54
	s_nop 1
	v_permlane16_swap_b32_e32 v56, v54
	v_add_f32_e32 v54, v54, v56
	v_mov_b32_e32 v56, v54
	s_nop 1
	v_permlane32_swap_b32_e32 v56, v54
	v_add_f32_e32 v54, v54, v56
	v_cndmask_b32_e64 v54, v55, v54, s[12:13]
	s_waitcnt vmcnt(34)
	v_mul_f32_e32 v55, v13, v53
	s_nop 1
	v_add_f32_dpp v55, v55, v55 quad_perm:[1,0,3,2] row_mask:0xf bank_mask:0xf
	s_nop 1
	v_add_f32_dpp v53, v55, v55 quad_perm:[2,3,0,1] row_mask:0xf bank_mask:0xf
	s_nop 1
	v_add_f32_dpp v53, v53, v53 row_half_mirror row_mask:0xf bank_mask:0xf
	s_nop 1
	v_add_f32_dpp v53, v53, v53 row_mirror row_mask:0xf bank_mask:0xf
	v_mov_b32_e32 v55, v53
	s_nop 1
	v_permlane16_swap_b32_e32 v55, v53
	v_add_f32_e32 v53, v53, v55
	v_mov_b32_e32 v55, v53
	s_nop 1
	v_permlane32_swap_b32_e32 v55, v53
	v_add_f32_e32 v53, v53, v55
	v_cndmask_b32_e64 v53, v54, v53, s[14:15]
	s_waitcnt vmcnt(33)
	v_mul_f32_e32 v54, v13, v52
	s_nop 1
	v_add_f32_dpp v54, v54, v54 quad_perm:[1,0,3,2] row_mask:0xf bank_mask:0xf
	s_nop 1
	v_add_f32_dpp v52, v54, v54 quad_perm:[2,3,0,1] row_mask:0xf bank_mask:0xf
	s_nop 1
	v_add_f32_dpp v52, v52, v52 row_half_mirror row_mask:0xf bank_mask:0xf
	s_nop 1
	v_add_f32_dpp v52, v52, v52 row_mirror row_mask:0xf bank_mask:0xf
	v_mov_b32_e32 v54, v52
	s_nop 1
	v_permlane16_swap_b32_e32 v54, v52
	v_add_f32_e32 v52, v52, v54
	v_mov_b32_e32 v54, v52
	s_nop 1
	v_permlane32_swap_b32_e32 v54, v52
	v_add_f32_e32 v52, v52, v54
	v_cndmask_b32_e64 v52, v53, v52, s[16:17]
	s_waitcnt vmcnt(32)
	v_mul_f32_e32 v53, v13, v51
	s_nop 1
	v_add_f32_dpp v53, v53, v53 quad_perm:[1,0,3,2] row_mask:0xf bank_mask:0xf
	s_nop 1
	v_add_f32_dpp v51, v53, v53 quad_perm:[2,3,0,1] row_mask:0xf bank_mask:0xf
	s_nop 1
	v_add_f32_dpp v51, v51, v51 row_half_mirror row_mask:0xf bank_mask:0xf
	s_nop 1
	v_add_f32_dpp v51, v51, v51 row_mirror row_mask:0xf bank_mask:0xf
	v_mov_b32_e32 v53, v51
	s_nop 1
	v_permlane16_swap_b32_e32 v53, v51
	v_add_f32_e32 v51, v51, v53
	v_mov_b32_e32 v53, v51
	s_nop 1
	v_permlane32_swap_b32_e32 v53, v51
	v_add_f32_e32 v51, v51, v53
	v_cndmask_b32_e64 v51, v52, v51, s[18:19]
	s_waitcnt vmcnt(31)
	v_mul_f32_e32 v52, v13, v50
	s_nop 1
	v_add_f32_dpp v52, v52, v52 quad_perm:[1,0,3,2] row_mask:0xf bank_mask:0xf
	s_nop 1
	v_add_f32_dpp v50, v52, v52 quad_perm:[2,3,0,1] row_mask:0xf bank_mask:0xf
	s_nop 1
	v_add_f32_dpp v50, v50, v50 row_half_mirror row_mask:0xf bank_mask:0xf
	s_nop 1
	v_add_f32_dpp v50, v50, v50 row_mirror row_mask:0xf bank_mask:0xf
	v_mov_b32_e32 v52, v50
	s_nop 1
	v_permlane16_swap_b32_e32 v52, v50
	v_add_f32_e32 v50, v50, v52
	v_mov_b32_e32 v52, v50
	s_nop 1
	v_permlane32_swap_b32_e32 v52, v50
	v_add_f32_e32 v50, v50, v52
	v_cndmask_b32_e64 v50, v51, v50, s[20:21]
	s_waitcnt vmcnt(30)
	v_mul_f32_e32 v51, v13, v49
	s_nop 1
	v_add_f32_dpp v51, v51, v51 quad_perm:[1,0,3,2] row_mask:0xf bank_mask:0xf
	s_nop 1
	v_add_f32_dpp v49, v51, v51 quad_perm:[2,3,0,1] row_mask:0xf bank_mask:0xf
	s_nop 1
	v_add_f32_dpp v49, v49, v49 row_half_mirror row_mask:0xf bank_mask:0xf
	s_nop 1
	v_add_f32_dpp v49, v49, v49 row_mirror row_mask:0xf bank_mask:0xf
	v_mov_b32_e32 v51, v49
	s_nop 1
	v_permlane16_swap_b32_e32 v51, v49
	v_add_f32_e32 v49, v49, v51
	v_mov_b32_e32 v51, v49
	s_nop 1
	v_permlane32_swap_b32_e32 v51, v49
	v_add_f32_e32 v49, v49, v51
	v_cndmask_b32_e64 v49, v50, v49, s[22:23]
	s_waitcnt vmcnt(29)
	v_mul_f32_e32 v50, v13, v48
	s_nop 1
	v_add_f32_dpp v50, v50, v50 quad_perm:[1,0,3,2] row_mask:0xf bank_mask:0xf
	s_nop 1
	v_add_f32_dpp v48, v50, v50 quad_perm:[2,3,0,1] row_mask:0xf bank_mask:0xf
	s_nop 1
	v_add_f32_dpp v48, v48, v48 row_half_mirror row_mask:0xf bank_mask:0xf
	s_nop 1
	v_add_f32_dpp v48, v48, v48 row_mirror row_mask:0xf bank_mask:0xf
	v_mov_b32_e32 v50, v48
	s_nop 1
	v_permlane16_swap_b32_e32 v50, v48
	v_add_f32_e32 v48, v48, v50
	v_mov_b32_e32 v50, v48
	s_nop 1
	v_permlane32_swap_b32_e32 v50, v48
	v_add_f32_e32 v48, v48, v50
	v_cndmask_b32_e64 v48, v49, v48, s[24:25]
	s_waitcnt vmcnt(28)
	v_mul_f32_e32 v49, v13, v47
	s_nop 1
	v_add_f32_dpp v49, v49, v49 quad_perm:[1,0,3,2] row_mask:0xf bank_mask:0xf
	s_nop 1
	v_add_f32_dpp v47, v49, v49 quad_perm:[2,3,0,1] row_mask:0xf bank_mask:0xf
	s_nop 1
	v_add_f32_dpp v47, v47, v47 row_half_mirror row_mask:0xf bank_mask:0xf
	s_nop 1
	v_add_f32_dpp v47, v47, v47 row_mirror row_mask:0xf bank_mask:0xf
	v_mov_b32_e32 v49, v47
	s_nop 1
	v_permlane16_swap_b32_e32 v49, v47
	v_add_f32_e32 v47, v47, v49
	v_mov_b32_e32 v49, v47
	s_nop 1
	v_permlane32_swap_b32_e32 v49, v47
	v_add_f32_e32 v47, v47, v49
	v_cndmask_b32_e64 v47, v48, v47, s[26:27]
	s_waitcnt vmcnt(27)
	v_mul_f32_e32 v48, v13, v46
	s_nop 1
	v_add_f32_dpp v48, v48, v48 quad_perm:[1,0,3,2] row_mask:0xf bank_mask:0xf
	s_nop 1
	v_add_f32_dpp v46, v48, v48 quad_perm:[2,3,0,1] row_mask:0xf bank_mask:0xf
	s_nop 1
	v_add_f32_dpp v46, v46, v46 row_half_mirror row_mask:0xf bank_mask:0xf
	s_nop 1
	v_add_f32_dpp v46, v46, v46 row_mirror row_mask:0xf bank_mask:0xf
	v_mov_b32_e32 v48, v46
	s_nop 1
	v_permlane16_swap_b32_e32 v48, v46
	v_add_f32_e32 v46, v46, v48
	v_mov_b32_e32 v48, v46
	s_nop 1
	v_permlane32_swap_b32_e32 v48, v46
	v_add_f32_e32 v46, v46, v48
	v_cndmask_b32_e64 v46, v47, v46, s[28:29]
	s_waitcnt vmcnt(26)
	v_mul_f32_e32 v47, v13, v45
	s_nop 1
	v_add_f32_dpp v47, v47, v47 quad_perm:[1,0,3,2] row_mask:0xf bank_mask:0xf
	s_nop 1
	v_add_f32_dpp v45, v47, v47 quad_perm:[2,3,0,1] row_mask:0xf bank_mask:0xf
	s_nop 1
	v_add_f32_dpp v45, v45, v45 row_half_mirror row_mask:0xf bank_mask:0xf
	s_nop 1
	v_add_f32_dpp v45, v45, v45 row_mirror row_mask:0xf bank_mask:0xf
	v_mov_b32_e32 v47, v45
	s_nop 1
	v_permlane16_swap_b32_e32 v47, v45
	v_add_f32_e32 v45, v45, v47
	v_mov_b32_e32 v47, v45
	s_nop 1
	v_permlane32_swap_b32_e32 v47, v45
	v_add_f32_e32 v45, v45, v47
	v_cndmask_b32_e64 v45, v46, v45, s[30:31]
	s_waitcnt vmcnt(25)
	v_mul_f32_e32 v46, v13, v44
	s_nop 1
	v_add_f32_dpp v46, v46, v46 quad_perm:[1,0,3,2] row_mask:0xf bank_mask:0xf
	s_nop 1
	v_add_f32_dpp v44, v46, v46 quad_perm:[2,3,0,1] row_mask:0xf bank_mask:0xf
	s_nop 1
	v_add_f32_dpp v44, v44, v44 row_half_mirror row_mask:0xf bank_mask:0xf
	s_nop 1
	v_add_f32_dpp v44, v44, v44 row_mirror row_mask:0xf bank_mask:0xf
	v_mov_b32_e32 v46, v44
	s_nop 1
	v_permlane16_swap_b32_e32 v46, v44
	v_add_f32_e32 v44, v44, v46
	v_mov_b32_e32 v46, v44
	s_nop 1
	v_permlane32_swap_b32_e32 v46, v44
	v_add_f32_e32 v44, v44, v46
	v_cndmask_b32_e64 v44, v45, v44, s[34:35]
	s_waitcnt vmcnt(24)
	v_mul_f32_e32 v45, v13, v43
	s_nop 1
	v_add_f32_dpp v45, v45, v45 quad_perm:[1,0,3,2] row_mask:0xf bank_mask:0xf
	s_nop 1
	v_add_f32_dpp v43, v45, v45 quad_perm:[2,3,0,1] row_mask:0xf bank_mask:0xf
	s_nop 1
	v_add_f32_dpp v43, v43, v43 row_half_mirror row_mask:0xf bank_mask:0xf
	s_nop 1
	v_add_f32_dpp v43, v43, v43 row_mirror row_mask:0xf bank_mask:0xf
	v_mov_b32_e32 v45, v43
	s_nop 1
	v_permlane16_swap_b32_e32 v45, v43
	v_add_f32_e32 v43, v43, v45
	v_mov_b32_e32 v45, v43
	s_nop 1
	v_permlane32_swap_b32_e32 v45, v43
	v_add_f32_e32 v43, v43, v45
	v_cndmask_b32_e64 v43, v44, v43, s[36:37]
	s_waitcnt vmcnt(23)
	v_mul_f32_e32 v44, v13, v42
	s_nop 1
	v_add_f32_dpp v44, v44, v44 quad_perm:[1,0,3,2] row_mask:0xf bank_mask:0xf
	s_nop 1
	v_add_f32_dpp v42, v44, v44 quad_perm:[2,3,0,1] row_mask:0xf bank_mask:0xf
	s_nop 1
	v_add_f32_dpp v42, v42, v42 row_half_mirror row_mask:0xf bank_mask:0xf
	s_nop 1
	v_add_f32_dpp v42, v42, v42 row_mirror row_mask:0xf bank_mask:0xf
	v_mov_b32_e32 v44, v42
	s_nop 1
	v_permlane16_swap_b32_e32 v44, v42
	v_add_f32_e32 v42, v42, v44
	v_mov_b32_e32 v44, v42
	s_nop 1
	v_permlane32_swap_b32_e32 v44, v42
	v_add_f32_e32 v42, v42, v44
	v_cndmask_b32_e64 v42, v43, v42, s[38:39]
	s_waitcnt vmcnt(22)
	v_mul_f32_e32 v43, v13, v41
	s_nop 1
	v_add_f32_dpp v43, v43, v43 quad_perm:[1,0,3,2] row_mask:0xf bank_mask:0xf
	s_nop 1
	v_add_f32_dpp v41, v43, v43 quad_perm:[2,3,0,1] row_mask:0xf bank_mask:0xf
	s_nop 1
	v_add_f32_dpp v41, v41, v41 row_half_mirror row_mask:0xf bank_mask:0xf
	s_nop 1
	v_add_f32_dpp v41, v41, v41 row_mirror row_mask:0xf bank_mask:0xf
	v_mov_b32_e32 v43, v41
	s_nop 1
	v_permlane16_swap_b32_e32 v43, v41
	v_add_f32_e32 v41, v41, v43
	v_mov_b32_e32 v43, v41
	s_nop 1
	v_permlane32_swap_b32_e32 v43, v41
	v_add_f32_e32 v41, v41, v43
	v_cndmask_b32_e64 v41, v42, v41, s[40:41]
	s_waitcnt vmcnt(21)
	v_mul_f32_e32 v42, v13, v40
	s_nop 1
	v_add_f32_dpp v42, v42, v42 quad_perm:[1,0,3,2] row_mask:0xf bank_mask:0xf
	s_nop 1
	v_add_f32_dpp v40, v42, v42 quad_perm:[2,3,0,1] row_mask:0xf bank_mask:0xf
	s_nop 1
	v_add_f32_dpp v40, v40, v40 row_half_mirror row_mask:0xf bank_mask:0xf
	s_nop 1
	v_add_f32_dpp v40, v40, v40 row_mirror row_mask:0xf bank_mask:0xf
	v_mov_b32_e32 v42, v40
	s_nop 1
	v_permlane16_swap_b32_e32 v42, v40
	v_add_f32_e32 v40, v40, v42
	v_mov_b32_e32 v42, v40
	s_nop 1
	v_permlane32_swap_b32_e32 v42, v40
	v_add_f32_e32 v40, v40, v42
	v_cndmask_b32_e64 v40, v41, v40, s[42:43]
	s_waitcnt vmcnt(20)
	v_mul_f32_e32 v41, v13, v39
	s_nop 1
	v_add_f32_dpp v41, v41, v41 quad_perm:[1,0,3,2] row_mask:0xf bank_mask:0xf
	s_nop 1
	v_add_f32_dpp v39, v41, v41 quad_perm:[2,3,0,1] row_mask:0xf bank_mask:0xf
	s_nop 1
	v_add_f32_dpp v39, v39, v39 row_half_mirror row_mask:0xf bank_mask:0xf
	s_nop 1
	v_add_f32_dpp v39, v39, v39 row_mirror row_mask:0xf bank_mask:0xf
	v_mov_b32_e32 v41, v39
	s_nop 1
	v_permlane16_swap_b32_e32 v41, v39
	v_add_f32_e32 v39, v39, v41
	v_mov_b32_e32 v41, v39
	s_nop 1
	v_permlane32_swap_b32_e32 v41, v39
	v_add_f32_e32 v39, v39, v41
	v_cndmask_b32_e64 v39, v40, v39, s[48:49]
	s_waitcnt vmcnt(19)
	v_mul_f32_e32 v40, v13, v38
	s_lshl_b64 s[48:49], s[2:3], 13
	s_nop 1
	v_add_f32_dpp v40, v40, v40 quad_perm:[1,0,3,2] row_mask:0xf bank_mask:0xf
	s_nop 1
	v_add_f32_dpp v38, v40, v40 quad_perm:[2,3,0,1] row_mask:0xf bank_mask:0xf
	s_nop 1
	v_add_f32_dpp v38, v38, v38 row_half_mirror row_mask:0xf bank_mask:0xf
	s_nop 1
	v_add_f32_dpp v38, v38, v38 row_mirror row_mask:0xf bank_mask:0xf
	v_mov_b32_e32 v40, v38
	s_nop 1
	v_permlane16_swap_b32_e32 v40, v38
	v_add_f32_e32 v38, v38, v40
	v_mov_b32_e32 v40, v38
	s_nop 1
	v_permlane32_swap_b32_e32 v40, v38
	v_add_f32_e32 v38, v38, v40
	v_cndmask_b32_e64 v38, v39, v38, s[50:51]
	s_waitcnt vmcnt(18)
	v_mul_f32_e32 v39, v13, v37
	s_nop 1
	v_add_f32_dpp v39, v39, v39 quad_perm:[1,0,3,2] row_mask:0xf bank_mask:0xf
	s_nop 1
	v_add_f32_dpp v37, v39, v39 quad_perm:[2,3,0,1] row_mask:0xf bank_mask:0xf
	s_nop 1
	v_add_f32_dpp v37, v37, v37 row_half_mirror row_mask:0xf bank_mask:0xf
	s_nop 1
	v_add_f32_dpp v37, v37, v37 row_mirror row_mask:0xf bank_mask:0xf
	v_mov_b32_e32 v39, v37
	s_nop 1
	v_permlane16_swap_b32_e32 v39, v37
	v_add_f32_e32 v37, v37, v39
	v_mov_b32_e32 v39, v37
	s_nop 1
	v_permlane32_swap_b32_e32 v39, v37
	v_add_f32_e32 v37, v37, v39
	v_cndmask_b32_e64 v37, v38, v37, s[64:65]
	s_waitcnt vmcnt(17)
	v_mul_f32_e32 v38, v13, v36
	s_nop 1
	v_add_f32_dpp v38, v38, v38 quad_perm:[1,0,3,2] row_mask:0xf bank_mask:0xf
	s_nop 1
	v_add_f32_dpp v36, v38, v38 quad_perm:[2,3,0,1] row_mask:0xf bank_mask:0xf
	s_nop 1
	v_add_f32_dpp v36, v36, v36 row_half_mirror row_mask:0xf bank_mask:0xf
	s_nop 1
	v_add_f32_dpp v36, v36, v36 row_mirror row_mask:0xf bank_mask:0xf
	v_mov_b32_e32 v38, v36
	s_nop 1
	v_permlane16_swap_b32_e32 v38, v36
	v_add_f32_e32 v36, v36, v38
	v_mov_b32_e32 v38, v36
	s_nop 1
	v_permlane32_swap_b32_e32 v38, v36
	v_add_f32_e32 v36, v36, v38
	v_cndmask_b32_e64 v36, v37, v36, s[78:79]
	s_waitcnt vmcnt(16)
	v_mul_f32_e32 v37, v13, v35
	s_nop 1
	v_add_f32_dpp v37, v37, v37 quad_perm:[1,0,3,2] row_mask:0xf bank_mask:0xf
	s_nop 1
	v_add_f32_dpp v35, v37, v37 quad_perm:[2,3,0,1] row_mask:0xf bank_mask:0xf
	s_nop 1
	v_add_f32_dpp v35, v35, v35 row_half_mirror row_mask:0xf bank_mask:0xf
	s_nop 1
	v_add_f32_dpp v35, v35, v35 row_mirror row_mask:0xf bank_mask:0xf
	v_mov_b32_e32 v37, v35
	s_nop 1
	v_permlane16_swap_b32_e32 v37, v35
	v_add_f32_e32 v35, v35, v37
	v_mov_b32_e32 v37, v35
	s_nop 1
	v_permlane32_swap_b32_e32 v37, v35
	v_add_f32_e32 v35, v35, v37
	v_cndmask_b32_e64 v35, v36, v35, s[86:87]
	s_waitcnt vmcnt(15)
	v_mul_f32_e32 v36, v13, v27
	s_nop 1
	v_add_f32_dpp v36, v36, v36 quad_perm:[1,0,3,2] row_mask:0xf bank_mask:0xf
	s_nop 1
	v_add_f32_dpp v27, v36, v36 quad_perm:[2,3,0,1] row_mask:0xf bank_mask:0xf
	s_nop 1
	v_add_f32_dpp v27, v27, v27 row_half_mirror row_mask:0xf bank_mask:0xf
	s_nop 1
	v_add_f32_dpp v27, v27, v27 row_mirror row_mask:0xf bank_mask:0xf
	v_mov_b32_e32 v36, v27
	s_nop 1
	v_permlane16_swap_b32_e32 v36, v27
	v_add_f32_e32 v27, v27, v36
	v_mov_b32_e32 v36, v27
	s_nop 1
	v_permlane32_swap_b32_e32 v36, v27
	v_add_f32_e32 v27, v27, v36
	v_cndmask_b32_e64 v27, v35, v27, s[0:1]
	s_waitcnt vmcnt(14)
	v_mul_f32_e32 v35, v13, v26
	v_readlane_b32 s0, v250, 15
	v_readlane_b32 s1, v250, 16
	s_nop 1
	v_add_f32_dpp v35, v35, v35 quad_perm:[1,0,3,2] row_mask:0xf bank_mask:0xf
	s_nop 1
	v_add_f32_dpp v26, v35, v35 quad_perm:[2,3,0,1] row_mask:0xf bank_mask:0xf
	s_nop 1
	v_add_f32_dpp v26, v26, v26 row_half_mirror row_mask:0xf bank_mask:0xf
	s_nop 1
	v_add_f32_dpp v26, v26, v26 row_mirror row_mask:0xf bank_mask:0xf
	v_mov_b32_e32 v35, v26
	s_nop 1
	v_permlane16_swap_b32_e32 v35, v26
	v_add_f32_e32 v26, v26, v35
	v_mov_b32_e32 v35, v26
	s_nop 1
	v_permlane32_swap_b32_e32 v35, v26
	v_add_f32_e32 v26, v26, v35
	v_cndmask_b32_e64 v26, v27, v26, s[0:1]
	s_waitcnt vmcnt(13)
	v_mul_f32_e32 v27, v13, v25
	v_readlane_b32 s0, v250, 17
	v_readlane_b32 s1, v250, 18
	s_nop 1
	v_add_f32_dpp v27, v27, v27 quad_perm:[1,0,3,2] row_mask:0xf bank_mask:0xf
	s_nop 1
	v_add_f32_dpp v25, v27, v27 quad_perm:[2,3,0,1] row_mask:0xf bank_mask:0xf
	s_nop 1
	v_add_f32_dpp v25, v25, v25 row_half_mirror row_mask:0xf bank_mask:0xf
	s_nop 1
	v_add_f32_dpp v25, v25, v25 row_mirror row_mask:0xf bank_mask:0xf
	v_mov_b32_e32 v27, v25
	s_nop 1
	v_permlane16_swap_b32_e32 v27, v25
	v_add_f32_e32 v25, v25, v27
	v_mov_b32_e32 v27, v25
	s_nop 1
	v_permlane32_swap_b32_e32 v27, v25
	v_add_f32_e32 v25, v25, v27
	v_cndmask_b32_e64 v25, v26, v25, s[0:1]
	s_waitcnt vmcnt(12)
	v_mul_f32_e32 v26, v13, v24
	v_readlane_b32 s0, v250, 19
	v_readlane_b32 s1, v250, 20
	s_nop 1
	v_add_f32_dpp v26, v26, v26 quad_perm:[1,0,3,2] row_mask:0xf bank_mask:0xf
	s_nop 1
	v_add_f32_dpp v24, v26, v26 quad_perm:[2,3,0,1] row_mask:0xf bank_mask:0xf
	s_nop 1
	v_add_f32_dpp v24, v24, v24 row_half_mirror row_mask:0xf bank_mask:0xf
	s_nop 1
	v_add_f32_dpp v24, v24, v24 row_mirror row_mask:0xf bank_mask:0xf
	v_mov_b32_e32 v26, v24
	s_nop 1
	v_permlane16_swap_b32_e32 v26, v24
	v_add_f32_e32 v24, v24, v26
	v_mov_b32_e32 v26, v24
	s_nop 1
	v_permlane32_swap_b32_e32 v26, v24
	v_add_f32_e32 v24, v24, v26
	v_cndmask_b32_e64 v24, v25, v24, s[0:1]
	s_waitcnt vmcnt(11)
	v_mul_f32_e32 v25, v13, v23
	v_readlane_b32 s0, v250, 21
	v_readlane_b32 s1, v250, 22
	s_nop 1
	v_add_f32_dpp v25, v25, v25 quad_perm:[1,0,3,2] row_mask:0xf bank_mask:0xf
	s_nop 1
	v_add_f32_dpp v23, v25, v25 quad_perm:[2,3,0,1] row_mask:0xf bank_mask:0xf
	s_nop 1
	v_add_f32_dpp v23, v23, v23 row_half_mirror row_mask:0xf bank_mask:0xf
	s_nop 1
	v_add_f32_dpp v23, v23, v23 row_mirror row_mask:0xf bank_mask:0xf
	v_mov_b32_e32 v25, v23
	s_nop 1
	v_permlane16_swap_b32_e32 v25, v23
	v_add_f32_e32 v23, v23, v25
	v_mov_b32_e32 v25, v23
	s_nop 1
	v_permlane32_swap_b32_e32 v25, v23
	v_add_f32_e32 v23, v23, v25
	v_cndmask_b32_e64 v23, v24, v23, s[0:1]
	s_waitcnt vmcnt(10)
	v_mul_f32_e32 v24, v13, v22
	v_readlane_b32 s0, v250, 23
	v_readlane_b32 s1, v250, 24
	s_nop 1
	v_add_f32_dpp v24, v24, v24 quad_perm:[1,0,3,2] row_mask:0xf bank_mask:0xf
	s_nop 1
	v_add_f32_dpp v22, v24, v24 quad_perm:[2,3,0,1] row_mask:0xf bank_mask:0xf
	s_nop 1
	v_add_f32_dpp v22, v22, v22 row_half_mirror row_mask:0xf bank_mask:0xf
	s_nop 1
	v_add_f32_dpp v22, v22, v22 row_mirror row_mask:0xf bank_mask:0xf
	v_mov_b32_e32 v24, v22
	s_nop 1
	v_permlane16_swap_b32_e32 v24, v22
	v_add_f32_e32 v22, v22, v24
	v_mov_b32_e32 v24, v22
	s_nop 1
	v_permlane32_swap_b32_e32 v24, v22
	v_add_f32_e32 v22, v22, v24
	v_cndmask_b32_e64 v22, v23, v22, s[0:1]
	s_waitcnt vmcnt(9)
	v_mul_f32_e32 v23, v13, v21
	v_readlane_b32 s0, v250, 25
	v_readlane_b32 s1, v250, 26
	s_nop 1
	v_add_f32_dpp v23, v23, v23 quad_perm:[1,0,3,2] row_mask:0xf bank_mask:0xf
	s_nop 1
	v_add_f32_dpp v21, v23, v23 quad_perm:[2,3,0,1] row_mask:0xf bank_mask:0xf
	s_nop 1
	v_add_f32_dpp v21, v21, v21 row_half_mirror row_mask:0xf bank_mask:0xf
	s_nop 1
	v_add_f32_dpp v21, v21, v21 row_mirror row_mask:0xf bank_mask:0xf
	v_mov_b32_e32 v23, v21
	s_nop 1
	v_permlane16_swap_b32_e32 v23, v21
	v_add_f32_e32 v21, v21, v23
	v_mov_b32_e32 v23, v21
	s_nop 1
	v_permlane32_swap_b32_e32 v23, v21
	v_add_f32_e32 v21, v21, v23
	v_cndmask_b32_e64 v21, v22, v21, s[0:1]
	s_waitcnt vmcnt(8)
	v_mul_f32_e32 v22, v13, v20
	v_readlane_b32 s0, v250, 27
	v_readlane_b32 s1, v250, 28
	s_nop 1
	v_add_f32_dpp v22, v22, v22 quad_perm:[1,0,3,2] row_mask:0xf bank_mask:0xf
	s_nop 1
	v_add_f32_dpp v20, v22, v22 quad_perm:[2,3,0,1] row_mask:0xf bank_mask:0xf
	s_nop 1
	v_add_f32_dpp v20, v20, v20 row_half_mirror row_mask:0xf bank_mask:0xf
	s_nop 1
	v_add_f32_dpp v20, v20, v20 row_mirror row_mask:0xf bank_mask:0xf
	v_mov_b32_e32 v22, v20
	s_nop 1
	v_permlane16_swap_b32_e32 v22, v20
	v_add_f32_e32 v20, v20, v22
	v_mov_b32_e32 v22, v20
	s_nop 1
	v_permlane32_swap_b32_e32 v22, v20
	v_add_f32_e32 v20, v20, v22
	v_cndmask_b32_e64 v20, v21, v20, s[0:1]
	s_waitcnt vmcnt(7)
	v_mul_f32_e32 v21, v13, v19
	v_readlane_b32 s0, v250, 29
	v_readlane_b32 s1, v250, 30
	s_nop 1
	v_add_f32_dpp v21, v21, v21 quad_perm:[1,0,3,2] row_mask:0xf bank_mask:0xf
	s_nop 1
	v_add_f32_dpp v19, v21, v21 quad_perm:[2,3,0,1] row_mask:0xf bank_mask:0xf
	s_nop 1
	v_add_f32_dpp v19, v19, v19 row_half_mirror row_mask:0xf bank_mask:0xf
	s_nop 1
	v_add_f32_dpp v19, v19, v19 row_mirror row_mask:0xf bank_mask:0xf
	v_mov_b32_e32 v21, v19
	s_nop 1
	v_permlane16_swap_b32_e32 v21, v19
	v_add_f32_e32 v19, v19, v21
	v_mov_b32_e32 v21, v19
	s_nop 1
	v_permlane32_swap_b32_e32 v21, v19
	v_add_f32_e32 v19, v19, v21
	v_cndmask_b32_e64 v19, v20, v19, s[0:1]
	s_waitcnt vmcnt(6)
	v_mul_f32_e32 v20, v13, v18
	v_readlane_b32 s0, v250, 31
	v_readlane_b32 s1, v250, 32
	s_nop 1
	v_add_f32_dpp v20, v20, v20 quad_perm:[1,0,3,2] row_mask:0xf bank_mask:0xf
	s_nop 1
	v_add_f32_dpp v18, v20, v20 quad_perm:[2,3,0,1] row_mask:0xf bank_mask:0xf
	s_nop 1
	v_add_f32_dpp v18, v18, v18 row_half_mirror row_mask:0xf bank_mask:0xf
	s_nop 1
	v_add_f32_dpp v18, v18, v18 row_mirror row_mask:0xf bank_mask:0xf
	v_mov_b32_e32 v20, v18
	s_nop 1
	v_permlane16_swap_b32_e32 v20, v18
	v_add_f32_e32 v18, v18, v20
	v_mov_b32_e32 v20, v18
	s_nop 1
	v_permlane32_swap_b32_e32 v20, v18
	v_add_f32_e32 v18, v18, v20
	v_cndmask_b32_e64 v18, v19, v18, s[0:1]
	s_waitcnt vmcnt(5)
	v_mul_f32_e32 v19, v13, v17
	v_readlane_b32 s0, v250, 33
	v_readlane_b32 s1, v250, 34
	s_nop 1
	v_add_f32_dpp v19, v19, v19 quad_perm:[1,0,3,2] row_mask:0xf bank_mask:0xf
	s_nop 1
	v_add_f32_dpp v17, v19, v19 quad_perm:[2,3,0,1] row_mask:0xf bank_mask:0xf
	s_nop 1
	v_add_f32_dpp v17, v17, v17 row_half_mirror row_mask:0xf bank_mask:0xf
	s_nop 1
	v_add_f32_dpp v17, v17, v17 row_mirror row_mask:0xf bank_mask:0xf
	v_mov_b32_e32 v19, v17
	s_nop 1
	v_permlane16_swap_b32_e32 v19, v17
	v_add_f32_e32 v17, v17, v19
	v_mov_b32_e32 v19, v17
	s_nop 1
	v_permlane32_swap_b32_e32 v19, v17
	v_add_f32_e32 v17, v17, v19
	v_cndmask_b32_e64 v17, v18, v17, s[0:1]
	s_waitcnt vmcnt(4)
	v_mul_f32_e32 v18, v13, v16
	v_readlane_b32 s0, v250, 35
	v_readlane_b32 s1, v250, 36
	s_nop 1
	v_add_f32_dpp v18, v18, v18 quad_perm:[1,0,3,2] row_mask:0xf bank_mask:0xf
	s_nop 1
	v_add_f32_dpp v16, v18, v18 quad_perm:[2,3,0,1] row_mask:0xf bank_mask:0xf
	s_nop 1
	v_add_f32_dpp v16, v16, v16 row_half_mirror row_mask:0xf bank_mask:0xf
	s_nop 1
	v_add_f32_dpp v16, v16, v16 row_mirror row_mask:0xf bank_mask:0xf
	v_mov_b32_e32 v18, v16
	s_nop 1
	v_permlane16_swap_b32_e32 v18, v16
	v_add_f32_e32 v16, v16, v18
	v_mov_b32_e32 v18, v16
	s_nop 1
	v_permlane32_swap_b32_e32 v18, v16
	v_add_f32_e32 v16, v16, v18
	v_cndmask_b32_e64 v16, v17, v16, s[0:1]
	s_waitcnt vmcnt(3)
	v_mul_f32_e32 v17, v13, v11
	v_readlane_b32 s0, v250, 37
	v_readlane_b32 s1, v250, 38
	s_nop 1
	v_add_f32_dpp v17, v17, v17 quad_perm:[1,0,3,2] row_mask:0xf bank_mask:0xf
	s_nop 1
	v_add_f32_dpp v11, v17, v17 quad_perm:[2,3,0,1] row_mask:0xf bank_mask:0xf
	s_nop 1
	v_add_f32_dpp v11, v11, v11 row_half_mirror row_mask:0xf bank_mask:0xf
	s_nop 1
	v_add_f32_dpp v11, v11, v11 row_mirror row_mask:0xf bank_mask:0xf
	v_mov_b32_e32 v17, v11
	s_nop 1
	v_permlane16_swap_b32_e32 v17, v11
	v_add_f32_e32 v11, v11, v17
	v_mov_b32_e32 v17, v11
	s_nop 1
	v_permlane32_swap_b32_e32 v17, v11
	v_add_f32_e32 v11, v11, v17
	v_cndmask_b32_e64 v11, v16, v11, s[0:1]
	s_waitcnt vmcnt(2)
	v_mul_f32_e32 v16, v13, v10
	v_readlane_b32 s0, v250, 39
	v_readlane_b32 s1, v250, 40
	s_nop 1
	v_add_f32_dpp v16, v16, v16 quad_perm:[1,0,3,2] row_mask:0xf bank_mask:0xf
	s_nop 1
	v_add_f32_dpp v10, v16, v16 quad_perm:[2,3,0,1] row_mask:0xf bank_mask:0xf
	s_nop 1
	v_add_f32_dpp v10, v10, v10 row_half_mirror row_mask:0xf bank_mask:0xf
	s_nop 1
	v_add_f32_dpp v10, v10, v10 row_mirror row_mask:0xf bank_mask:0xf
	v_mov_b32_e32 v16, v10
	s_nop 1
	v_permlane16_swap_b32_e32 v16, v10
	v_add_f32_e32 v10, v10, v16
	v_mov_b32_e32 v16, v10
	s_nop 1
	v_permlane32_swap_b32_e32 v16, v10
	v_add_f32_e32 v10, v10, v16
	v_cndmask_b32_e64 v10, v11, v10, s[0:1]
	s_waitcnt vmcnt(1)
	v_mul_f32_e32 v11, v13, v9
	v_readlane_b32 s0, v250, 41
	v_readlane_b32 s1, v250, 42
	s_nop 1
	v_add_f32_dpp v11, v11, v11 quad_perm:[1,0,3,2] row_mask:0xf bank_mask:0xf
	s_nop 1
	v_add_f32_dpp v9, v11, v11 quad_perm:[2,3,0,1] row_mask:0xf bank_mask:0xf
	s_nop 1
	v_add_f32_dpp v9, v9, v9 row_half_mirror row_mask:0xf bank_mask:0xf
	s_nop 1
	v_add_f32_dpp v9, v9, v9 row_mirror row_mask:0xf bank_mask:0xf
	v_mov_b32_e32 v11, v9
	s_nop 1
	v_permlane16_swap_b32_e32 v11, v9
	v_add_f32_e32 v9, v9, v11
	v_mov_b32_e32 v11, v9
	s_nop 1
	v_permlane32_swap_b32_e32 v11, v9
	v_add_f32_e32 v9, v9, v11
	v_cndmask_b32_e64 v9, v10, v9, s[0:1]
	s_waitcnt vmcnt(0)
	v_mul_f32_e32 v10, v13, v8
	v_readlane_b32 s0, v250, 43
	v_readlane_b32 s1, v250, 44
	s_nop 1
	v_add_f32_dpp v10, v10, v10 quad_perm:[1,0,3,2] row_mask:0xf bank_mask:0xf
	s_nop 1
	v_add_f32_dpp v8, v10, v10 quad_perm:[2,3,0,1] row_mask:0xf bank_mask:0xf
	s_nop 1
	v_add_f32_dpp v8, v8, v8 row_half_mirror row_mask:0xf bank_mask:0xf
	s_nop 1
	v_add_f32_dpp v8, v8, v8 row_mirror row_mask:0xf bank_mask:0xf
	v_mov_b32_e32 v10, v8
	s_nop 1
	v_permlane16_swap_b32_e32 v10, v8
	v_add_f32_e32 v8, v8, v10
	v_mov_b32_e32 v10, v8
	s_nop 1
	v_permlane32_swap_b32_e32 v10, v8
	v_add_f32_e32 v8, v8, v10
	v_cndmask_b32_e64 v8, v9, v8, s[0:1]
	v_mul_f32_e32 v9, v13, v14
	v_readlane_b32 s0, v250, 52
	v_readlane_b32 s1, v250, 53
	v_max_f32_e32 v11, v8, v8
	s_nop 1
	v_add_f32_dpp v9, v9, v9 quad_perm:[1,0,3,2] row_mask:0xf bank_mask:0xf
	v_lshl_add_u64 v[26:27], v[6:7], 0, s[0:1]
	v_readlane_b32 s0, v250, 49
	s_lshl_b32 s43, s0, 2
	s_movk_i32 s1, 0x1000
	s_nop 1
	v_add_f32_dpp v9, v9, v9 quad_perm:[2,3,0,1] row_mask:0xf bank_mask:0xf
	v_add_co_u32_e32 v14, vcc, s1, v26
	s_movk_i32 s1, 0x2000
	s_nop 1
	v_add_f32_dpp v9, v9, v9 row_half_mirror row_mask:0xf bank_mask:0xf
	s_nop 1
	v_add_f32_dpp v9, v9, v9 row_mirror row_mask:0xf bank_mask:0xf
	v_mov_b32_e32 v10, v9
	s_nop 1
	v_permlane16_swap_b32_e32 v10, v9
	v_add_f32_e32 v9, v9, v10
	v_mov_b32_e32 v10, v9
	s_nop 1
	v_permlane32_swap_b32_e32 v10, v9
	v_add_f32_e32 v9, v9, v10
	v_mov_b32_e32 v10, s43
	global_load_dword v35, v10, s[44:45]
	v_max_f32_e32 v10, v15, v15
	v_max_f32_e32 v10, v10, v11
	s_nop 1
	v_max_f32_dpp v10, v10, v10 quad_perm:[1,0,3,2] row_mask:0xf bank_mask:0xf
	s_nop 1
	v_max_f32_dpp v10, v10, v10 quad_perm:[2,3,0,1] row_mask:0xf bank_mask:0xf
	s_nop 1
	v_max_f32_dpp v10, v10, v10 row_half_mirror row_mask:0xf bank_mask:0xf
	s_nop 1
	v_max_f32_dpp v10, v10, v10 row_mirror row_mask:0xf bank_mask:0xf
	v_mov_b32_e32 v11, v10
	s_nop 1
	v_permlane16_swap_b32_e32 v11, v10
	v_max_f32_e32 v10, v10, v11
	v_mov_b32_e32 v11, v10
	s_nop 1
	v_permlane32_swap_b32_e32 v11, v10
	v_max_f32_e32 v10, v10, v11
	s_waitcnt vmcnt(0)
	v_max3_f32 v36, v10, v9, v35
	v_sub_f32_e32 v8, v8, v36
	v_mul_f32_e32 v8, 0x3fb8aa3b, v8
	v_sub_f32_e32 v10, v15, v36
	v_exp_f32_e32 v13, v8
	v_sub_f32_e32 v8, v9, v36
	v_mul_f32_e32 v10, 0x3fb8aa3b, v10
	v_mul_f32_e32 v8, 0x3fb8aa3b, v8
	v_exp_f32_e32 v11, v10
	v_exp_f32_e32 v9, v8
	global_load_dword v8, v[26:27], off
	global_load_dword v10, v[26:27], off offset:2048
	v_addc_co_u32_e32 v15, vcc, 0, v27, vcc
	v_add_co_u32_e32 v16, vcc, s1, v26
	s_movk_i32 s1, 0x3000
	s_nop 0
	v_addc_co_u32_e32 v17, vcc, 0, v27, vcc
	global_load_dword v18, v[16:17], off offset:-4096
	global_load_dword v19, v[14:15], off offset:2048
	global_load_dword v20, v[16:17], off
	global_load_dword v21, v[16:17], off offset:2048
	v_add_co_u32_e32 v14, vcc, s1, v26
	s_movk_i32 s1, 0x4000
	s_nop 0
	v_addc_co_u32_e32 v15, vcc, 0, v27, vcc
	v_add_co_u32_e32 v16, vcc, s1, v26
	s_movk_i32 s1, 0x5000
	s_nop 0
	v_addc_co_u32_e32 v17, vcc, 0, v27, vcc
	global_load_dword v22, v[16:17], off offset:-4096
	global_load_dword v23, v[14:15], off offset:2048
	global_load_dword v24, v[16:17], off
	global_load_dword v25, v[16:17], off offset:2048
	v_add_co_u32_e32 v14, vcc, s1, v26
	s_movk_i32 s1, 0x6000
	s_nop 0
	v_addc_co_u32_e32 v15, vcc, 0, v27, vcc
	v_add_co_u32_e32 v16, vcc, s1, v26
	s_movk_i32 s1, 0x7000
	s_nop 0
	v_addc_co_u32_e32 v17, vcc, 0, v27, vcc
	global_load_dword v37, v[16:17], off offset:-4096
	global_load_dword v38, v[14:15], off offset:2048
	global_load_dword v39, v[16:17], off
	global_load_dword v40, v[16:17], off offset:2048
	v_add_co_u32_e32 v14, vcc, s1, v26
	s_mov_b32 s1, 0x8000
	s_nop 0
	v_addc_co_u32_e32 v15, vcc, 0, v27, vcc
	v_add_co_u32_e32 v16, vcc, s1, v26
	s_mov_b32 s1, 0x9000
	s_nop 0
	v_addc_co_u32_e32 v17, vcc, 0, v27, vcc
	global_load_dword v41, v[16:17], off offset:-4096
	global_load_dword v42, v[14:15], off offset:2048
	global_load_dword v43, v[16:17], off
	global_load_dword v44, v[16:17], off offset:2048
	v_add_co_u32_e32 v14, vcc, s1, v26
	s_mov_b32 s1, 0xa000
	s_nop 0
	v_addc_co_u32_e32 v15, vcc, 0, v27, vcc
	v_add_co_u32_e32 v16, vcc, s1, v26
	s_mov_b32 s1, 0xb000
	s_nop 0
	v_addc_co_u32_e32 v17, vcc, 0, v27, vcc
	global_load_dword v45, v[16:17], off offset:-4096
	global_load_dword v46, v[14:15], off offset:2048
	global_load_dword v47, v[16:17], off
	global_load_dword v48, v[16:17], off offset:2048
	v_add_co_u32_e32 v14, vcc, s1, v26
	s_mov_b32 s1, 0xc000
	s_nop 0
	v_addc_co_u32_e32 v15, vcc, 0, v27, vcc
	v_add_co_u32_e32 v16, vcc, s1, v26
	s_mov_b32 s1, 0xd000
	s_nop 0
	v_addc_co_u32_e32 v17, vcc, 0, v27, vcc
	global_load_dword v49, v[16:17], off offset:-4096
	global_load_dword v50, v[14:15], off offset:2048
	global_load_dword v51, v[16:17], off
	global_load_dword v52, v[16:17], off offset:2048
	v_add_co_u32_e32 v14, vcc, s1, v26
	s_mov_b32 s1, 0xe000
	s_nop 0
	v_addc_co_u32_e32 v15, vcc, 0, v27, vcc
	v_add_co_u32_e32 v16, vcc, s1, v26
	s_mov_b32 s1, 0xf000
	s_nop 0
	v_addc_co_u32_e32 v17, vcc, 0, v27, vcc
	global_load_dword v53, v[16:17], off offset:-4096
	global_load_dword v54, v[14:15], off offset:2048
	global_load_dword v55, v[16:17], off
	global_load_dword v56, v[16:17], off offset:2048
	v_add_co_u32_e32 v14, vcc, s1, v26
	s_mov_b32 s1, 0x10000
	s_nop 0
	v_addc_co_u32_e32 v15, vcc, 0, v27, vcc
	v_add_co_u32_e32 v16, vcc, s1, v26
	s_mov_b32 s1, 0x11000
	s_nop 0
	v_addc_co_u32_e32 v17, vcc, 0, v27, vcc
	global_load_dword v57, v[16:17], off offset:-4096
	global_load_dword v58, v[14:15], off offset:2048
	global_load_dword v59, v[16:17], off
	global_load_dword v60, v[16:17], off offset:2048
	v_add_co_u32_e32 v14, vcc, s1, v26
	s_mov_b32 s1, 0x12000
	s_nop 0
	v_addc_co_u32_e32 v15, vcc, 0, v27, vcc
	v_add_co_u32_e32 v16, vcc, s1, v26
	s_mov_b32 s1, 0x13000
	s_nop 0
	v_addc_co_u32_e32 v17, vcc, 0, v27, vcc
	global_load_dword v61, v[16:17], off offset:-4096
	global_load_dword v62, v[14:15], off offset:2048
	global_load_dword v63, v[16:17], off
	global_load_dword v64, v[16:17], off offset:2048
	v_add_co_u32_e32 v14, vcc, s1, v26
	s_mov_b32 s1, 0x14000
	s_nop 0
	v_addc_co_u32_e32 v15, vcc, 0, v27, vcc
	v_add_co_u32_e32 v16, vcc, s1, v26
	s_mov_b32 s1, 0x15000
	s_nop 0
	v_addc_co_u32_e32 v17, vcc, 0, v27, vcc
	global_load_dword v65, v[16:17], off offset:-4096
	global_load_dword v66, v[14:15], off offset:2048
	global_load_dword v67, v[16:17], off
	global_load_dword v68, v[16:17], off offset:2048
	v_add_co_u32_e32 v14, vcc, s1, v26
	s_mov_b32 s1, 0x16000
	s_nop 0
	v_addc_co_u32_e32 v15, vcc, 0, v27, vcc
	v_add_co_u32_e32 v16, vcc, s1, v26
	s_mov_b32 s1, 0x17000
	s_nop 0
	v_addc_co_u32_e32 v17, vcc, 0, v27, vcc
	global_load_dword v69, v[16:17], off offset:-4096
	global_load_dword v70, v[14:15], off offset:2048
	global_load_dword v71, v[16:17], off
	global_load_dword v72, v[16:17], off offset:2048
	v_add_co_u32_e32 v14, vcc, s1, v26
	s_mov_b32 s1, 0x18000
	s_nop 0
	v_addc_co_u32_e32 v15, vcc, 0, v27, vcc
	v_add_co_u32_e32 v16, vcc, s1, v26
	s_mov_b32 s1, 0x19000
	s_nop 0
	v_addc_co_u32_e32 v17, vcc, 0, v27, vcc
	global_load_dword v73, v[16:17], off offset:-4096
	global_load_dword v74, v[14:15], off offset:2048
	global_load_dword v75, v[16:17], off
	global_load_dword v76, v[16:17], off offset:2048
	v_add_co_u32_e32 v14, vcc, s1, v26
	s_mov_b32 s1, 0x1a000
	s_nop 0
	v_addc_co_u32_e32 v15, vcc, 0, v27, vcc
	v_add_co_u32_e32 v16, vcc, s1, v26
	s_mov_b32 s1, 0x1b000
	s_nop 0
	v_addc_co_u32_e32 v17, vcc, 0, v27, vcc
	global_load_dword v77, v[16:17], off offset:-4096
	global_load_dword v78, v[14:15], off offset:2048
	global_load_dword v79, v[16:17], off
	global_load_dword v80, v[16:17], off offset:2048
	v_add_co_u32_e32 v14, vcc, s1, v26
	s_mov_b32 s1, 0x1c000
	s_nop 0
	v_addc_co_u32_e32 v15, vcc, 0, v27, vcc
	v_add_co_u32_e32 v16, vcc, s1, v26
	s_mov_b32 s1, 0x1d000
	s_nop 0
	v_addc_co_u32_e32 v17, vcc, 0, v27, vcc
	global_load_dword v81, v[16:17], off offset:-4096
	global_load_dword v82, v[14:15], off offset:2048
	global_load_dword v83, v[16:17], off
	global_load_dword v84, v[16:17], off offset:2048
	v_add_co_u32_e32 v14, vcc, s1, v26
	s_mov_b32 s1, 0x1e000
	s_nop 0
	v_addc_co_u32_e32 v15, vcc, 0, v27, vcc
	v_add_co_u32_e32 v16, vcc, s1, v26
	s_mov_b32 s1, 0x1f000
	s_nop 0
	v_addc_co_u32_e32 v17, vcc, 0, v27, vcc
	global_load_dword v85, v[16:17], off offset:-4096
	global_load_dword v86, v[14:15], off offset:2048
	global_load_dword v87, v[16:17], off
	global_load_dword v88, v[16:17], off offset:2048
	v_add_co_u32_e32 v14, vcc, s1, v26
	s_mov_b32 s1, 0x20000
	s_nop 0
	v_addc_co_u32_e32 v15, vcc, 0, v27, vcc
	v_add_co_u32_e32 v16, vcc, s1, v26
	v_readlane_b32 s43, v11, 0
	s_nop 0
	v_addc_co_u32_e32 v17, vcc, 0, v27, vcc
	global_load_dword v89, v[16:17], off offset:-4096
	s_nop 0
	global_load_dword v14, v[14:15], off offset:2048
	s_waitcnt vmcnt(62)
	v_mul_f32_e32 v8, s43, v8
	v_fmac_f32_e32 v8, v12, v9
	v_readlane_b32 s43, v11, 1
	s_mov_b32 s1, 0x21000
	v_readlane_b32 s50, v13, 43
	v_fmac_f32_e32 v8, s43, v10
	v_readlane_b32 s43, v11, 2
	v_readlane_b32 s51, v13, 44
	s_waitcnt vmcnt(61)
	v_fmac_f32_e32 v8, s43, v18
	v_readlane_b32 s43, v11, 3
	s_waitcnt vmcnt(60)
	s_nop 0
	v_fmac_f32_e32 v8, s43, v19
	v_readlane_b32 s43, v11, 4
	s_waitcnt vmcnt(59)
	s_nop 0
	v_fmac_f32_e32 v8, s43, v20
	v_readlane_b32 s43, v11, 5
	s_waitcnt vmcnt(58)
	s_nop 0
	v_fmac_f32_e32 v8, s43, v21
	v_readlane_b32 s43, v11, 6
	s_waitcnt vmcnt(57)
	s_nop 0
	v_fmac_f32_e32 v8, s43, v22
	v_readlane_b32 s43, v11, 7
	s_waitcnt vmcnt(56)
	s_nop 0
	v_fmac_f32_e32 v8, s43, v23
	v_readlane_b32 s43, v11, 8
	s_waitcnt vmcnt(55)
	s_nop 0
	v_fmac_f32_e32 v8, s43, v24
	v_readlane_b32 s43, v11, 9
	s_waitcnt vmcnt(54)
	s_nop 0
	v_fmac_f32_e32 v8, s43, v25
	v_readlane_b32 s43, v11, 10
	s_waitcnt vmcnt(53)
	s_nop 0
	v_fmac_f32_e32 v8, s43, v37
	v_readlane_b32 s43, v11, 11
	s_waitcnt vmcnt(52)
	s_nop 0
	v_fmac_f32_e32 v8, s43, v38
	v_readlane_b32 s43, v11, 12
	s_waitcnt vmcnt(51)
	s_nop 0
	v_fmac_f32_e32 v8, s43, v39
	v_readlane_b32 s43, v11, 13
	s_waitcnt vmcnt(50)
	s_nop 0
	v_fmac_f32_e32 v8, s43, v40
	v_readlane_b32 s43, v11, 14
	s_waitcnt vmcnt(49)
	s_nop 0
	v_fmac_f32_e32 v8, s43, v41
	v_readlane_b32 s43, v11, 15
	s_waitcnt vmcnt(48)
	s_nop 0
	v_fmac_f32_e32 v8, s43, v42
	v_readlane_b32 s43, v11, 16
	s_waitcnt vmcnt(47)
	s_nop 0
	v_fmac_f32_e32 v8, s43, v43
	v_readlane_b32 s43, v11, 17
	global_load_dword v43, v[16:17], off
	global_load_dword v10, v[16:17], off offset:2048
	s_waitcnt vmcnt(48)
	v_fmac_f32_e32 v8, s43, v44
	v_readlane_b32 s43, v11, 18
	s_waitcnt vmcnt(47)
	s_nop 0
	v_fmac_f32_e32 v8, s43, v45
	v_readlane_b32 s43, v11, 19
	s_waitcnt vmcnt(46)
	s_nop 0
	v_fmac_f32_e32 v8, s43, v46
	v_readlane_b32 s43, v11, 20
	s_waitcnt vmcnt(45)
	s_nop 0
	v_fmac_f32_e32 v8, s43, v47
	v_readlane_b32 s43, v11, 21
	s_waitcnt vmcnt(44)
	s_nop 0
	v_fmac_f32_e32 v8, s43, v48
	v_readlane_b32 s43, v11, 22
	s_waitcnt vmcnt(43)
	s_nop 0
	v_fmac_f32_e32 v8, s43, v49
	v_readlane_b32 s43, v11, 23
	s_waitcnt vmcnt(42)
	s_nop 0
	v_fmac_f32_e32 v8, s43, v50
	v_readlane_b32 s43, v11, 24
	s_waitcnt vmcnt(41)
	s_nop 0
	v_fmac_f32_e32 v8, s43, v51
	v_readlane_b32 s43, v11, 25
	s_waitcnt vmcnt(40)
	s_nop 0
	v_fmac_f32_e32 v8, s43, v52
	v_readlane_b32 s43, v11, 26
	s_waitcnt vmcnt(39)
	s_nop 0
	v_fmac_f32_e32 v8, s43, v53
	v_readlane_b32 s43, v11, 27
	s_waitcnt vmcnt(38)
	s_nop 0
	v_fmac_f32_e32 v8, s43, v54
	v_readlane_b32 s43, v11, 28
	s_waitcnt vmcnt(37)
	s_nop 0
	v_fmac_f32_e32 v8, s43, v55
	v_readlane_b32 s43, v11, 29
	s_waitcnt vmcnt(36)
	s_nop 0
	v_fmac_f32_e32 v8, s43, v56
	v_readlane_b32 s43, v11, 30
	s_waitcnt vmcnt(35)
	s_nop 0
	v_fmac_f32_e32 v8, s43, v57
	v_readlane_b32 s43, v11, 31
	s_waitcnt vmcnt(34)
	s_nop 0
	v_fmac_f32_e32 v8, s43, v58
	v_readlane_b32 s43, v11, 32
	s_waitcnt vmcnt(33)
	s_nop 0
	v_fmac_f32_e32 v8, s43, v59
	v_readlane_b32 s43, v11, 33
	s_waitcnt vmcnt(32)
	s_nop 0
	v_fmac_f32_e32 v8, s43, v60
	v_readlane_b32 s43, v11, 34
	s_waitcnt vmcnt(31)
	s_nop 0
	v_fmac_f32_e32 v8, s43, v61
	v_readlane_b32 s43, v11, 35
	s_waitcnt vmcnt(30)
	s_nop 0
	v_fmac_f32_e32 v8, s43, v62
	v_readlane_b32 s43, v11, 36
	s_waitcnt vmcnt(29)
	s_nop 0
	v_fmac_f32_e32 v8, s43, v63
	v_readlane_b32 s43, v11, 37
	s_waitcnt vmcnt(28)
	s_nop 0
	v_fmac_f32_e32 v8, s43, v64
	v_readlane_b32 s43, v11, 38
	s_waitcnt vmcnt(27)
	s_nop 0
	v_fmac_f32_e32 v8, s43, v65
	v_readlane_b32 s43, v11, 39
	s_waitcnt vmcnt(26)
	s_nop 0
	v_fmac_f32_e32 v8, s43, v66
	v_readlane_b32 s43, v11, 40
	s_waitcnt vmcnt(25)
	s_nop 0
	v_fmac_f32_e32 v8, s43, v67
	v_readlane_b32 s43, v11, 41
	s_waitcnt vmcnt(24)
	s_nop 0
	v_fmac_f32_e32 v8, s43, v68
	v_readlane_b32 s43, v11, 42
	s_waitcnt vmcnt(23)
	s_nop 0
	v_fmac_f32_e32 v8, s43, v69
	v_readlane_b32 s43, v11, 43
	s_waitcnt vmcnt(22)
	s_nop 0
	v_fmac_f32_e32 v8, s43, v70
	v_readlane_b32 s43, v11, 44
	s_waitcnt vmcnt(21)
	s_nop 0
	v_fmac_f32_e32 v8, s43, v71
	v_readlane_b32 s43, v11, 45
	s_waitcnt vmcnt(20)
	s_nop 0
	v_fmac_f32_e32 v8, s43, v72
	v_readlane_b32 s43, v11, 46
	s_waitcnt vmcnt(19)
	s_nop 0
	v_fmac_f32_e32 v8, s43, v73
	v_readlane_b32 s43, v11, 47
	s_waitcnt vmcnt(18)
	s_nop 0
	v_fmac_f32_e32 v8, s43, v74
	v_readlane_b32 s43, v11, 48
	s_waitcnt vmcnt(17)
	s_nop 0
	v_fmac_f32_e32 v8, s43, v75
	v_readlane_b32 s43, v11, 49
	s_waitcnt vmcnt(16)
	s_nop 0
	v_fmac_f32_e32 v8, s43, v76
	v_readlane_b32 s43, v11, 50
	s_waitcnt vmcnt(15)
	s_nop 0
	v_fmac_f32_e32 v8, s43, v77
	v_readlane_b32 s43, v11, 51
	s_waitcnt vmcnt(14)
	s_nop 0
	v_fmac_f32_e32 v8, s43, v78
	v_readlane_b32 s43, v11, 52
	s_waitcnt vmcnt(13)
	s_nop 0
	v_fmac_f32_e32 v8, s43, v79
	v_readlane_b32 s43, v11, 53
	s_waitcnt vmcnt(12)
	s_nop 0
	v_fmac_f32_e32 v8, s43, v80
	v_readlane_b32 s43, v11, 54
	s_waitcnt vmcnt(11)
	s_nop 0
	v_fmac_f32_e32 v8, s43, v81
	v_readlane_b32 s43, v11, 55
	s_waitcnt vmcnt(10)
	s_nop 0
	v_fmac_f32_e32 v8, s43, v82
	v_readlane_b32 s43, v11, 56
	s_waitcnt vmcnt(9)
	s_nop 0
	v_fmac_f32_e32 v8, s43, v83
	v_readlane_b32 s43, v11, 57
	s_waitcnt vmcnt(8)
	s_nop 0
	v_fmac_f32_e32 v8, s43, v84
	v_readlane_b32 s43, v11, 58
	s_waitcnt vmcnt(7)
	s_nop 0
	v_fmac_f32_e32 v8, s43, v85
	v_readlane_b32 s43, v11, 59
	s_waitcnt vmcnt(6)
	s_nop 0
	v_fmac_f32_e32 v8, s43, v86
	v_readlane_b32 s43, v11, 60
	s_waitcnt vmcnt(5)
	s_nop 0
	v_fmac_f32_e32 v8, s43, v87
	v_readlane_b32 s43, v11, 61
	s_waitcnt vmcnt(4)
	s_nop 0
	v_fmac_f32_e32 v8, s43, v88
	v_readlane_b32 s43, v11, 62
	s_waitcnt vmcnt(3)
	s_nop 0
	v_fmac_f32_e32 v8, s43, v89
	v_readlane_b32 s43, v11, 63
	s_waitcnt vmcnt(2)
	s_nop 0
	v_fmac_f32_e32 v8, s43, v14
	v_add_co_u32_e32 v14, vcc, s1, v26
	s_mov_b32 s1, 0x22000
	s_nop 0
	v_addc_co_u32_e32 v15, vcc, 0, v27, vcc
	v_add_co_u32_e32 v16, vcc, s1, v26
	s_mov_b32 s1, 0x23000
	s_nop 0
	v_addc_co_u32_e32 v17, vcc, 0, v27, vcc
	global_load_dword v47, v[16:17], off offset:-4096
	global_load_dword v46, v[14:15], off offset:2048
	global_load_dword v45, v[16:17], off
	global_load_dword v44, v[16:17], off offset:2048
	v_add_co_u32_e32 v14, vcc, s1, v26
	s_mov_b32 s1, 0x24000
	s_nop 0
	v_addc_co_u32_e32 v15, vcc, 0, v27, vcc
	v_add_co_u32_e32 v16, vcc, s1, v26
	s_mov_b32 s1, 0x25000
	s_nop 0
	v_addc_co_u32_e32 v17, vcc, 0, v27, vcc
	global_load_dword v51, v[16:17], off offset:-4096
	global_load_dword v50, v[14:15], off offset:2048
	global_load_dword v49, v[16:17], off
	global_load_dword v48, v[16:17], off offset:2048
	v_add_co_u32_e32 v14, vcc, s1, v26
	s_mov_b32 s1, 0x26000
	s_nop 0
	v_addc_co_u32_e32 v15, vcc, 0, v27, vcc
	v_add_co_u32_e32 v16, vcc, s1, v26
	s_mov_b32 s1, 0x27000
	s_nop 0
	v_addc_co_u32_e32 v17, vcc, 0, v27, vcc
	global_load_dword v55, v[16:17], off offset:-4096
	global_load_dword v54, v[14:15], off offset:2048
	global_load_dword v53, v[16:17], off
	global_load_dword v52, v[16:17], off offset:2048
	v_add_co_u32_e32 v14, vcc, s1, v26
	s_mov_b32 s1, 0x28000
	s_nop 0
	v_addc_co_u32_e32 v15, vcc, 0, v27, vcc
	v_add_co_u32_e32 v16, vcc, s1, v26
	s_mov_b32 s1, 0x29000
	s_nop 0
	v_addc_co_u32_e32 v17, vcc, 0, v27, vcc
	global_load_dword v59, v[16:17], off offset:-4096
	global_load_dword v58, v[14:15], off offset:2048
	global_load_dword v57, v[16:17], off
	global_load_dword v56, v[16:17], off offset:2048
	v_add_co_u32_e32 v14, vcc, s1, v26
	s_mov_b32 s1, 0x2a000
	s_nop 0
	v_addc_co_u32_e32 v15, vcc, 0, v27, vcc
	v_add_co_u32_e32 v16, vcc, s1, v26
	s_mov_b32 s1, 0x2b000
	s_nop 0
	v_addc_co_u32_e32 v17, vcc, 0, v27, vcc
	global_load_dword v63, v[16:17], off offset:-4096
	global_load_dword v62, v[14:15], off offset:2048
	global_load_dword v61, v[16:17], off
	global_load_dword v60, v[16:17], off offset:2048
	v_add_co_u32_e32 v14, vcc, s1, v26
	s_mov_b32 s1, 0x2c000
	s_nop 0
	v_addc_co_u32_e32 v15, vcc, 0, v27, vcc
	v_add_co_u32_e32 v16, vcc, s1, v26
	s_mov_b32 s1, 0x2d000
	s_nop 0
	v_addc_co_u32_e32 v17, vcc, 0, v27, vcc
	global_load_dword v67, v[16:17], off offset:-4096
	global_load_dword v66, v[14:15], off offset:2048
	global_load_dword v65, v[16:17], off
	global_load_dword v64, v[16:17], off offset:2048
	v_add_co_u32_e32 v14, vcc, s1, v26
	s_mov_b32 s1, 0x2e000
	s_nop 0
	v_addc_co_u32_e32 v15, vcc, 0, v27, vcc
	v_add_co_u32_e32 v16, vcc, s1, v26
	s_mov_b32 s1, 0x2f000
	s_nop 0
	v_addc_co_u32_e32 v17, vcc, 0, v27, vcc
	global_load_dword v71, v[16:17], off offset:-4096
	global_load_dword v70, v[14:15], off offset:2048
	global_load_dword v69, v[16:17], off
	global_load_dword v68, v[16:17], off offset:2048
	v_add_co_u32_e32 v14, vcc, s1, v26
	s_mov_b32 s1, 0x30000
	s_nop 0
	v_addc_co_u32_e32 v15, vcc, 0, v27, vcc
	v_add_co_u32_e32 v16, vcc, s1, v26
	s_mov_b32 s1, 0x31000
	s_nop 0
	v_addc_co_u32_e32 v17, vcc, 0, v27, vcc
	global_load_dword v75, v[16:17], off offset:-4096
	global_load_dword v74, v[14:15], off offset:2048
	global_load_dword v73, v[16:17], off
	global_load_dword v72, v[16:17], off offset:2048
	v_add_co_u32_e32 v14, vcc, s1, v26
	s_mov_b32 s1, 0x32000
	s_nop 0
	v_addc_co_u32_e32 v15, vcc, 0, v27, vcc
	v_add_co_u32_e32 v16, vcc, s1, v26
	s_mov_b32 s1, 0x33000
	s_nop 0
	v_addc_co_u32_e32 v17, vcc, 0, v27, vcc
	global_load_dword v79, v[16:17], off offset:-4096
	global_load_dword v78, v[14:15], off offset:2048
	global_load_dword v77, v[16:17], off
	global_load_dword v76, v[16:17], off offset:2048
	v_add_co_u32_e32 v14, vcc, s1, v26
	s_mov_b32 s1, 0x34000
	s_nop 0
	v_addc_co_u32_e32 v15, vcc, 0, v27, vcc
	v_add_co_u32_e32 v16, vcc, s1, v26
	s_mov_b32 s1, 0x35000
	s_nop 0
	v_addc_co_u32_e32 v17, vcc, 0, v27, vcc
	global_load_dword v83, v[16:17], off offset:-4096
	global_load_dword v82, v[14:15], off offset:2048
	global_load_dword v81, v[16:17], off
	global_load_dword v80, v[16:17], off offset:2048
	v_add_co_u32_e32 v14, vcc, s1, v26
	s_mov_b32 s1, 0x36000
	s_nop 0
	v_addc_co_u32_e32 v15, vcc, 0, v27, vcc
	v_add_co_u32_e32 v16, vcc, s1, v26
	s_mov_b32 s1, 0x37000
	s_nop 0
	v_addc_co_u32_e32 v17, vcc, 0, v27, vcc
	global_load_dword v85, v[16:17], off offset:-4096
	global_load_dword v24, v[14:15], off offset:2048
	global_load_dword v25, v[16:17], off
	global_load_dword v20, v[16:17], off offset:2048
	v_add_co_u32_e32 v14, vcc, s1, v26
	s_mov_b32 s1, 0x38000
	s_nop 0
	v_addc_co_u32_e32 v15, vcc, 0, v27, vcc
	v_add_co_u32_e32 v16, vcc, s1, v26
	s_mov_b32 s1, 0x39000
	s_nop 0
	v_addc_co_u32_e32 v17, vcc, 0, v27, vcc
	global_load_dword v21, v[16:17], off offset:-4096
	global_load_dword v22, v[14:15], off offset:2048
	global_load_dword v23, v[16:17], off
	global_load_dword v18, v[16:17], off offset:2048
	v_add_co_u32_e32 v14, vcc, s1, v26
	s_mov_b32 s1, 0x3a000
	s_nop 0
	v_addc_co_u32_e32 v15, vcc, 0, v27, vcc
	v_add_co_u32_e32 v38, vcc, s1, v26
	s_mov_b32 s1, 0x3b000
	s_nop 0
	v_addc_co_u32_e32 v39, vcc, 0, v27, vcc
	global_load_dword v19, v[38:39], off offset:-4096
	global_load_dword v16, v[14:15], off offset:2048
	global_load_dword v17, v[38:39], off
	s_nop 0
	global_load_dword v14, v[38:39], off offset:2048
	v_add_co_u32_e32 v38, vcc, s1, v26
	s_mov_b32 s1, 0x3c000
	s_nop 0
	v_addc_co_u32_e32 v39, vcc, 0, v27, vcc
	v_add_co_u32_e32 v40, vcc, s1, v26
	s_mov_b32 s1, 0x3d000
	s_nop 0
	v_addc_co_u32_e32 v41, vcc, 0, v27, vcc
	global_load_dword v15, v[40:41], off offset:-4096
	global_load_dword v12, v[38:39], off offset:2048
	s_nop 0
	global_load_dword v38, v[40:41], off
	global_load_dword v37, v[40:41], off offset:2048
	v_add_co_u32_e32 v40, vcc, s1, v26
	s_mov_b32 s1, 0x3e000
	s_nop 0
	v_addc_co_u32_e32 v41, vcc, 0, v27, vcc
	v_add_co_u32_e32 v86, vcc, s1, v26
	v_readlane_b32 s43, v13, 0
	s_nop 0
	v_addc_co_u32_e32 v87, vcc, 0, v27, vcc
	global_load_dword v42, v[86:87], off offset:-4096
	s_nop 0
	global_load_dword v41, v[40:41], off offset:2048
	s_nop 0
	global_load_dword v40, v[86:87], off
	global_load_dword v39, v[86:87], off offset:2048
	s_waitcnt vmcnt(61)
	v_fmac_f32_e32 v8, s43, v43
	v_readlane_b32 s43, v13, 1
	s_mov_b32 s1, 0x3f000
	v_add_co_u32_e32 v26, vcc, s1, v26
	s_waitcnt vmcnt(60)
	v_fmac_f32_e32 v8, s43, v10
	v_readlane_b32 s43, v13, 2
	v_addc_co_u32_e32 v27, vcc, 0, v27, vcc
	s_waitcnt vmcnt(59)
	v_fmac_f32_e32 v8, s43, v47
	v_readlane_b32 s43, v13, 3
	global_load_dword v84, v[26:27], off
	s_nop 0
	global_load_dword v26, v[26:27], off offset:2048
	s_waitcnt vmcnt(60)
	v_fmac_f32_e32 v8, s43, v46
	v_readlane_b32 s43, v13, 4
	s_waitcnt vmcnt(19)
	v_pk_mul_f32 v[24:25], v[24:25], s[50:51]
	v_fmac_f32_e32 v8, s43, v45
	v_readlane_b32 s43, v13, 5
	v_readlane_b32 s50, v13, 45
	v_readlane_b32 s51, v13, 46
	v_fmac_f32_e32 v8, s43, v44
	v_readlane_b32 s43, v13, 6
	s_waitcnt vmcnt(17)
	v_pk_mul_f32 v[20:21], v[20:21], s[50:51]
	v_fmac_f32_e32 v8, s43, v51
	v_readlane_b32 s43, v13, 7
	v_readlane_b32 s50, v13, 47
	v_readlane_b32 s51, v13, 48
	v_fmac_f32_e32 v8, s43, v50
	v_readlane_b32 s43, v13, 8
	s_nop 1
	v_fmac_f32_e32 v8, s43, v49
	v_readlane_b32 s43, v13, 9
	s_nop 1
	v_fmac_f32_e32 v8, s43, v48
	v_readlane_b32 s43, v13, 10
	s_nop 1
	v_fmac_f32_e32 v8, s43, v55
	v_readlane_b32 s43, v13, 11
	s_nop 1
	v_fmac_f32_e32 v8, s43, v54
	v_readlane_b32 s43, v13, 12
	s_nop 1
	v_fmac_f32_e32 v8, s43, v53
	v_readlane_b32 s43, v13, 13
	s_nop 1
	v_fmac_f32_e32 v8, s43, v52
	v_readlane_b32 s43, v13, 14
	s_nop 1
	v_fmac_f32_e32 v8, s43, v59
	v_readlane_b32 s43, v13, 15
	s_nop 1
	v_fmac_f32_e32 v8, s43, v58
	v_readlane_b32 s43, v13, 16
	s_nop 1
	v_fmac_f32_e32 v8, s43, v57
	v_readlane_b32 s43, v13, 17
	s_nop 1
	v_fmac_f32_e32 v8, s43, v56
	v_readlane_b32 s43, v13, 18
	s_nop 1
	v_fmac_f32_e32 v8, s43, v63
	v_readlane_b32 s43, v13, 19
	s_nop 1
	v_fmac_f32_e32 v8, s43, v62
	v_readlane_b32 s43, v13, 20
	s_nop 1
	v_fmac_f32_e32 v8, s43, v61
	v_readlane_b32 s43, v13, 21
	s_nop 1
	v_fmac_f32_e32 v8, s43, v60
	v_readlane_b32 s43, v13, 22
	s_nop 1
	v_fmac_f32_e32 v8, s43, v67
	v_readlane_b32 s43, v13, 23
	s_nop 1
	v_fmac_f32_e32 v8, s43, v66
	v_readlane_b32 s43, v13, 24
	s_nop 1
	v_fmac_f32_e32 v8, s43, v65
	v_readlane_b32 s43, v13, 25
	s_nop 1
	v_fmac_f32_e32 v8, s43, v64
	v_readlane_b32 s43, v13, 26
	s_nop 1
	v_fmac_f32_e32 v8, s43, v71
	v_readlane_b32 s43, v13, 27
	s_nop 1
	v_fmac_f32_e32 v8, s43, v70
	v_readlane_b32 s43, v13, 28
	s_nop 1
	v_fmac_f32_e32 v8, s43, v69
	v_readlane_b32 s43, v13, 29
	s_nop 1
	v_fmac_f32_e32 v8, s43, v68
	v_readlane_b32 s43, v13, 30
	s_nop 1
	v_fmac_f32_e32 v8, s43, v75
	v_readlane_b32 s43, v13, 31
	s_nop 1
	v_fmac_f32_e32 v8, s43, v74
	v_readlane_b32 s43, v13, 32
	s_nop 1
	v_fmac_f32_e32 v8, s43, v73
	v_readlane_b32 s43, v13, 33
	s_nop 1
	v_fmac_f32_e32 v8, s43, v72
	v_readlane_b32 s43, v13, 34
	s_nop 1
	v_fmac_f32_e32 v8, s43, v79
	v_readlane_b32 s43, v13, 35
	s_nop 1
	v_fmac_f32_e32 v8, s43, v78
	v_readlane_b32 s43, v13, 36
	s_nop 1
	v_fmac_f32_e32 v8, s43, v77
	v_readlane_b32 s43, v13, 37
	s_nop 1
	v_fmac_f32_e32 v8, s43, v76
	v_readlane_b32 s43, v13, 38
	s_nop 1
	v_fmac_f32_e32 v8, s43, v83
	v_readlane_b32 s43, v13, 39
	s_nop 1
	v_fmac_f32_e32 v8, s43, v82
	v_readlane_b32 s43, v13, 40
	s_nop 1
	v_fmac_f32_e32 v8, s43, v81
	v_readlane_b32 s43, v13, 41
	s_nop 1
	v_fmac_f32_e32 v8, s43, v80
	v_readlane_b32 s43, v13, 42
	s_nop 1
	v_fmac_f32_e32 v8, s43, v85
	v_add_f32_e32 v8, v8, v24
	v_add_f32_e32 v8, v8, v25
	v_add_f32_e32 v8, v8, v20
	v_add_f32_e32 v8, v8, v21
	s_waitcnt vmcnt(15)
	v_pk_mul_f32 v[20:21], v[22:23], s[50:51]
	v_readlane_b32 s50, v13, 49
	v_add_f32_e32 v8, v8, v20
	v_readlane_b32 s51, v13, 50
	v_add_f32_e32 v8, v8, v21
	v_readlane_b32 s43, v13, 55
	s_waitcnt vmcnt(13)
	v_pk_mul_f32 v[18:19], v[18:19], s[50:51]
	v_readlane_b32 s50, v13, 51
	v_add_f32_e32 v8, v8, v18
	v_readlane_b32 s51, v13, 52
	v_add_f32_e32 v8, v8, v19
	s_waitcnt vmcnt(8)
	v_mul_f32_e32 v12, s43, v12
	v_pk_mul_f32 v[16:17], v[16:17], s[50:51]
	v_readlane_b32 s50, v13, 53
	v_add_f32_e32 v8, v8, v16
	v_readlane_b32 s51, v13, 54
	v_add_f32_e32 v8, v8, v17
	v_readlane_b32 s43, v13, 56
	v_pk_mul_f32 v[14:15], v[14:15], s[50:51]
	s_nop 0
	v_add_f32_e32 v8, v8, v14
	v_add_f32_e32 v10, v8, v15
	v_pk_add_f32 v[10:11], v[10:11], v[12:13]
	ds_bpermute_b32 v25, v28, v11
	s_waitcnt vmcnt(7)
	v_mul_f32_e32 v24, s43, v38
	v_readlane_b32 s43, v13, 57
	v_sub_f32_e32 v15, v35, v36
	v_mul_f32_e32 v15, 0x3fb8aa3b, v15
	s_waitcnt lgkmcnt(0)
	v_pk_add_f32 v[10:11], v[10:11], v[24:25]
	ds_bpermute_b32 v23, v29, v11
	s_waitcnt vmcnt(6)
	v_mul_f32_e32 v22, s43, v37
	v_readlane_b32 s43, v13, 58
	v_exp_f32_e32 v27, v15
	s_waitcnt lgkmcnt(0)
	v_pk_add_f32 v[10:11], v[10:11], v[22:23]
	ds_bpermute_b32 v21, v30, v11
	s_waitcnt vmcnt(5)
	v_mul_f32_e32 v20, s43, v42
	v_readlane_b32 s43, v13, 59
	s_waitcnt lgkmcnt(0)
	v_pk_add_f32 v[10:11], v[10:11], v[20:21]
	ds_bpermute_b32 v19, v31, v11
	s_waitcnt vmcnt(4)
	v_mul_f32_e32 v18, s43, v41
	v_readlane_b32 s43, v13, 60
	s_waitcnt lgkmcnt(0)
	v_pk_add_f32 v[10:11], v[10:11], v[18:19]
	ds_bpermute_b32 v17, v32, v11
	s_waitcnt vmcnt(3)
	v_mul_f32_e32 v16, s43, v40
	v_readlane_b32 s43, v13, 61
	s_waitcnt lgkmcnt(0)
	v_pk_add_f32 v[10:11], v[10:11], v[16:17]
	ds_bpermute_b32 v15, v33, v11
	s_waitcnt vmcnt(2)
	v_mul_f32_e32 v14, s43, v39
	v_readlane_b32 s43, v13, 62
	s_waitcnt lgkmcnt(0)
	v_pk_add_f32 v[10:11], v[10:11], v[14:15]
	s_waitcnt vmcnt(1)
	v_mul_f32_e32 v8, s43, v84
	v_readlane_b32 s43, v13, 63
	v_pk_add_f32 v[8:9], v[8:9], v[10:11]
	s_waitcnt vmcnt(0)
	v_mul_f32_e32 v26, s43, v26
	v_pk_add_f32 v[8:9], v[26:27], v[8:9]
	s_movk_i32 s43, 0x7fff
	v_div_scale_f32 v10, s[50:51], v9, v9, v8
	v_rcp_f32_e32 v11, v10
	s_nop 0
	v_fma_f32 v12, -v10, v11, 1.0
	v_fmac_f32_e32 v11, v12, v11
	v_div_scale_f32 v12, vcc, v8, v9, v8
	v_mul_f32_e32 v13, v12, v11
	v_fma_f32 v14, -v10, v13, v12
	v_fmac_f32_e32 v13, v14, v11
	v_fma_f32 v10, -v10, v13, v12
	v_div_fmas_f32 v10, v10, v11, v13
	v_div_fixup_f32 v8, v10, v9, v8
	v_bfe_u32 v9, v8, 16, 1
	v_add3_u32 v8, v8, v9, s43
	v_readlane_b32 s43, v252, 43
	s_add_u32 s43, s43, s48
	v_readlane_b32 s48, v252, 44
	s_addc_u32 s49, s48, s49
	s_lshl_b32 s48, s0, 7
	s_add_u32 s48, s43, s48
	v_readlane_b32 s42, v250, 45
	s_addc_u32 s49, s49, 0
	s_add_i32 s33, s33, s4
	v_readlane_b32 s43, v250, 46
	s_cmpk_gt_i32 s33, 0x7ff
	global_store_short_d16_hi v34, v8, s[48:49]
	s_cbranch_scc0 .LBB0_1424
